# residual epilogues: row-statistics atomics packed 4 rows per wave-instruction and issued once at the end of the epilogue (waits re-derived); plus pipelined weight conversions
# baseline (speedup 1.0000x reference)
;     __device__ __forceinline__ void operator()(const f32x4 (&acc)[2][2][4][2], const Unit& u, int wr, int wc, int fr, int fq) const {
;     ...
;         const int row0 = u.pm * BM + wr * 64 + fr; const int col0 = u.pn * BM + wc * 32 + 8 * fq;
;         f32x4 g[2][2], b[2][2];
; #pragma unroll
;         for (int bj = 0; bj < 2; ++bj)
; #pragma unroll
;             for (int n = 0; n < 2; ++n) { g[bj][n] = *(const f32x4*)(gam + col0 + bj * HALF + 4 * n); b[bj][n] = *(const f32x4*)(bet + col0 + bj * HALF + 4 * n) * alpha; }
;         f32x4 nx[2][2]; f32x2v nst;
;         { const int row = row0; nst = *(const f32x2v*)(st_in + 2 * row);
; #pragma unroll
;           for (int bj = 0; bj < 2; ++bj) { const size_t off = (size_t)row * ldc + col0 + bj * HALF; nx[bj][0] = *(const f32x4*)(Src + off); nx[bj][1] = *(const f32x4*)(Src + off + 4); } }
; #pragma unroll
;         for (int r = 0; r < 8; ++r) { const int ai = r >> 2, m = r & 3; const int row = row0 + ai * HALF + m * 16;
;             f32x4 cx[2][2]; const f32x2v cst = nst;
; #pragma unroll
;             for (int bj = 0; bj < 2; ++bj) { cx[bj][0] = nx[bj][0]; cx[bj][1] = nx[bj][1]; }
;             if (r + 1 < 8) { const int rown = row0 + ((r + 1) >> 2) * HALF + ((r + 1) & 3) * 16; nst = *(const f32x2v*)(st_in + 2 * rown);
; #pragma unroll
;                 for (int bj = 0; bj < 2; ++bj) { const size_t off = (size_t)rown * ldc + col0 + bj * HALF; nx[bj][0] = *(const f32x4*)(Src + off); nx[bj][1] = *(const f32x4*)(Src + off + 4); } }
;             const float mean = cst.x * (1.0f / 2048.0f); const float rstd = 1.0f / sqrtf(cst.y * (1.0f / 2048.0f) - mean * mean + 1e-5f);
;             const float sc = rstd * alpha; float s1 = 0.f, s2 = 0.f;
; #pragma unroll
;             for (int bj = 0; bj < 2; ++bj) { const size_t off = (size_t)row * ldc + col0 + bj * HALF;
;                 const f32x4 a = (cx[bj][0] - mean) * sc * g[bj][0] + b[bj][0] + acc[ai][bj][m][0], d = (cx[bj][1] - mean) * sc * g[bj][1] + b[bj][1] + acc[ai][bj][m][1];
.LBB0_336:
	v_lshl_or_b32 v176, s56, 8, v210
	v_ashrrev_i32_e32 v177, 31, v176
	v_lshl_add_u32 v194, s10, 8, v208
	v_lshlrev_b64 v[144:145], 2, v[176:177]
	v_lshlrev_b32_e32 v198, 1, v194
	v_lshl_add_u64 v[64:65], s[34:35], 0, v[144:145]
	v_ashrrev_i32_e32 v199, 31, v198
	global_load_dwordx4 v[178:181], v[64:65], off offset:16
	global_load_dwordx4 v[182:185], v[64:65], off
	global_load_dwordx4 v[202:205], v[64:65], off offset:528
	global_load_dwordx4 v[218:221], v[64:65], off offset:512
	v_lshl_add_u64 v[64:65], v[198:199], 2, s[14:15]
	global_load_dwordx2 v[238:239], v[64:65], off
	v_ashrrev_i32_e32 v195, 31, v194
	v_lshlrev_b64 v[64:65], 13, v[194:195]
	v_lshl_add_u64 v[64:65], s[28:29], 0, v[64:65]
	v_lshl_add_u64 v[146:147], v[64:65], 0, v[144:145]
	global_load_dwordx4 v[222:225], v[146:147], off
	global_load_dwordx4 v[226:229], v[146:147], off offset:16
	v_lshl_add_u64 v[72:73], s[30:31], 0, v[144:145]
	global_load_dwordx4 v[68:71], v[72:73], off offset:16
	global_load_dwordx4 v[76:79], v[72:73], off
	v_and_b32_e32 v65, 64, v214
	v_xor_b32_e32 v64, 16, v214
	v_add_u32_e32 v65, 64, v65
	v_xor_b32_e32 v66, 32, v214
	v_or_b32_e32 v200, 16, v194
	v_cmp_lt_i32_e32 vcc, v64, v65
	v_lshlrev_b32_e32 v196, 1, v200
	v_ashrrev_i32_e32 v197, 31, v196
	v_cndmask_b32_e32 v67, v214, v64, vcc
	v_cmp_lt_i32_e32 vcc, v66, v65
	v_lshlrev_b64 v[64:65], 11, v[194:195]
	v_lshlrev_b32_e32 v216, 2, v67
	v_cndmask_b32_e32 v66, v214, v66, vcc
	v_lshlrev_b32_e32 v195, 2, v66
	v_lshl_add_u64 v[244:245], v[64:65], 0, v[176:177]
	global_load_dwordx4 v[64:67], v[72:73], off offset:528
	s_nop 0
	global_load_dwordx4 v[72:75], v[72:73], off offset:512
	v_lshl_add_u64 v[150:151], v[196:197], 2, s[14:15]
	global_load_dwordx4 v[230:233], v[146:147], off offset:528
	global_load_dwordx4 v[234:237], v[146:147], off offset:512
	global_load_dwordx2 v[206:207], v[150:151], off
	v_ashrrev_i32_e32 v201, 31, v200
	v_lshlrev_b64 v[148:149], 13, v[200:201]
	v_lshl_add_u64 v[148:149], s[28:29], 0, v[148:149]
	v_lshl_add_u64 v[148:149], v[148:149], 0, v[144:145]
	global_load_dwordx4 v[152:155], v[148:149], off offset:16
	global_load_dwordx4 v[156:159], v[148:149], off
	global_load_dwordx4 v[144:147], v[148:149], off offset:528
	s_nop 0
	global_load_dwordx4 v[148:151], v[148:149], off offset:512
	v_lshl_add_u64 v[246:247], v[244:245], 2, s[18:19]
	s_waitcnt vmcnt(0)
	v_pk_mul_f32 v[186:187], v[180:181], s[44:45] op_sel_hi:[1,0]
	v_pk_mul_f32 v[190:191], v[184:185], s[44:45] op_sel_hi:[1,0]
	v_pk_mul_f32 v[180:181], v[202:203], s[44:45] op_sel_hi:[1,0]
	v_pk_mul_f32 v[184:185], v[218:219], s[44:45] op_sel_hi:[1,0]
	v_pk_mul_f32 v[188:189], v[178:179], s[44:45] op_sel_hi:[1,0]
	v_pk_mul_f32 v[218:219], v[238:239], s[46:47] op_sel_hi:[1,0]
	v_pk_mul_f32 v[178:179], v[204:205], s[44:45] op_sel_hi:[1,0]
	v_fma_f32 v217, -v218, v218, v219
	v_add_f32_e32 v217, 0x3727c5ac, v217
	v_mul_f32_e32 v219, 0x4f800000, v217
	v_cmp_gt_f32_e32 vcc, s77, v217
	v_sub_f32_e32 v202, v222, v218
	v_sub_f32_e32 v205, v225, v218
	v_cndmask_b32_e32 v217, v217, v219, vcc
	v_sqrt_f32_e32 v219, v217
	v_sub_f32_e32 v204, v224, v218
	v_pk_mul_f32 v[192:193], v[182:183], s[44:45] op_sel_hi:[1,0]
	v_pk_mul_f32 v[182:183], v[220:221], s[44:45] op_sel_hi:[1,0]
	v_add_u32_e32 v222, -1, v219
	v_add_u32_e32 v224, 1, v219
	v_fma_f32 v225, -v222, v219, v217
	v_sub_f32_e32 v220, v226, v218
	v_fma_f32 v226, -v224, v219, v217
	v_cmp_ge_f32_e64 s[10:11], 0, v225
	v_sub_f32_e32 v221, v227, v218
	v_sub_f32_e32 v203, v223, v218
	v_cndmask_b32_e64 v219, v219, v222, s[10:11]
	v_cmp_lt_f32_e64 s[10:11], 0, v226
	v_sub_f32_e32 v223, v229, v218
	s_nop 0
	v_cndmask_b32_e64 v219, v219, v224, s[10:11]
	v_mul_f32_e32 v222, 0x37800000, v219
	v_cndmask_b32_e32 v219, v219, v222, vcc
	v_cmp_class_f32_e32 vcc, v217, v215
	v_sub_f32_e32 v222, v228, v218
	s_nop 0
	v_cndmask_b32_e32 v217, v219, v217, vcc
	v_div_scale_f32 v219, s[10:11], v217, v217, 1.0
	v_rcp_f32_e32 v224, v219
	v_div_scale_f32 v225, vcc, 1.0, v217, 1.0
	v_fma_f32 v226, -v219, v224, 1.0
	v_fmac_f32_e32 v224, v226, v224
	v_mul_f32_e32 v226, v225, v224
	v_fma_f32 v227, -v219, v226, v225
	v_fmac_f32_e32 v226, v227, v224
	v_fma_f32 v219, -v219, v226, v225
	v_div_fmas_f32 v219, v219, v224, v226
	v_div_fixup_f32 v217, v219, v217, 1.0
	v_mul_f32_e32 v224, 0x3fb504f3, v217
	v_pk_mul_f32 v[204:205], v[204:205], v[224:225] op_sel_hi:[1,0]
	v_pk_mul_f32 v[202:203], v[202:203], v[224:225] op_sel_hi:[1,0]
	v_pk_mul_f32 v[222:223], v[222:223], v[224:225] op_sel_hi:[1,0]
	v_pk_mul_f32 v[220:221], v[220:221], v[224:225] op_sel_hi:[1,0]
	v_pk_fma_f32 v[202:203], v[76:77], v[202:203], v[192:193]
	v_pk_fma_f32 v[204:205], v[78:79], v[204:205], v[190:191]
	v_pk_fma_f32 v[220:221], v[68:69], v[220:221], v[188:189]
	v_pk_fma_f32 v[222:223], v[70:71], v[222:223], v[186:187]
	v_pk_add_f32 v[142:143], v[142:143], v[204:205]
	v_pk_add_f32 v[140:141], v[140:141], v[202:203]
	v_pk_add_f32 v[138:139], v[138:139], v[222:223]
	v_pk_add_f32 v[136:137], v[136:137], v[220:221]
	v_lshlrev_b64 v[220:221], 1, v[244:245]
	v_cvt_pk_bf16_f32 v202, v140, v141
	v_cvt_pk_bf16_f32 v203, v142, v143
	v_cvt_pk_bf16_f32 v204, v136, v137
	v_cvt_pk_bf16_f32 v205, v138, v139
	v_lshl_add_u64 v[222:223], s[24:25], 0, v[220:221]
	global_store_dwordx4 v[246:247], v[140:143], off
	global_store_dwordx4 v[246:247], v[136:139], off offset:16
	global_store_dwordx4 v[222:223], v[202:205], off
	v_or_b32_e32 v220, 0x100, v220
	s_nop 0
	v_add_f32_e32 v202, v140, v141
	v_add_f32_e32 v203, v142, v143
	v_add_f32_e32 v202, v202, v203
	v_add_f32_e32 v203, v136, v137
	v_mul_f32_e32 v141, v141, v141
	v_mul_f32_e32 v137, v137, v137
;     __device__ __forceinline__ void operator()(const f32x4 (&acc)[2][2][4][2], const Unit& u, int wr, int wc, int fr, int fq) const {
;     ...
;             for (int bj = 0; bj < 2; ++bj) { const size_t off = (size_t)row * ldc + col0 + bj * HALF;
;                 const f32x4 a = (cx[bj][0] - mean) * sc * g[bj][0] + b[bj][0] + acc[ai][bj][m][0], d = (cx[bj][1] - mean) * sc * g[bj][1] + b[bj][1] + acc[ai][bj][m][1];
;                 *(f32x4*)(Dst + off) = a; *(f32x4*)(Dst + off + 4) = d;
;                 if (OUTB) { u32x4 pw; pw.x = cvt_pk_bf16(a[0], a[1]); pw.y = cvt_pk_bf16(a[2], a[3]); pw.z = cvt_pk_bf16(d[0], d[1]); pw.w = cvt_pk_bf16(d[2], d[3]);
;                     *(u32x4*)(YB + off) = pw;
;                     s1 += ((a[0] + a[1]) + (a[2] + a[3])) + ((d[0] + d[1]) + (d[2] + d[3]));
;                     s2 += ((a[0] * a[0] + a[1] * a[1]) + (a[2] * a[2] + a[3] * a[3])) + ((d[0] * d[0] + d[1] * d[1]) + (d[2] * d[2] + d[3] * d[3])); } }
;             if (OUTB) { s1 += __shfl_xor(s1, 16); s2 += __shfl_xor(s2, 16); s1 += __shfl_xor(s1, 32); s2 += __shfl_xor(s2, 32);
;                 if (fq == 0) { __hip_atomic_fetch_add(st_out + 2 * row, s1, __ATOMIC_RELAXED, __HIP_MEMORY_SCOPE_AGENT); __hip_atomic_fetch_add(st_out + 2 * row + 1, s2, __ATOMIC_RELAXED, __HIP_MEMORY_SCOPE_AGENT); } } }
	v_fmac_f32_e32 v141, v140, v140
	v_mul_f32_e32 v140, v143, v143
	v_fmac_f32_e32 v137, v136, v136
	v_mul_f32_e32 v136, v139, v139
	v_fmac_f32_e32 v140, v142, v142
	v_fmac_f32_e32 v136, v138, v138
	v_add_f32_e32 v140, v141, v140
	v_add_f32_e32 v136, v137, v136
	v_add_f32_e32 v204, v138, v139
	v_add_f32_e32 v140, v140, v136
	v_sub_f32_e32 v137, v235, v218
	v_sub_f32_e32 v136, v234, v218
	v_sub_f32_e32 v139, v237, v218
	v_sub_f32_e32 v138, v236, v218
	v_pk_mul_f32 v[138:139], v[138:139], v[224:225] op_sel_hi:[1,0]
	v_pk_mul_f32 v[136:137], v[136:137], v[224:225] op_sel_hi:[1,0]
	v_pk_fma_f32 v[138:139], v[74:75], v[138:139], v[182:183]
	v_pk_fma_f32 v[136:137], v[72:73], v[136:137], v[184:185]
	v_pk_add_f32 v[134:135], v[134:135], v[138:139]
	v_pk_add_f32 v[132:133], v[132:133], v[136:137]
	v_sub_f32_e32 v137, v231, v218
	v_sub_f32_e32 v136, v230, v218
	v_sub_f32_e32 v139, v233, v218
	v_sub_f32_e32 v138, v232, v218
	v_pk_mul_f32 v[138:139], v[138:139], v[224:225] op_sel_hi:[1,0]
	v_pk_mul_f32 v[136:137], v[136:137], v[224:225] op_sel_hi:[1,0]
	v_pk_fma_f32 v[138:139], v[66:67], v[138:139], v[178:179]
	v_pk_fma_f32 v[136:137], v[64:65], v[136:137], v[180:181]
	v_pk_add_f32 v[138:139], v[130:131], v[138:139]
	v_pk_add_f32 v[136:137], v[128:129], v[136:137]
	v_add_f32_e32 v128, v132, v133
	v_add_f32_e32 v129, v134, v135
	v_add_f32_e32 v128, v128, v129
	v_add_f32_e32 v129, v136, v137
	v_add_f32_e32 v130, v138, v139
	v_add_f32_e32 v129, v129, v130
	v_add_f32_e32 v128, v128, v129
	v_mul_f32_e32 v129, v133, v133
	v_mul_f32_e32 v130, v135, v135
	v_fmac_f32_e32 v129, v132, v132
	v_fmac_f32_e32 v130, v134, v134
	v_add_f32_e32 v129, v129, v130
	v_mul_f32_e32 v130, v137, v137
	v_mul_f32_e32 v131, v139, v139
	v_add_f32_e32 v203, v203, v204
	v_fmac_f32_e32 v130, v136, v136
	v_fmac_f32_e32 v131, v138, v138
	v_add_f32_e32 v202, v202, v203
	v_add_f32_e32 v130, v130, v131
	v_add_f32_e32 v202, 0, v202
	v_add_f32_e32 v129, v129, v130
	v_add_f32_e32 v128, v128, v202
	v_add_f32_e32 v129, v140, v129
	ds_bpermute_b32 v130, v216, v128
	ds_bpermute_b32 v131, v216, v129
	global_store_dwordx4 v[246:247], v[132:135], off offset:512
	global_store_dwordx4 v[246:247], v[136:139], off offset:528
	s_waitcnt lgkmcnt(1)
	v_add_f32_e32 v128, v128, v130
	s_waitcnt lgkmcnt(0)
	v_add_f32_e32 v129, v129, v131
	ds_bpermute_b32 v130, v195, v128
	ds_bpermute_b32 v131, v195, v129
	v_cvt_pk_bf16_f32 v132, v132, v133
	v_cvt_pk_bf16_f32 v133, v134, v135
	v_cvt_pk_bf16_f32 v134, v136, v137
	v_cvt_pk_bf16_f32 v135, v138, v139
	v_lshl_add_u64 v[136:137], s[24:25], 0, v[220:221]
	global_store_dwordx4 v[136:137], v[132:135], off
	v_lshl_add_u64 v[250:251], v[198:199], 2, s[38:39]
	s_waitcnt lgkmcnt(1)
	v_add_f32_e32 v128, v128, v130
	s_waitcnt lgkmcnt(0)
	v_add_f32_e32 v129, v129, v131
	v_mov_b32_e32 v252, v128
	v_mov_b32_e32 v253, v129
	v_or_b32_e32 v202, 32, v194
	v_lshlrev_b32_e32 v198, 1, v202
	v_ashrrev_i32_e32 v199, 31, v198
	v_lshl_add_u64 v[128:129], v[198:199], 2, s[14:15]
	v_pk_mul_f32 v[206:207], v[206:207], s[46:47] op_sel_hi:[1,0]
	global_load_dwordx2 v[204:205], v[128:129], off
	v_fma_f32 v128, -v206, v206, v207
	v_add_f32_e32 v128, 0x3727c5ac, v128
	v_mul_f32_e32 v129, 0x4f800000, v128
	v_cmp_gt_f32_e32 vcc, s77, v128
	v_ashrrev_i32_e32 v203, 31, v202
	v_sub_f32_e32 v157, v157, v206
	s_waitcnt lgkmcnt(1)
	v_cndmask_b32_e32 v130, v128, v129, vcc
	s_waitcnt lgkmcnt(0)
	v_sqrt_f32_e32 v131, v130
	v_lshlrev_b64 v[128:129], 13, v[202:203]
	v_lshl_add_u64 v[128:129], s[28:29], 0, v[128:129]
	v_lshl_add_u64 v[132:133], v[176:177], 2, v[128:129]
	v_add_u32_e32 v128, -1, v131
	v_fma_f32 v129, -v128, v131, v130
	v_cmp_ge_f32_e64 s[10:11], 0, v129
	v_add_u32_e32 v129, 1, v131
	v_sub_f32_e32 v156, v156, v206
	v_cndmask_b32_e64 v128, v131, v128, s[10:11]
	v_fma_f32 v131, -v129, v131, v130
	v_cmp_lt_f32_e64 s[10:11], 0, v131
	v_sub_f32_e32 v159, v159, v206
	v_sub_f32_e32 v158, v158, v206
	v_cndmask_b32_e64 v128, v128, v129, s[10:11]
	v_mul_f32_e32 v129, 0x37800000, v128
	v_cndmask_b32_e32 v128, v128, v129, vcc
	v_cmp_class_f32_e32 vcc, v130, v215
	v_sub_f32_e32 v153, v153, v206
	v_sub_f32_e32 v152, v152, v206
	v_cndmask_b32_e32 v207, v128, v130, vcc
	global_load_dwordx4 v[136:139], v[132:133], off offset:16
	global_load_dwordx4 v[140:143], v[132:133], off
	global_load_dwordx4 v[128:131], v[132:133], off offset:528
	s_nop 0
	global_load_dwordx4 v[132:135], v[132:133], off offset:512
	v_div_scale_f32 v217, s[10:11], v207, v207, 1.0
	v_rcp_f32_e32 v218, v217
	v_sub_f32_e32 v155, v155, v206
	v_sub_f32_e32 v154, v154, v206
	v_lshlrev_b64 v[200:201], 11, v[200:201]
	v_fma_f32 v219, -v217, v218, 1.0
	v_fmac_f32_e32 v218, v219, v218
	v_div_scale_f32 v219, vcc, 1.0, v207, 1.0
	v_mul_f32_e32 v220, v219, v218
	v_fma_f32 v221, -v217, v220, v219
	v_fmac_f32_e32 v220, v221, v218
	v_fma_f32 v217, -v217, v220, v219
	v_div_fmas_f32 v217, v217, v218, v220
	v_div_fixup_f32 v207, v217, v207, 1.0
	v_mul_f32_e32 v218, 0x3fb504f3, v207
	v_pk_mul_f32 v[158:159], v[158:159], v[218:219] op_sel_hi:[1,0]
	v_pk_mul_f32 v[156:157], v[156:157], v[218:219] op_sel_hi:[1,0]
	v_pk_mul_f32 v[154:155], v[154:155], v[218:219] op_sel_hi:[1,0]
	v_pk_mul_f32 v[152:153], v[152:153], v[218:219] op_sel_hi:[1,0]
	v_lshl_add_u64 v[200:201], v[200:201], 0, v[176:177]
	v_pk_fma_f32 v[156:157], v[76:77], v[156:157], v[192:193]
	v_pk_fma_f32 v[158:159], v[78:79], v[158:159], v[190:191]
	v_pk_fma_f32 v[152:153], v[68:69], v[152:153], v[188:189]
	v_pk_fma_f32 v[154:155], v[70:71], v[154:155], v[186:187]
	v_pk_add_f32 v[126:127], v[126:127], v[158:159]
	v_pk_add_f32 v[124:125], v[124:125], v[156:157]
	v_pk_add_f32 v[122:123], v[122:123], v[154:155]
;     __device__ __forceinline__ void operator()(const f32x4 (&acc)[2][2][4][2], const Unit& u, int wr, int wc, int fr, int fq) const {
;     ...
;         for (int r = 0; r < 8; ++r) { const int ai = r >> 2, m = r & 3; const int row = row0 + ai * HALF + m * 16;
;             f32x4 cx[2][2]; const f32x2v cst = nst;
; #pragma unroll
;             for (int bj = 0; bj < 2; ++bj) { cx[bj][0] = nx[bj][0]; cx[bj][1] = nx[bj][1]; }
;             if (r + 1 < 8) { const int rown = row0 + ((r + 1) >> 2) * HALF + ((r + 1) & 3) * 16; nst = *(const f32x2v*)(st_in + 2 * rown);
; #pragma unroll
;                 for (int bj = 0; bj < 2; ++bj) { const size_t off = (size_t)rown * ldc + col0 + bj * HALF; nx[bj][0] = *(const f32x4*)(Src + off); nx[bj][1] = *(const f32x4*)(Src + off + 4); } }
;             const float mean = cst.x * (1.0f / 2048.0f); const float rstd = 1.0f / sqrtf(cst.y * (1.0f / 2048.0f) - mean * mean + 1e-5f);
;             const float sc = rstd * alpha; float s1 = 0.f, s2 = 0.f;
; #pragma unroll
;             for (int bj = 0; bj < 2; ++bj) { const size_t off = (size_t)row * ldc + col0 + bj * HALF;
;                 const f32x4 a = (cx[bj][0] - mean) * sc * g[bj][0] + b[bj][0] + acc[ai][bj][m][0], d = (cx[bj][1] - mean) * sc * g[bj][1] + b[bj][1] + acc[ai][bj][m][1];
;                 *(f32x4*)(Dst + off) = a; *(f32x4*)(Dst + off + 4) = d;
;                 if (OUTB) { u32x4 pw; pw.x = cvt_pk_bf16(a[0], a[1]); pw.y = cvt_pk_bf16(a[2], a[3]); pw.z = cvt_pk_bf16(d[0], d[1]); pw.w = cvt_pk_bf16(d[2], d[3]);
;                     *(u32x4*)(YB + off) = pw;
;                     s1 += ((a[0] + a[1]) + (a[2] + a[3])) + ((d[0] + d[1]) + (d[2] + d[3]));
;                     s2 += ((a[0] * a[0] + a[1] * a[1]) + (a[2] * a[2] + a[3] * a[3])) + ((d[0] * d[0] + d[1] * d[1]) + (d[2] * d[2] + d[3] * d[3])); } }
;             if (OUTB) { s1 += __shfl_xor(s1, 16); s2 += __shfl_xor(s2, 16); s1 += __shfl_xor(s1, 32); s2 += __shfl_xor(s2, 32);
;                 if (fq == 0) { __hip_atomic_fetch_add(st_out + 2 * row, s1, __ATOMIC_RELAXED, __HIP_MEMORY_SCOPE_AGENT); __hip_atomic_fetch_add(st_out + 2 * row + 1, s2, __ATOMIC_RELAXED, __HIP_MEMORY_SCOPE_AGENT); } } }
	v_pk_add_f32 v[120:121], v[120:121], v[152:153]
	v_lshlrev_b64 v[158:159], 1, v[200:201]
	v_lshl_add_u64 v[156:157], v[200:201], 2, s[18:19]
	v_cvt_pk_bf16_f32 v152, v124, v125
	v_cvt_pk_bf16_f32 v153, v126, v127
	v_cvt_pk_bf16_f32 v154, v120, v121
	v_cvt_pk_bf16_f32 v155, v122, v123
	v_lshl_add_u64 v[200:201], s[24:25], 0, v[158:159]
	global_store_dwordx4 v[156:157], v[124:127], off
	global_store_dwordx4 v[156:157], v[120:123], off offset:16
	global_store_dwordx4 v[200:201], v[152:155], off
	v_or_b32_e32 v158, 0x100, v158
	s_nop 0
	v_add_f32_e32 v152, v124, v125
	v_add_f32_e32 v153, v126, v127
	v_add_f32_e32 v152, v152, v153
	v_add_f32_e32 v153, v120, v121
	v_mul_f32_e32 v125, v125, v125
	v_mul_f32_e32 v121, v121, v121
	v_fmac_f32_e32 v125, v124, v124
	v_mul_f32_e32 v124, v127, v127
	v_fmac_f32_e32 v121, v120, v120
	v_mul_f32_e32 v120, v123, v123
	v_fmac_f32_e32 v124, v126, v126
	v_fmac_f32_e32 v120, v122, v122
	v_add_f32_e32 v124, v125, v124
	v_add_f32_e32 v120, v121, v120
	v_add_f32_e32 v154, v122, v123
	v_add_f32_e32 v124, v124, v120
	v_sub_f32_e32 v121, v149, v206
	v_sub_f32_e32 v120, v148, v206
	v_sub_f32_e32 v123, v151, v206
	v_sub_f32_e32 v122, v150, v206
	v_pk_mul_f32 v[122:123], v[122:123], v[218:219] op_sel_hi:[1,0]
	v_pk_mul_f32 v[120:121], v[120:121], v[218:219] op_sel_hi:[1,0]
	v_pk_fma_f32 v[122:123], v[74:75], v[122:123], v[182:183]
	v_pk_fma_f32 v[120:121], v[72:73], v[120:121], v[184:185]
	v_pk_add_f32 v[118:119], v[118:119], v[122:123]
	v_pk_add_f32 v[116:117], v[116:117], v[120:121]
	v_sub_f32_e32 v121, v145, v206
	v_sub_f32_e32 v120, v144, v206
	v_sub_f32_e32 v123, v147, v206
	v_sub_f32_e32 v122, v146, v206
	v_pk_mul_f32 v[122:123], v[122:123], v[218:219] op_sel_hi:[1,0]
	v_pk_mul_f32 v[120:121], v[120:121], v[218:219] op_sel_hi:[1,0]
	v_pk_fma_f32 v[122:123], v[66:67], v[122:123], v[178:179]
	v_pk_fma_f32 v[120:121], v[64:65], v[120:121], v[180:181]
	v_pk_add_f32 v[122:123], v[114:115], v[122:123]
	v_pk_add_f32 v[120:121], v[112:113], v[120:121]
	v_add_f32_e32 v112, v116, v117
	v_add_f32_e32 v113, v118, v119
	v_add_f32_e32 v112, v112, v113
	v_add_f32_e32 v113, v120, v121
	v_add_f32_e32 v114, v122, v123
	v_add_f32_e32 v113, v113, v114
	v_add_f32_e32 v112, v112, v113
	v_mul_f32_e32 v113, v117, v117
	v_mul_f32_e32 v114, v119, v119
	v_fmac_f32_e32 v113, v116, v116
	v_fmac_f32_e32 v114, v118, v118
	v_add_f32_e32 v113, v113, v114
	v_mul_f32_e32 v114, v121, v121
	v_mul_f32_e32 v115, v123, v123
	v_add_f32_e32 v153, v153, v154
	v_fmac_f32_e32 v114, v120, v120
	v_fmac_f32_e32 v115, v122, v122
	v_add_f32_e32 v152, v152, v153
	v_add_f32_e32 v114, v114, v115
	v_add_f32_e32 v152, 0, v152
	v_add_f32_e32 v113, v113, v114
	v_add_f32_e32 v112, v112, v152
	v_add_f32_e32 v113, v124, v113
	ds_bpermute_b32 v114, v216, v112
	ds_bpermute_b32 v115, v216, v113
	global_store_dwordx4 v[156:157], v[116:119], off offset:512
	global_store_dwordx4 v[156:157], v[120:123], off offset:528
	s_waitcnt lgkmcnt(1)
	v_add_f32_e32 v112, v112, v114
	s_waitcnt lgkmcnt(0)
	v_add_f32_e32 v113, v113, v115
	ds_bpermute_b32 v114, v195, v112
	ds_bpermute_b32 v115, v195, v113
	v_cvt_pk_bf16_f32 v116, v116, v117
	v_cvt_pk_bf16_f32 v117, v118, v119
	v_cvt_pk_bf16_f32 v118, v120, v121
	v_cvt_pk_bf16_f32 v119, v122, v123
	v_lshl_add_u64 v[120:121], s[24:25], 0, v[158:159]
	global_store_dwordx4 v[120:121], v[116:119], off
	s_waitcnt lgkmcnt(1)
	v_add_f32_e32 v112, v112, v114
	s_waitcnt lgkmcnt(0)
	v_add_f32_e32 v113, v113, v115
	s_mov_b32 s90, 0xffff0000
	s_mov_b32 s91, 0
	v_cndmask_b32_e64 v252, v252, v112, s[90:91]
	v_cndmask_b32_e64 v253, v253, v113, s[90:91]
	v_or_b32_e32 v146, 48, v194
	v_lshlrev_b32_e32 v144, 1, v146
	v_ashrrev_i32_e32 v145, 31, v144
	v_lshl_add_u64 v[112:113], v[144:145], 2, s[14:15]
	s_waitcnt vmcnt(8)
	v_pk_mul_f32 v[150:151], v[204:205], s[46:47] op_sel_hi:[1,0]
	global_load_dwordx2 v[148:149], v[112:113], off
	v_fma_f32 v112, -v150, v150, v151
	v_add_f32_e32 v112, 0x3727c5ac, v112
	v_mul_f32_e32 v113, 0x4f800000, v112
	v_cmp_gt_f32_e32 vcc, s77, v112
	v_ashrrev_i32_e32 v147, 31, v146
	s_waitcnt vmcnt(7)
	v_sub_f32_e32 v141, v141, v150
	s_waitcnt lgkmcnt(1)
	v_cndmask_b32_e32 v114, v112, v113, vcc
	s_waitcnt lgkmcnt(0)
	v_sqrt_f32_e32 v115, v114
	v_lshlrev_b64 v[112:113], 13, v[146:147]
	v_lshl_add_u64 v[112:113], s[28:29], 0, v[112:113]
	v_lshl_add_u64 v[116:117], v[176:177], 2, v[112:113]
	v_add_u32_e32 v112, -1, v115
	v_fma_f32 v113, -v112, v115, v114
	v_cmp_ge_f32_e64 s[10:11], 0, v113
	v_add_u32_e32 v113, 1, v115
	v_sub_f32_e32 v140, v140, v150
	v_cndmask_b32_e64 v112, v115, v112, s[10:11]
	v_fma_f32 v115, -v113, v115, v114
	v_cmp_lt_f32_e64 s[10:11], 0, v115
	v_sub_f32_e32 v143, v143, v150
	v_sub_f32_e32 v142, v142, v150
	v_cndmask_b32_e64 v112, v112, v113, s[10:11]
	v_mul_f32_e32 v113, 0x37800000, v112
	v_cndmask_b32_e32 v112, v112, v113, vcc
	v_cmp_class_f32_e32 vcc, v114, v215
	v_sub_f32_e32 v137, v137, v150
	v_sub_f32_e32 v136, v136, v150
	v_cndmask_b32_e32 v151, v112, v114, vcc
	global_load_dwordx4 v[120:123], v[116:117], off offset:16
	global_load_dwordx4 v[124:127], v[116:117], off
	global_load_dwordx4 v[112:115], v[116:117], off offset:528
	s_nop 0
	global_load_dwordx4 v[116:119], v[116:117], off offset:512
	v_div_scale_f32 v152, s[10:11], v151, v151, 1.0
	v_rcp_f32_e32 v153, v152
	v_sub_f32_e32 v139, v139, v150
	v_sub_f32_e32 v138, v138, v150
	v_fma_f32 v154, -v152, v153, 1.0
	v_fmac_f32_e32 v153, v154, v153
	v_div_scale_f32 v154, vcc, 1.0, v151, 1.0
	v_mul_f32_e32 v155, v154, v153
	v_fma_f32 v156, -v152, v155, v154
	v_fmac_f32_e32 v155, v156, v153
	v_fma_f32 v152, -v152, v155, v154
	v_div_fmas_f32 v152, v152, v153, v155
;     __device__ __forceinline__ void operator()(const f32x4 (&acc)[2][2][4][2], const Unit& u, int wr, int wc, int fr, int fq) const {
;     ...
;         for (int r = 0; r < 8; ++r) { const int ai = r >> 2, m = r & 3; const int row = row0 + ai * HALF + m * 16;
;             f32x4 cx[2][2]; const f32x2v cst = nst;
; #pragma unroll
;             for (int bj = 0; bj < 2; ++bj) { cx[bj][0] = nx[bj][0]; cx[bj][1] = nx[bj][1]; }
;             if (r + 1 < 8) { const int rown = row0 + ((r + 1) >> 2) * HALF + ((r + 1) & 3) * 16; nst = *(const f32x2v*)(st_in + 2 * rown);
; #pragma unroll
;                 for (int bj = 0; bj < 2; ++bj) { const size_t off = (size_t)rown * ldc + col0 + bj * HALF; nx[bj][0] = *(const f32x4*)(Src + off); nx[bj][1] = *(const f32x4*)(Src + off + 4); } }
;             const float mean = cst.x * (1.0f / 2048.0f); const float rstd = 1.0f / sqrtf(cst.y * (1.0f / 2048.0f) - mean * mean + 1e-5f);
;             const float sc = rstd * alpha; float s1 = 0.f, s2 = 0.f;
; #pragma unroll
;             for (int bj = 0; bj < 2; ++bj) { const size_t off = (size_t)row * ldc + col0 + bj * HALF;
;                 const f32x4 a = (cx[bj][0] - mean) * sc * g[bj][0] + b[bj][0] + acc[ai][bj][m][0], d = (cx[bj][1] - mean) * sc * g[bj][1] + b[bj][1] + acc[ai][bj][m][1];
;                 *(f32x4*)(Dst + off) = a; *(f32x4*)(Dst + off + 4) = d;
;                 if (OUTB) { u32x4 pw; pw.x = cvt_pk_bf16(a[0], a[1]); pw.y = cvt_pk_bf16(a[2], a[3]); pw.z = cvt_pk_bf16(d[0], d[1]); pw.w = cvt_pk_bf16(d[2], d[3]);
;                     *(u32x4*)(YB + off) = pw;
;                     s1 += ((a[0] + a[1]) + (a[2] + a[3])) + ((d[0] + d[1]) + (d[2] + d[3]));
;                     s2 += ((a[0] * a[0] + a[1] * a[1]) + (a[2] * a[2] + a[3] * a[3])) + ((d[0] * d[0] + d[1] * d[1]) + (d[2] * d[2] + d[3] * d[3])); } }
;             if (OUTB) { s1 += __shfl_xor(s1, 16); s2 += __shfl_xor(s2, 16); s1 += __shfl_xor(s1, 32); s2 += __shfl_xor(s2, 32);
;                 if (fq == 0) { __hip_atomic_fetch_add(st_out + 2 * row, s1, __ATOMIC_RELAXED, __HIP_MEMORY_SCOPE_AGENT); __hip_atomic_fetch_add(st_out + 2 * row + 1, s2, __ATOMIC_RELAXED, __HIP_MEMORY_SCOPE_AGENT); } } }
	v_div_fixup_f32 v151, v152, v151, 1.0
	v_mul_f32_e32 v152, 0x3fb504f3, v151
	v_lshlrev_b64 v[154:155], 11, v[202:203]
	v_pk_mul_f32 v[142:143], v[142:143], v[152:153] op_sel_hi:[1,0]
	v_pk_mul_f32 v[140:141], v[140:141], v[152:153] op_sel_hi:[1,0]
	v_pk_mul_f32 v[138:139], v[138:139], v[152:153] op_sel_hi:[1,0]
	v_pk_mul_f32 v[136:137], v[136:137], v[152:153] op_sel_hi:[1,0]
	v_lshl_add_u64 v[154:155], v[154:155], 0, v[176:177]
	v_pk_fma_f32 v[140:141], v[76:77], v[140:141], v[192:193]
	v_pk_fma_f32 v[142:143], v[78:79], v[142:143], v[190:191]
	v_pk_fma_f32 v[136:137], v[68:69], v[136:137], v[188:189]
	v_pk_fma_f32 v[138:139], v[70:71], v[138:139], v[186:187]
	v_pk_add_f32 v[110:111], v[110:111], v[142:143]
	v_pk_add_f32 v[108:109], v[108:109], v[140:141]
	v_pk_add_f32 v[106:107], v[106:107], v[138:139]
	v_pk_add_f32 v[104:105], v[104:105], v[136:137]
	v_lshlrev_b64 v[142:143], 1, v[154:155]
	v_lshl_add_u64 v[140:141], v[154:155], 2, s[18:19]
	v_cvt_pk_bf16_f32 v136, v108, v109
	v_cvt_pk_bf16_f32 v137, v110, v111
	v_cvt_pk_bf16_f32 v138, v104, v105
	v_cvt_pk_bf16_f32 v139, v106, v107
	v_lshl_add_u64 v[154:155], s[24:25], 0, v[142:143]
	global_store_dwordx4 v[140:141], v[108:111], off
	global_store_dwordx4 v[140:141], v[104:107], off offset:16
	global_store_dwordx4 v[154:155], v[136:139], off
	v_or_b32_e32 v142, 0x100, v142
	s_nop 0
	v_add_f32_e32 v136, v108, v109
	v_add_f32_e32 v137, v110, v111
	v_add_f32_e32 v136, v136, v137
	v_add_f32_e32 v137, v104, v105
	v_mul_f32_e32 v109, v109, v109
	v_mul_f32_e32 v105, v105, v105
	v_fmac_f32_e32 v109, v108, v108
	v_mul_f32_e32 v108, v111, v111
	v_fmac_f32_e32 v105, v104, v104
	v_mul_f32_e32 v104, v107, v107
	v_fmac_f32_e32 v108, v110, v110
	v_fmac_f32_e32 v104, v106, v106
	v_add_f32_e32 v108, v109, v108
	v_add_f32_e32 v104, v105, v104
	v_add_f32_e32 v138, v106, v107
	v_add_f32_e32 v108, v108, v104
	s_waitcnt vmcnt(12)
	v_sub_f32_e32 v105, v133, v150
	v_sub_f32_e32 v104, v132, v150
	v_sub_f32_e32 v107, v135, v150
	v_sub_f32_e32 v106, v134, v150
	v_pk_mul_f32 v[106:107], v[106:107], v[152:153] op_sel_hi:[1,0]
	v_pk_mul_f32 v[104:105], v[104:105], v[152:153] op_sel_hi:[1,0]
	v_pk_fma_f32 v[106:107], v[74:75], v[106:107], v[182:183]
	v_pk_fma_f32 v[104:105], v[72:73], v[104:105], v[184:185]
	v_pk_add_f32 v[102:103], v[102:103], v[106:107]
	v_pk_add_f32 v[100:101], v[100:101], v[104:105]
	v_sub_f32_e32 v105, v129, v150
	v_sub_f32_e32 v104, v128, v150
	v_sub_f32_e32 v107, v131, v150
	v_sub_f32_e32 v106, v130, v150
	v_pk_mul_f32 v[106:107], v[106:107], v[152:153] op_sel_hi:[1,0]
	v_pk_mul_f32 v[104:105], v[104:105], v[152:153] op_sel_hi:[1,0]
	v_pk_fma_f32 v[106:107], v[66:67], v[106:107], v[178:179]
	v_pk_fma_f32 v[104:105], v[64:65], v[104:105], v[180:181]
	v_pk_add_f32 v[106:107], v[98:99], v[106:107]
	v_pk_add_f32 v[104:105], v[96:97], v[104:105]
	v_add_f32_e32 v96, v100, v101
	v_add_f32_e32 v97, v102, v103
	v_add_f32_e32 v96, v96, v97
	v_add_f32_e32 v97, v104, v105
	v_add_f32_e32 v98, v106, v107
	v_add_f32_e32 v97, v97, v98
	v_add_f32_e32 v96, v96, v97
	v_mul_f32_e32 v97, v101, v101
	v_mul_f32_e32 v98, v103, v103
	v_fmac_f32_e32 v97, v100, v100
	v_fmac_f32_e32 v98, v102, v102
	v_add_f32_e32 v97, v97, v98
	v_mul_f32_e32 v98, v105, v105
	v_mul_f32_e32 v99, v107, v107
	v_add_f32_e32 v137, v137, v138
	v_fmac_f32_e32 v98, v104, v104
	v_fmac_f32_e32 v99, v106, v106
	v_add_f32_e32 v136, v136, v137
	v_add_f32_e32 v98, v98, v99
	v_add_f32_e32 v136, 0, v136
	v_add_f32_e32 v97, v97, v98
	v_add_f32_e32 v96, v96, v136
	v_add_f32_e32 v97, v108, v97
	ds_bpermute_b32 v98, v216, v96
	ds_bpermute_b32 v99, v216, v97
	global_store_dwordx4 v[140:141], v[100:103], off offset:512
	global_store_dwordx4 v[140:141], v[104:107], off offset:528
	s_waitcnt lgkmcnt(1)
	v_add_f32_e32 v96, v96, v98
	s_waitcnt lgkmcnt(0)
	v_add_f32_e32 v97, v97, v99
	ds_bpermute_b32 v98, v195, v96
	ds_bpermute_b32 v99, v195, v97
	v_cvt_pk_bf16_f32 v100, v100, v101
	v_cvt_pk_bf16_f32 v101, v102, v103
	v_cvt_pk_bf16_f32 v102, v104, v105
	v_cvt_pk_bf16_f32 v103, v106, v107
	v_lshl_add_u64 v[104:105], s[24:25], 0, v[142:143]
	global_store_dwordx4 v[104:105], v[100:103], off
	s_waitcnt lgkmcnt(1)
	v_add_f32_e32 v96, v96, v98
	s_waitcnt lgkmcnt(0)
	v_add_f32_e32 v97, v97, v99
	s_mov_b32 s90, 0
	s_mov_b32 s91, 0xffff
	v_cndmask_b32_e64 v252, v252, v96, s[90:91]
	v_cndmask_b32_e64 v253, v253, v97, s[90:91]
	v_add_u32_e32 v128, 0x80, v194
	v_lshlrev_b32_e32 v130, 1, v128
	v_ashrrev_i32_e32 v131, 31, v130
	v_lshl_add_u64 v[96:97], v[130:131], 2, s[14:15]
	s_waitcnt vmcnt(8)
	v_pk_mul_f32 v[134:135], v[148:149], s[46:47] op_sel_hi:[1,0]
	global_load_dwordx2 v[132:133], v[96:97], off
	v_fma_f32 v96, -v134, v134, v135
	v_add_f32_e32 v96, 0x3727c5ac, v96
	v_mul_f32_e32 v97, 0x4f800000, v96
	v_cmp_gt_f32_e32 vcc, s77, v96
	v_ashrrev_i32_e32 v129, 31, v128
	s_waitcnt vmcnt(7)
	v_sub_f32_e32 v125, v125, v134
	s_waitcnt lgkmcnt(1)
	v_cndmask_b32_e32 v98, v96, v97, vcc
	s_waitcnt lgkmcnt(0)
;     __device__ __forceinline__ void operator()(const f32x4 (&acc)[2][2][4][2], const Unit& u, int wr, int wc, int fr, int fq) const {
;     ...
;         for (int r = 0; r < 8; ++r) { const int ai = r >> 2, m = r & 3; const int row = row0 + ai * HALF + m * 16;
;             f32x4 cx[2][2]; const f32x2v cst = nst;
; #pragma unroll
;             for (int bj = 0; bj < 2; ++bj) { cx[bj][0] = nx[bj][0]; cx[bj][1] = nx[bj][1]; }
;             if (r + 1 < 8) { const int rown = row0 + ((r + 1) >> 2) * HALF + ((r + 1) & 3) * 16; nst = *(const f32x2v*)(st_in + 2 * rown);
; #pragma unroll
;                 for (int bj = 0; bj < 2; ++bj) { const size_t off = (size_t)rown * ldc + col0 + bj * HALF; nx[bj][0] = *(const f32x4*)(Src + off); nx[bj][1] = *(const f32x4*)(Src + off + 4); } }
;             const float mean = cst.x * (1.0f / 2048.0f); const float rstd = 1.0f / sqrtf(cst.y * (1.0f / 2048.0f) - mean * mean + 1e-5f);
;             const float sc = rstd * alpha; float s1 = 0.f, s2 = 0.f;
; #pragma unroll
;             for (int bj = 0; bj < 2; ++bj) { const size_t off = (size_t)row * ldc + col0 + bj * HALF;
;                 const f32x4 a = (cx[bj][0] - mean) * sc * g[bj][0] + b[bj][0] + acc[ai][bj][m][0], d = (cx[bj][1] - mean) * sc * g[bj][1] + b[bj][1] + acc[ai][bj][m][1];
;                 *(f32x4*)(Dst + off) = a; *(f32x4*)(Dst + off + 4) = d;
;                 if (OUTB) { u32x4 pw; pw.x = cvt_pk_bf16(a[0], a[1]); pw.y = cvt_pk_bf16(a[2], a[3]); pw.z = cvt_pk_bf16(d[0], d[1]); pw.w = cvt_pk_bf16(d[2], d[3]);
;                     *(u32x4*)(YB + off) = pw;
;                     s1 += ((a[0] + a[1]) + (a[2] + a[3])) + ((d[0] + d[1]) + (d[2] + d[3]));
;                     s2 += ((a[0] * a[0] + a[1] * a[1]) + (a[2] * a[2] + a[3] * a[3])) + ((d[0] * d[0] + d[1] * d[1]) + (d[2] * d[2] + d[3] * d[3])); } }
;             if (OUTB) { s1 += __shfl_xor(s1, 16); s2 += __shfl_xor(s2, 16); s1 += __shfl_xor(s1, 32); s2 += __shfl_xor(s2, 32);
;                 if (fq == 0) { __hip_atomic_fetch_add(st_out + 2 * row, s1, __ATOMIC_RELAXED, __HIP_MEMORY_SCOPE_AGENT); __hip_atomic_fetch_add(st_out + 2 * row + 1, s2, __ATOMIC_RELAXED, __HIP_MEMORY_SCOPE_AGENT); } } }
	v_sqrt_f32_e32 v99, v98
	v_lshlrev_b64 v[96:97], 13, v[128:129]
	v_lshl_add_u64 v[96:97], s[28:29], 0, v[96:97]
	v_lshl_add_u64 v[100:101], v[176:177], 2, v[96:97]
	v_add_u32_e32 v96, -1, v99
	v_fma_f32 v97, -v96, v99, v98
	v_cmp_ge_f32_e64 s[10:11], 0, v97
	v_add_u32_e32 v97, 1, v99
	v_sub_f32_e32 v124, v124, v134
	v_cndmask_b32_e64 v96, v99, v96, s[10:11]
	v_fma_f32 v99, -v97, v99, v98
	v_cmp_lt_f32_e64 s[10:11], 0, v99
	v_sub_f32_e32 v127, v127, v134
	v_sub_f32_e32 v126, v126, v134
	v_cndmask_b32_e64 v96, v96, v97, s[10:11]
	v_mul_f32_e32 v97, 0x37800000, v96
	v_cndmask_b32_e32 v96, v96, v97, vcc
	v_cmp_class_f32_e32 vcc, v98, v215
	v_sub_f32_e32 v121, v121, v134
	v_sub_f32_e32 v120, v120, v134
	v_cndmask_b32_e32 v135, v96, v98, vcc
	global_load_dwordx4 v[104:107], v[100:101], off offset:16
	global_load_dwordx4 v[108:111], v[100:101], off
	global_load_dwordx4 v[96:99], v[100:101], off offset:528
	s_nop 0
	global_load_dwordx4 v[100:103], v[100:101], off offset:512
	v_div_scale_f32 v136, s[10:11], v135, v135, 1.0
	v_rcp_f32_e32 v137, v136
	v_sub_f32_e32 v123, v123, v134
	v_sub_f32_e32 v122, v122, v134
	v_fma_f32 v138, -v136, v137, 1.0
	v_fmac_f32_e32 v137, v138, v137
	v_div_scale_f32 v138, vcc, 1.0, v135, 1.0
	v_mul_f32_e32 v139, v138, v137
	v_fma_f32 v140, -v136, v139, v138
	v_fmac_f32_e32 v139, v140, v137
	v_fma_f32 v136, -v136, v139, v138
	v_div_fmas_f32 v136, v136, v137, v139
	v_div_fixup_f32 v135, v136, v135, 1.0
	v_mul_f32_e32 v136, 0x3fb504f3, v135
	v_lshlrev_b64 v[138:139], 11, v[146:147]
	v_pk_mul_f32 v[126:127], v[126:127], v[136:137] op_sel_hi:[1,0]
	v_pk_mul_f32 v[124:125], v[124:125], v[136:137] op_sel_hi:[1,0]
	v_pk_mul_f32 v[122:123], v[122:123], v[136:137] op_sel_hi:[1,0]
	v_pk_mul_f32 v[120:121], v[120:121], v[136:137] op_sel_hi:[1,0]
	v_lshl_add_u64 v[138:139], v[138:139], 0, v[176:177]
	v_pk_fma_f32 v[124:125], v[76:77], v[124:125], v[192:193]
	v_pk_fma_f32 v[126:127], v[78:79], v[126:127], v[190:191]
	v_pk_fma_f32 v[120:121], v[68:69], v[120:121], v[188:189]
	v_pk_fma_f32 v[122:123], v[70:71], v[122:123], v[186:187]
	v_pk_add_f32 v[94:95], v[94:95], v[126:127]
	v_pk_add_f32 v[92:93], v[92:93], v[124:125]
	v_pk_add_f32 v[90:91], v[90:91], v[122:123]
	v_pk_add_f32 v[88:89], v[88:89], v[120:121]
	v_lshlrev_b64 v[126:127], 1, v[138:139]
	v_lshl_add_u64 v[124:125], v[138:139], 2, s[18:19]
	v_cvt_pk_bf16_f32 v120, v92, v93
	v_cvt_pk_bf16_f32 v121, v94, v95
	v_cvt_pk_bf16_f32 v122, v88, v89
	v_cvt_pk_bf16_f32 v123, v90, v91
	v_lshl_add_u64 v[138:139], s[24:25], 0, v[126:127]
	global_store_dwordx4 v[124:125], v[92:95], off
	global_store_dwordx4 v[124:125], v[88:91], off offset:16
	global_store_dwordx4 v[138:139], v[120:123], off
	v_or_b32_e32 v126, 0x100, v126
	s_nop 0
	v_add_f32_e32 v120, v92, v93
	v_add_f32_e32 v121, v94, v95
	v_add_f32_e32 v120, v120, v121
	v_add_f32_e32 v121, v88, v89
	v_mul_f32_e32 v93, v93, v93
	v_mul_f32_e32 v89, v89, v89
	v_fmac_f32_e32 v93, v92, v92
	v_mul_f32_e32 v92, v95, v95
	v_fmac_f32_e32 v89, v88, v88
	v_mul_f32_e32 v88, v91, v91
	v_fmac_f32_e32 v92, v94, v94
	v_fmac_f32_e32 v88, v90, v90
	v_add_f32_e32 v92, v93, v92
	v_add_f32_e32 v88, v89, v88
	v_add_f32_e32 v122, v90, v91
	v_add_f32_e32 v92, v92, v88
	s_waitcnt vmcnt(12)
	v_sub_f32_e32 v89, v117, v134
	v_sub_f32_e32 v88, v116, v134
	v_sub_f32_e32 v91, v119, v134
	v_sub_f32_e32 v90, v118, v134
	v_pk_mul_f32 v[90:91], v[90:91], v[136:137] op_sel_hi:[1,0]
	v_pk_mul_f32 v[88:89], v[88:89], v[136:137] op_sel_hi:[1,0]
	v_pk_fma_f32 v[90:91], v[74:75], v[90:91], v[182:183]
	v_pk_fma_f32 v[88:89], v[72:73], v[88:89], v[184:185]
	v_pk_add_f32 v[86:87], v[86:87], v[90:91]
	v_pk_add_f32 v[84:85], v[84:85], v[88:89]
	v_sub_f32_e32 v89, v113, v134
	v_sub_f32_e32 v88, v112, v134
	v_sub_f32_e32 v91, v115, v134
	v_sub_f32_e32 v90, v114, v134
	v_pk_mul_f32 v[90:91], v[90:91], v[136:137] op_sel_hi:[1,0]
	v_pk_mul_f32 v[88:89], v[88:89], v[136:137] op_sel_hi:[1,0]
	v_pk_fma_f32 v[90:91], v[66:67], v[90:91], v[178:179]
	v_pk_fma_f32 v[88:89], v[64:65], v[88:89], v[180:181]
	v_pk_add_f32 v[90:91], v[82:83], v[90:91]
	v_pk_add_f32 v[88:89], v[80:81], v[88:89]
	v_add_f32_e32 v80, v84, v85
	v_add_f32_e32 v81, v86, v87
	v_add_f32_e32 v80, v80, v81
	v_add_f32_e32 v81, v88, v89
	v_add_f32_e32 v82, v90, v91
	v_add_f32_e32 v81, v81, v82
	v_add_f32_e32 v80, v80, v81
	v_mul_f32_e32 v81, v85, v85
	v_mul_f32_e32 v82, v87, v87
	v_fmac_f32_e32 v81, v84, v84
	v_fmac_f32_e32 v82, v86, v86
	v_add_f32_e32 v81, v81, v82
	v_mul_f32_e32 v82, v89, v89
	v_mul_f32_e32 v83, v91, v91
	v_add_f32_e32 v121, v121, v122
	v_fmac_f32_e32 v82, v88, v88
	v_fmac_f32_e32 v83, v90, v90
	v_add_f32_e32 v120, v120, v121
	v_add_f32_e32 v82, v82, v83
	v_add_f32_e32 v120, 0, v120
	v_add_f32_e32 v81, v81, v82
	v_add_f32_e32 v80, v80, v120
	v_add_f32_e32 v81, v92, v81
	ds_bpermute_b32 v82, v216, v80
	ds_bpermute_b32 v83, v216, v81
	global_store_dwordx4 v[124:125], v[84:87], off offset:512
	global_store_dwordx4 v[124:125], v[88:91], off offset:528
	s_waitcnt lgkmcnt(1)
	v_add_f32_e32 v80, v80, v82
	s_waitcnt lgkmcnt(0)
	v_add_f32_e32 v81, v81, v83
	ds_bpermute_b32 v82, v195, v80
	ds_bpermute_b32 v83, v195, v81
	v_cvt_pk_bf16_f32 v84, v84, v85
	v_cvt_pk_bf16_f32 v85, v86, v87
	v_cvt_pk_bf16_f32 v86, v88, v89
	v_cvt_pk_bf16_f32 v87, v90, v91
	v_lshl_add_u64 v[88:89], s[24:25], 0, v[126:127]
	global_store_dwordx4 v[88:89], v[84:87], off
	s_waitcnt lgkmcnt(1)
	v_add_f32_e32 v80, v80, v82
	s_waitcnt lgkmcnt(0)
	v_add_f32_e32 v81, v81, v83
	s_mov_b32 s90, 0
	s_mov_b32 s91, 0xffff0000
	v_cndmask_b32_e64 v252, v252, v80, s[90:91]
	v_cndmask_b32_e64 v253, v253, v81, s[90:91]
	v_or_b32_e32 v114, 16, v128
	v_lshlrev_b32_e32 v112, 1, v114
	v_ashrrev_i32_e32 v113, 31, v112
	v_lshl_add_u64 v[80:81], v[112:113], 2, s[14:15]
	s_waitcnt vmcnt(8)
;     __device__ __forceinline__ void operator()(const f32x4 (&acc)[2][2][4][2], const Unit& u, int wr, int wc, int fr, int fq) const {
;     ...
;         for (int r = 0; r < 8; ++r) { const int ai = r >> 2, m = r & 3; const int row = row0 + ai * HALF + m * 16;
;             f32x4 cx[2][2]; const f32x2v cst = nst;
; #pragma unroll
;             for (int bj = 0; bj < 2; ++bj) { cx[bj][0] = nx[bj][0]; cx[bj][1] = nx[bj][1]; }
;             if (r + 1 < 8) { const int rown = row0 + ((r + 1) >> 2) * HALF + ((r + 1) & 3) * 16; nst = *(const f32x2v*)(st_in + 2 * rown);
; #pragma unroll
;                 for (int bj = 0; bj < 2; ++bj) { const size_t off = (size_t)rown * ldc + col0 + bj * HALF; nx[bj][0] = *(const f32x4*)(Src + off); nx[bj][1] = *(const f32x4*)(Src + off + 4); } }
;             const float mean = cst.x * (1.0f / 2048.0f); const float rstd = 1.0f / sqrtf(cst.y * (1.0f / 2048.0f) - mean * mean + 1e-5f);
;             const float sc = rstd * alpha; float s1 = 0.f, s2 = 0.f;
; #pragma unroll
;             for (int bj = 0; bj < 2; ++bj) { const size_t off = (size_t)row * ldc + col0 + bj * HALF;
;                 const f32x4 a = (cx[bj][0] - mean) * sc * g[bj][0] + b[bj][0] + acc[ai][bj][m][0], d = (cx[bj][1] - mean) * sc * g[bj][1] + b[bj][1] + acc[ai][bj][m][1];
;                 *(f32x4*)(Dst + off) = a; *(f32x4*)(Dst + off + 4) = d;
;                 if (OUTB) { u32x4 pw; pw.x = cvt_pk_bf16(a[0], a[1]); pw.y = cvt_pk_bf16(a[2], a[3]); pw.z = cvt_pk_bf16(d[0], d[1]); pw.w = cvt_pk_bf16(d[2], d[3]);
;                     *(u32x4*)(YB + off) = pw;
;                     s1 += ((a[0] + a[1]) + (a[2] + a[3])) + ((d[0] + d[1]) + (d[2] + d[3]));
;                     s2 += ((a[0] * a[0] + a[1] * a[1]) + (a[2] * a[2] + a[3] * a[3])) + ((d[0] * d[0] + d[1] * d[1]) + (d[2] * d[2] + d[3] * d[3])); } }
;             if (OUTB) { s1 += __shfl_xor(s1, 16); s2 += __shfl_xor(s2, 16); s1 += __shfl_xor(s1, 32); s2 += __shfl_xor(s2, 32);
;                 if (fq == 0) { __hip_atomic_fetch_add(st_out + 2 * row, s1, __ATOMIC_RELAXED, __HIP_MEMORY_SCOPE_AGENT); __hip_atomic_fetch_add(st_out + 2 * row + 1, s2, __ATOMIC_RELAXED, __HIP_MEMORY_SCOPE_AGENT); } } }
	v_pk_mul_f32 v[118:119], v[132:133], s[46:47] op_sel_hi:[1,0]
	global_load_dwordx2 v[116:117], v[80:81], off
	v_fma_f32 v80, -v118, v118, v119
	v_add_f32_e32 v80, 0x3727c5ac, v80
	v_mul_f32_e32 v81, 0x4f800000, v80
	v_cmp_gt_f32_e32 vcc, s77, v80
	v_ashrrev_i32_e32 v115, 31, v114
	s_waitcnt vmcnt(7)
	v_sub_f32_e32 v109, v109, v118
	s_waitcnt lgkmcnt(1)
	v_cndmask_b32_e32 v82, v80, v81, vcc
	s_waitcnt lgkmcnt(0)
	v_sqrt_f32_e32 v83, v82
	v_lshlrev_b64 v[80:81], 13, v[114:115]
	v_lshl_add_u64 v[80:81], s[28:29], 0, v[80:81]
	v_lshl_add_u64 v[84:85], v[176:177], 2, v[80:81]
	v_add_u32_e32 v80, -1, v83
	v_fma_f32 v81, -v80, v83, v82
	v_cmp_ge_f32_e64 s[10:11], 0, v81
	v_add_u32_e32 v81, 1, v83
	v_sub_f32_e32 v108, v108, v118
	v_cndmask_b32_e64 v80, v83, v80, s[10:11]
	v_fma_f32 v83, -v81, v83, v82
	v_cmp_lt_f32_e64 s[10:11], 0, v83
	v_sub_f32_e32 v111, v111, v118
	v_sub_f32_e32 v110, v110, v118
	v_cndmask_b32_e64 v80, v80, v81, s[10:11]
	v_mul_f32_e32 v81, 0x37800000, v80
	v_cndmask_b32_e32 v80, v80, v81, vcc
	v_cmp_class_f32_e32 vcc, v82, v215
	v_sub_f32_e32 v105, v105, v118
	v_sub_f32_e32 v104, v104, v118
	v_cndmask_b32_e32 v119, v80, v82, vcc
	global_load_dwordx4 v[88:91], v[84:85], off offset:16
	global_load_dwordx4 v[92:95], v[84:85], off
	global_load_dwordx4 v[80:83], v[84:85], off offset:528
	s_nop 0
	global_load_dwordx4 v[84:87], v[84:85], off offset:512
	v_div_scale_f32 v120, s[10:11], v119, v119, 1.0
	v_rcp_f32_e32 v121, v120
	v_sub_f32_e32 v107, v107, v118
	v_sub_f32_e32 v106, v106, v118
	v_fma_f32 v122, -v120, v121, 1.0
	v_fmac_f32_e32 v121, v122, v121
	v_div_scale_f32 v122, vcc, 1.0, v119, 1.0
	v_mul_f32_e32 v123, v122, v121
	v_fma_f32 v124, -v120, v123, v122
	v_fmac_f32_e32 v123, v124, v121
	v_fma_f32 v120, -v120, v123, v122
	v_div_fmas_f32 v120, v120, v121, v123
	v_div_fixup_f32 v119, v120, v119, 1.0
	v_mul_f32_e32 v120, 0x3fb504f3, v119
	v_lshlrev_b64 v[122:123], 11, v[128:129]
	v_pk_mul_f32 v[110:111], v[110:111], v[120:121] op_sel_hi:[1,0]
	v_pk_mul_f32 v[108:109], v[108:109], v[120:121] op_sel_hi:[1,0]
	v_pk_mul_f32 v[106:107], v[106:107], v[120:121] op_sel_hi:[1,0]
	v_pk_mul_f32 v[104:105], v[104:105], v[120:121] op_sel_hi:[1,0]
	v_lshl_add_u64 v[122:123], v[122:123], 0, v[176:177]
	v_pk_fma_f32 v[108:109], v[76:77], v[108:109], v[192:193]
	v_pk_fma_f32 v[110:111], v[78:79], v[110:111], v[190:191]
	v_pk_fma_f32 v[104:105], v[68:69], v[104:105], v[188:189]
	v_pk_fma_f32 v[106:107], v[70:71], v[106:107], v[186:187]
	v_pk_add_f32 v[62:63], v[62:63], v[110:111]
	v_pk_add_f32 v[60:61], v[60:61], v[108:109]
	v_pk_add_f32 v[58:59], v[58:59], v[106:107]
	v_pk_add_f32 v[56:57], v[56:57], v[104:105]
	v_lshlrev_b64 v[110:111], 1, v[122:123]
	v_lshl_add_u64 v[108:109], v[122:123], 2, s[18:19]
	v_cvt_pk_bf16_f32 v104, v60, v61
	v_cvt_pk_bf16_f32 v105, v62, v63
	v_cvt_pk_bf16_f32 v106, v56, v57
	v_cvt_pk_bf16_f32 v107, v58, v59
	v_lshl_add_u64 v[122:123], s[24:25], 0, v[110:111]
	global_store_dwordx4 v[108:109], v[60:63], off
	global_store_dwordx4 v[108:109], v[56:59], off offset:16
	global_store_dwordx4 v[122:123], v[104:107], off
	v_or_b32_e32 v110, 0x100, v110
	s_nop 0
	v_add_f32_e32 v104, v60, v61
	v_add_f32_e32 v105, v62, v63
	v_add_f32_e32 v104, v104, v105
	v_add_f32_e32 v105, v56, v57
	v_mul_f32_e32 v61, v61, v61
	v_mul_f32_e32 v57, v57, v57
	v_fmac_f32_e32 v61, v60, v60
	v_mul_f32_e32 v60, v63, v63
	v_fmac_f32_e32 v57, v56, v56
	v_mul_f32_e32 v56, v59, v59
	v_fmac_f32_e32 v60, v62, v62
	v_fmac_f32_e32 v56, v58, v58
	v_add_f32_e32 v60, v61, v60
	v_add_f32_e32 v56, v57, v56
	v_add_f32_e32 v106, v58, v59
	v_add_f32_e32 v60, v60, v56
	s_waitcnt vmcnt(12)
	v_sub_f32_e32 v57, v101, v118
	v_sub_f32_e32 v56, v100, v118
	v_sub_f32_e32 v59, v103, v118
	v_sub_f32_e32 v58, v102, v118
	v_pk_mul_f32 v[58:59], v[58:59], v[120:121] op_sel_hi:[1,0]
	v_pk_mul_f32 v[56:57], v[56:57], v[120:121] op_sel_hi:[1,0]
	v_pk_fma_f32 v[58:59], v[74:75], v[58:59], v[182:183]
	v_pk_fma_f32 v[56:57], v[72:73], v[56:57], v[184:185]
	v_pk_add_f32 v[54:55], v[54:55], v[58:59]
	v_pk_add_f32 v[52:53], v[52:53], v[56:57]
	v_sub_f32_e32 v57, v97, v118
	v_sub_f32_e32 v56, v96, v118
	v_sub_f32_e32 v59, v99, v118
	v_sub_f32_e32 v58, v98, v118
	v_pk_mul_f32 v[58:59], v[58:59], v[120:121] op_sel_hi:[1,0]
	v_pk_mul_f32 v[56:57], v[56:57], v[120:121] op_sel_hi:[1,0]
	v_pk_fma_f32 v[58:59], v[66:67], v[58:59], v[178:179]
	v_pk_fma_f32 v[56:57], v[64:65], v[56:57], v[180:181]
	v_pk_add_f32 v[58:59], v[50:51], v[58:59]
	v_pk_add_f32 v[56:57], v[48:49], v[56:57]
	v_add_f32_e32 v48, v52, v53
	v_add_f32_e32 v49, v54, v55
	v_add_f32_e32 v48, v48, v49
	v_add_f32_e32 v49, v56, v57
	v_add_f32_e32 v50, v58, v59
	v_add_f32_e32 v49, v49, v50
	v_add_f32_e32 v48, v48, v49
	v_mul_f32_e32 v49, v53, v53
	v_mul_f32_e32 v50, v55, v55
	v_fmac_f32_e32 v49, v52, v52
	v_fmac_f32_e32 v50, v54, v54
	v_add_f32_e32 v49, v49, v50
	v_mul_f32_e32 v50, v57, v57
	v_mul_f32_e32 v51, v59, v59
	v_add_f32_e32 v105, v105, v106
	v_fmac_f32_e32 v50, v56, v56
	v_fmac_f32_e32 v51, v58, v58
	v_add_f32_e32 v104, v104, v105
	v_add_f32_e32 v50, v50, v51
	v_add_f32_e32 v104, 0, v104
	v_add_f32_e32 v49, v49, v50
	v_add_f32_e32 v48, v48, v104
	v_add_f32_e32 v49, v60, v49
	ds_bpermute_b32 v50, v216, v48
	ds_bpermute_b32 v51, v216, v49
	global_store_dwordx4 v[108:109], v[52:55], off offset:512
	global_store_dwordx4 v[108:109], v[56:59], off offset:528
	s_waitcnt lgkmcnt(1)
	v_add_f32_e32 v48, v48, v50
	s_waitcnt lgkmcnt(0)
	v_add_f32_e32 v49, v49, v51
	ds_bpermute_b32 v50, v195, v48
	ds_bpermute_b32 v51, v195, v49
	v_cvt_pk_bf16_f32 v52, v52, v53
	v_cvt_pk_bf16_f32 v53, v54, v55
	v_cvt_pk_bf16_f32 v54, v56, v57
	v_cvt_pk_bf16_f32 v55, v58, v59
	v_lshl_add_u64 v[56:57], s[24:25], 0, v[110:111]
	global_store_dwordx4 v[56:57], v[52:55], off
	s_waitcnt lgkmcnt(1)
;     __device__ __forceinline__ void operator()(const f32x4 (&acc)[2][2][4][2], const Unit& u, int wr, int wc, int fr, int fq) const {
;     ...
;         for (int r = 0; r < 8; ++r) { const int ai = r >> 2, m = r & 3; const int row = row0 + ai * HALF + m * 16;
;             f32x4 cx[2][2]; const f32x2v cst = nst;
; #pragma unroll
;             for (int bj = 0; bj < 2; ++bj) { cx[bj][0] = nx[bj][0]; cx[bj][1] = nx[bj][1]; }
;             if (r + 1 < 8) { const int rown = row0 + ((r + 1) >> 2) * HALF + ((r + 1) & 3) * 16; nst = *(const f32x2v*)(st_in + 2 * rown);
; #pragma unroll
;                 for (int bj = 0; bj < 2; ++bj) { const size_t off = (size_t)rown * ldc + col0 + bj * HALF; nx[bj][0] = *(const f32x4*)(Src + off); nx[bj][1] = *(const f32x4*)(Src + off + 4); } }
;             const float mean = cst.x * (1.0f / 2048.0f); const float rstd = 1.0f / sqrtf(cst.y * (1.0f / 2048.0f) - mean * mean + 1e-5f);
;             const float sc = rstd * alpha; float s1 = 0.f, s2 = 0.f;
; #pragma unroll
;             for (int bj = 0; bj < 2; ++bj) { const size_t off = (size_t)row * ldc + col0 + bj * HALF;
;                 const f32x4 a = (cx[bj][0] - mean) * sc * g[bj][0] + b[bj][0] + acc[ai][bj][m][0], d = (cx[bj][1] - mean) * sc * g[bj][1] + b[bj][1] + acc[ai][bj][m][1];
;                 *(f32x4*)(Dst + off) = a; *(f32x4*)(Dst + off + 4) = d;
;                 if (OUTB) { u32x4 pw; pw.x = cvt_pk_bf16(a[0], a[1]); pw.y = cvt_pk_bf16(a[2], a[3]); pw.z = cvt_pk_bf16(d[0], d[1]); pw.w = cvt_pk_bf16(d[2], d[3]);
;                     *(u32x4*)(YB + off) = pw;
;                     s1 += ((a[0] + a[1]) + (a[2] + a[3])) + ((d[0] + d[1]) + (d[2] + d[3]));
;                     s2 += ((a[0] * a[0] + a[1] * a[1]) + (a[2] * a[2] + a[3] * a[3])) + ((d[0] * d[0] + d[1] * d[1]) + (d[2] * d[2] + d[3] * d[3])); } }
;             if (OUTB) { s1 += __shfl_xor(s1, 16); s2 += __shfl_xor(s2, 16); s1 += __shfl_xor(s1, 32); s2 += __shfl_xor(s2, 32);
;                 if (fq == 0) { __hip_atomic_fetch_add(st_out + 2 * row, s1, __ATOMIC_RELAXED, __HIP_MEMORY_SCOPE_AGENT); __hip_atomic_fetch_add(st_out + 2 * row + 1, s2, __ATOMIC_RELAXED, __HIP_MEMORY_SCOPE_AGENT); } } }
	v_add_f32_e32 v48, v48, v50
	s_waitcnt lgkmcnt(0)
	v_add_f32_e32 v49, v49, v51
	v_mov_b32_e32 v254, v48
	v_mov_b32_e32 v255, v49
	v_or_b32_e32 v98, 32, v128
	v_lshlrev_b32_e32 v96, 1, v98
	v_ashrrev_i32_e32 v97, 31, v96
	v_lshl_add_u64 v[48:49], v[96:97], 2, s[14:15]
	s_waitcnt vmcnt(8)
	v_pk_mul_f32 v[102:103], v[116:117], s[46:47] op_sel_hi:[1,0]
	global_load_dwordx2 v[100:101], v[48:49], off
	v_fma_f32 v48, -v102, v102, v103
	v_add_f32_e32 v48, 0x3727c5ac, v48
	v_mul_f32_e32 v49, 0x4f800000, v48
	v_cmp_gt_f32_e32 vcc, s77, v48
	v_ashrrev_i32_e32 v99, 31, v98
	s_waitcnt vmcnt(7)
	v_sub_f32_e32 v93, v93, v102
	s_waitcnt lgkmcnt(1)
	v_cndmask_b32_e32 v50, v48, v49, vcc
	s_waitcnt lgkmcnt(0)
	v_sqrt_f32_e32 v51, v50
	v_lshlrev_b64 v[48:49], 13, v[98:99]
	v_lshl_add_u64 v[48:49], s[28:29], 0, v[48:49]
	v_lshl_add_u64 v[52:53], v[176:177], 2, v[48:49]
	v_add_u32_e32 v48, -1, v51
	v_fma_f32 v49, -v48, v51, v50
	v_cmp_ge_f32_e64 s[10:11], 0, v49
	v_add_u32_e32 v49, 1, v51
	v_sub_f32_e32 v92, v92, v102
	v_cndmask_b32_e64 v48, v51, v48, s[10:11]
	v_fma_f32 v51, -v49, v51, v50
	v_cmp_lt_f32_e64 s[10:11], 0, v51
	v_sub_f32_e32 v95, v95, v102
	v_sub_f32_e32 v94, v94, v102
	v_cndmask_b32_e64 v48, v48, v49, s[10:11]
	v_mul_f32_e32 v49, 0x37800000, v48
	v_cndmask_b32_e32 v48, v48, v49, vcc
	v_cmp_class_f32_e32 vcc, v50, v215
	v_sub_f32_e32 v89, v89, v102
	v_sub_f32_e32 v88, v88, v102
	v_cndmask_b32_e32 v103, v48, v50, vcc
	global_load_dwordx4 v[56:59], v[52:53], off offset:16
	global_load_dwordx4 v[60:63], v[52:53], off
	global_load_dwordx4 v[48:51], v[52:53], off offset:528
	s_nop 0
	global_load_dwordx4 v[52:55], v[52:53], off offset:512
	v_div_scale_f32 v104, s[10:11], v103, v103, 1.0
	v_rcp_f32_e32 v105, v104
	v_sub_f32_e32 v91, v91, v102
	v_sub_f32_e32 v90, v90, v102
	v_fma_f32 v106, -v104, v105, 1.0
	v_fmac_f32_e32 v105, v106, v105
	v_div_scale_f32 v106, vcc, 1.0, v103, 1.0
	v_mul_f32_e32 v107, v106, v105
	v_fma_f32 v108, -v104, v107, v106
	v_fmac_f32_e32 v107, v108, v105
	v_fma_f32 v104, -v104, v107, v106
	v_div_fmas_f32 v104, v104, v105, v107
	v_div_fixup_f32 v103, v104, v103, 1.0
	v_mul_f32_e32 v104, 0x3fb504f3, v103
	v_lshlrev_b64 v[106:107], 11, v[114:115]
	v_pk_mul_f32 v[94:95], v[94:95], v[104:105] op_sel_hi:[1,0]
	v_pk_mul_f32 v[92:93], v[92:93], v[104:105] op_sel_hi:[1,0]
	v_pk_mul_f32 v[90:91], v[90:91], v[104:105] op_sel_hi:[1,0]
	v_pk_mul_f32 v[88:89], v[88:89], v[104:105] op_sel_hi:[1,0]
	v_lshl_add_u64 v[106:107], v[106:107], 0, v[176:177]
	v_pk_fma_f32 v[92:93], v[76:77], v[92:93], v[192:193]
	v_pk_fma_f32 v[94:95], v[78:79], v[94:95], v[190:191]
	v_pk_fma_f32 v[88:89], v[68:69], v[88:89], v[188:189]
	v_pk_fma_f32 v[90:91], v[70:71], v[90:91], v[186:187]
	v_pk_add_f32 v[46:47], v[46:47], v[94:95]
	v_pk_add_f32 v[44:45], v[44:45], v[92:93]
	v_pk_add_f32 v[42:43], v[42:43], v[90:91]
	v_pk_add_f32 v[40:41], v[40:41], v[88:89]
	v_lshlrev_b64 v[94:95], 1, v[106:107]
	v_lshl_add_u64 v[92:93], v[106:107], 2, s[18:19]
	v_cvt_pk_bf16_f32 v88, v44, v45
	v_cvt_pk_bf16_f32 v89, v46, v47
	v_cvt_pk_bf16_f32 v90, v40, v41
	v_cvt_pk_bf16_f32 v91, v42, v43
	v_lshl_add_u64 v[106:107], s[24:25], 0, v[94:95]
	global_store_dwordx4 v[92:93], v[44:47], off
	global_store_dwordx4 v[92:93], v[40:43], off offset:16
	global_store_dwordx4 v[106:107], v[88:91], off
	v_or_b32_e32 v94, 0x100, v94
	s_nop 0
	v_add_f32_e32 v88, v44, v45
	v_add_f32_e32 v89, v46, v47
	v_add_f32_e32 v88, v88, v89
	v_add_f32_e32 v89, v40, v41
	v_mul_f32_e32 v45, v45, v45
	v_mul_f32_e32 v41, v41, v41
	v_fmac_f32_e32 v45, v44, v44
	v_mul_f32_e32 v44, v47, v47
	v_fmac_f32_e32 v41, v40, v40
	v_mul_f32_e32 v40, v43, v43
	v_fmac_f32_e32 v44, v46, v46
	v_fmac_f32_e32 v40, v42, v42
	v_add_f32_e32 v44, v45, v44
	v_add_f32_e32 v40, v41, v40
	v_add_f32_e32 v90, v42, v43
	v_add_f32_e32 v44, v44, v40
	s_waitcnt vmcnt(12)
	v_sub_f32_e32 v41, v85, v102
	v_sub_f32_e32 v40, v84, v102
	v_sub_f32_e32 v43, v87, v102
	v_sub_f32_e32 v42, v86, v102
	v_pk_mul_f32 v[42:43], v[42:43], v[104:105] op_sel_hi:[1,0]
	v_pk_mul_f32 v[40:41], v[40:41], v[104:105] op_sel_hi:[1,0]
	v_pk_fma_f32 v[42:43], v[74:75], v[42:43], v[182:183]
	v_pk_fma_f32 v[40:41], v[72:73], v[40:41], v[184:185]
	v_pk_add_f32 v[38:39], v[38:39], v[42:43]
	v_pk_add_f32 v[36:37], v[36:37], v[40:41]
	v_sub_f32_e32 v41, v81, v102
	v_sub_f32_e32 v40, v80, v102
	v_sub_f32_e32 v43, v83, v102
	v_sub_f32_e32 v42, v82, v102
	v_pk_mul_f32 v[42:43], v[42:43], v[104:105] op_sel_hi:[1,0]
	v_pk_mul_f32 v[40:41], v[40:41], v[104:105] op_sel_hi:[1,0]
	v_pk_fma_f32 v[42:43], v[66:67], v[42:43], v[178:179]
	v_pk_fma_f32 v[40:41], v[64:65], v[40:41], v[180:181]
	v_pk_add_f32 v[42:43], v[34:35], v[42:43]
	v_pk_add_f32 v[40:41], v[32:33], v[40:41]
	v_add_f32_e32 v32, v36, v37
	v_add_f32_e32 v33, v38, v39
	v_add_f32_e32 v32, v32, v33
	v_add_f32_e32 v33, v40, v41
	v_add_f32_e32 v34, v42, v43
	v_add_f32_e32 v33, v33, v34
	v_add_f32_e32 v32, v32, v33
	v_mul_f32_e32 v33, v37, v37
	v_mul_f32_e32 v34, v39, v39
	v_fmac_f32_e32 v33, v36, v36
	v_fmac_f32_e32 v34, v38, v38
	v_add_f32_e32 v33, v33, v34
	v_mul_f32_e32 v34, v41, v41
	v_mul_f32_e32 v35, v43, v43
	v_add_f32_e32 v89, v89, v90
	v_fmac_f32_e32 v34, v40, v40
	v_fmac_f32_e32 v35, v42, v42
	v_add_f32_e32 v88, v88, v89
	v_add_f32_e32 v34, v34, v35
	v_add_f32_e32 v88, 0, v88
	v_add_f32_e32 v33, v33, v34
	v_add_f32_e32 v32, v32, v88
	v_add_f32_e32 v33, v44, v33
	ds_bpermute_b32 v34, v216, v32
	ds_bpermute_b32 v35, v216, v33
	global_store_dwordx4 v[92:93], v[36:39], off offset:512
	global_store_dwordx4 v[92:93], v[40:43], off offset:528
	s_waitcnt lgkmcnt(1)
	v_add_f32_e32 v32, v32, v34
	s_waitcnt lgkmcnt(0)
;     __device__ __forceinline__ void operator()(const f32x4 (&acc)[2][2][4][2], const Unit& u, int wr, int wc, int fr, int fq) const {
;     ...
;         for (int r = 0; r < 8; ++r) { const int ai = r >> 2, m = r & 3; const int row = row0 + ai * HALF + m * 16;
;             f32x4 cx[2][2]; const f32x2v cst = nst;
; #pragma unroll
;             for (int bj = 0; bj < 2; ++bj) { cx[bj][0] = nx[bj][0]; cx[bj][1] = nx[bj][1]; }
;             if (r + 1 < 8) { const int rown = row0 + ((r + 1) >> 2) * HALF + ((r + 1) & 3) * 16; nst = *(const f32x2v*)(st_in + 2 * rown);
; #pragma unroll
;                 for (int bj = 0; bj < 2; ++bj) { const size_t off = (size_t)rown * ldc + col0 + bj * HALF; nx[bj][0] = *(const f32x4*)(Src + off); nx[bj][1] = *(const f32x4*)(Src + off + 4); } }
;             const float mean = cst.x * (1.0f / 2048.0f); const float rstd = 1.0f / sqrtf(cst.y * (1.0f / 2048.0f) - mean * mean + 1e-5f);
;             const float sc = rstd * alpha; float s1 = 0.f, s2 = 0.f;
; #pragma unroll
;             for (int bj = 0; bj < 2; ++bj) { const size_t off = (size_t)row * ldc + col0 + bj * HALF;
;                 const f32x4 a = (cx[bj][0] - mean) * sc * g[bj][0] + b[bj][0] + acc[ai][bj][m][0], d = (cx[bj][1] - mean) * sc * g[bj][1] + b[bj][1] + acc[ai][bj][m][1];
;                 *(f32x4*)(Dst + off) = a; *(f32x4*)(Dst + off + 4) = d;
;                 if (OUTB) { u32x4 pw; pw.x = cvt_pk_bf16(a[0], a[1]); pw.y = cvt_pk_bf16(a[2], a[3]); pw.z = cvt_pk_bf16(d[0], d[1]); pw.w = cvt_pk_bf16(d[2], d[3]);
;                     *(u32x4*)(YB + off) = pw;
;                     s1 += ((a[0] + a[1]) + (a[2] + a[3])) + ((d[0] + d[1]) + (d[2] + d[3]));
;                     s2 += ((a[0] * a[0] + a[1] * a[1]) + (a[2] * a[2] + a[3] * a[3])) + ((d[0] * d[0] + d[1] * d[1]) + (d[2] * d[2] + d[3] * d[3])); } }
;             if (OUTB) { s1 += __shfl_xor(s1, 16); s2 += __shfl_xor(s2, 16); s1 += __shfl_xor(s1, 32); s2 += __shfl_xor(s2, 32);
;                 if (fq == 0) { __hip_atomic_fetch_add(st_out + 2 * row, s1, __ATOMIC_RELAXED, __HIP_MEMORY_SCOPE_AGENT); __hip_atomic_fetch_add(st_out + 2 * row + 1, s2, __ATOMIC_RELAXED, __HIP_MEMORY_SCOPE_AGENT); } } }
	v_add_f32_e32 v33, v33, v35
	ds_bpermute_b32 v34, v195, v32
	ds_bpermute_b32 v35, v195, v33
	v_cvt_pk_bf16_f32 v36, v36, v37
	v_cvt_pk_bf16_f32 v37, v38, v39
	v_cvt_pk_bf16_f32 v38, v40, v41
	v_cvt_pk_bf16_f32 v39, v42, v43
	v_lshl_add_u64 v[40:41], s[24:25], 0, v[94:95]
	global_store_dwordx4 v[40:41], v[36:39], off
	s_waitcnt lgkmcnt(1)
	v_add_f32_e32 v32, v32, v34
	s_waitcnt lgkmcnt(0)
	v_add_f32_e32 v33, v33, v35
	s_mov_b32 s90, 0xffff0000
	s_mov_b32 s91, 0
	v_cndmask_b32_e64 v254, v254, v32, s[90:91]
	v_cndmask_b32_e64 v255, v255, v33, s[90:91]
	v_or_b32_e32 v82, 48, v128
	v_lshlrev_b32_e32 v80, 1, v82
	v_ashrrev_i32_e32 v81, 31, v80
	v_lshl_add_u64 v[32:33], v[80:81], 2, s[14:15]
	s_waitcnt vmcnt(8)
	v_pk_mul_f32 v[86:87], v[100:101], s[46:47] op_sel_hi:[1,0]
	global_load_dwordx2 v[84:85], v[32:33], off
	v_fma_f32 v32, -v86, v86, v87
	v_add_f32_e32 v32, 0x3727c5ac, v32
	v_mul_f32_e32 v33, 0x4f800000, v32
	v_cmp_gt_f32_e32 vcc, s77, v32
	v_ashrrev_i32_e32 v83, 31, v82
	s_waitcnt vmcnt(7)
	v_sub_f32_e32 v61, v61, v86
	s_waitcnt lgkmcnt(1)
	v_cndmask_b32_e32 v34, v32, v33, vcc
	s_waitcnt lgkmcnt(0)
	v_sqrt_f32_e32 v35, v34
	v_lshlrev_b64 v[32:33], 13, v[82:83]
	v_lshl_add_u64 v[32:33], s[28:29], 0, v[32:33]
	v_lshl_add_u64 v[36:37], v[176:177], 2, v[32:33]
	v_add_u32_e32 v32, -1, v35
	v_fma_f32 v33, -v32, v35, v34
	v_cmp_ge_f32_e64 s[10:11], 0, v33
	v_add_u32_e32 v33, 1, v35
	v_sub_f32_e32 v60, v60, v86
	v_cndmask_b32_e64 v32, v35, v32, s[10:11]
	v_fma_f32 v35, -v33, v35, v34
	v_cmp_lt_f32_e64 s[10:11], 0, v35
	v_sub_f32_e32 v63, v63, v86
	v_sub_f32_e32 v62, v62, v86
	v_cndmask_b32_e64 v32, v32, v33, s[10:11]
	v_mul_f32_e32 v33, 0x37800000, v32
	v_cndmask_b32_e32 v32, v32, v33, vcc
	v_cmp_class_f32_e32 vcc, v34, v215
	v_sub_f32_e32 v57, v57, v86
	v_sub_f32_e32 v56, v56, v86
	v_cndmask_b32_e32 v87, v32, v34, vcc
	global_load_dwordx4 v[40:43], v[36:37], off offset:16
	global_load_dwordx4 v[44:47], v[36:37], off
	global_load_dwordx4 v[32:35], v[36:37], off offset:528
	s_nop 0
	global_load_dwordx4 v[36:39], v[36:37], off offset:512
	v_div_scale_f32 v88, s[10:11], v87, v87, 1.0
	v_rcp_f32_e32 v89, v88
	v_sub_f32_e32 v59, v59, v86
	v_sub_f32_e32 v58, v58, v86
	v_fma_f32 v90, -v88, v89, 1.0
	v_fmac_f32_e32 v89, v90, v89
	v_div_scale_f32 v90, vcc, 1.0, v87, 1.0
	v_mul_f32_e32 v91, v90, v89
	v_fma_f32 v92, -v88, v91, v90
	v_fmac_f32_e32 v91, v92, v89
	v_fma_f32 v88, -v88, v91, v90
	v_div_fmas_f32 v88, v88, v89, v91
	v_div_fixup_f32 v87, v88, v87, 1.0
	v_mul_f32_e32 v88, 0x3fb504f3, v87
	v_lshlrev_b64 v[90:91], 11, v[98:99]
	v_pk_mul_f32 v[62:63], v[62:63], v[88:89] op_sel_hi:[1,0]
	v_pk_mul_f32 v[60:61], v[60:61], v[88:89] op_sel_hi:[1,0]
	v_pk_mul_f32 v[58:59], v[58:59], v[88:89] op_sel_hi:[1,0]
	v_pk_mul_f32 v[56:57], v[56:57], v[88:89] op_sel_hi:[1,0]
	v_lshl_add_u64 v[90:91], v[90:91], 0, v[176:177]
	v_pk_fma_f32 v[60:61], v[76:77], v[60:61], v[192:193]
	v_pk_fma_f32 v[62:63], v[78:79], v[62:63], v[190:191]
	v_pk_fma_f32 v[56:57], v[68:69], v[56:57], v[188:189]
	v_pk_fma_f32 v[58:59], v[70:71], v[58:59], v[186:187]
	v_pk_add_f32 v[30:31], v[30:31], v[62:63]
	v_pk_add_f32 v[28:29], v[28:29], v[60:61]
	v_pk_add_f32 v[26:27], v[26:27], v[58:59]
	v_pk_add_f32 v[24:25], v[24:25], v[56:57]
	v_lshlrev_b64 v[62:63], 1, v[90:91]
	v_lshl_add_u64 v[60:61], v[90:91], 2, s[18:19]
	v_cvt_pk_bf16_f32 v56, v28, v29
	v_cvt_pk_bf16_f32 v57, v30, v31
	v_cvt_pk_bf16_f32 v58, v24, v25
	v_cvt_pk_bf16_f32 v59, v26, v27
	v_lshl_add_u64 v[90:91], s[24:25], 0, v[62:63]
	global_store_dwordx4 v[60:61], v[28:31], off
	global_store_dwordx4 v[60:61], v[24:27], off offset:16
	global_store_dwordx4 v[90:91], v[56:59], off
	v_or_b32_e32 v62, 0x100, v62
	s_nop 0
	v_add_f32_e32 v56, v28, v29
	v_add_f32_e32 v57, v30, v31
	v_add_f32_e32 v56, v56, v57
	v_add_f32_e32 v57, v24, v25
	v_mul_f32_e32 v29, v29, v29
	v_mul_f32_e32 v25, v25, v25
	v_fmac_f32_e32 v29, v28, v28
	v_mul_f32_e32 v28, v31, v31
	v_fmac_f32_e32 v25, v24, v24
	v_mul_f32_e32 v24, v27, v27
	v_fmac_f32_e32 v28, v30, v30
	v_fmac_f32_e32 v24, v26, v26
	v_add_f32_e32 v28, v29, v28
	v_add_f32_e32 v24, v25, v24
	v_add_f32_e32 v58, v26, v27
	v_add_f32_e32 v28, v28, v24
	s_waitcnt vmcnt(12)
	v_sub_f32_e32 v25, v53, v86
	v_sub_f32_e32 v24, v52, v86
	v_sub_f32_e32 v27, v55, v86
	v_sub_f32_e32 v26, v54, v86
	v_pk_mul_f32 v[26:27], v[26:27], v[88:89] op_sel_hi:[1,0]
	v_pk_mul_f32 v[24:25], v[24:25], v[88:89] op_sel_hi:[1,0]
	v_pk_fma_f32 v[26:27], v[74:75], v[26:27], v[182:183]
	v_pk_fma_f32 v[24:25], v[72:73], v[24:25], v[184:185]
	v_pk_add_f32 v[22:23], v[22:23], v[26:27]
	v_pk_add_f32 v[20:21], v[20:21], v[24:25]
	v_sub_f32_e32 v25, v49, v86
	v_sub_f32_e32 v24, v48, v86
	v_sub_f32_e32 v27, v51, v86
	v_sub_f32_e32 v26, v50, v86
	v_pk_mul_f32 v[26:27], v[26:27], v[88:89] op_sel_hi:[1,0]
	v_pk_mul_f32 v[24:25], v[24:25], v[88:89] op_sel_hi:[1,0]
	v_pk_fma_f32 v[26:27], v[66:67], v[26:27], v[178:179]
	v_pk_fma_f32 v[24:25], v[64:65], v[24:25], v[180:181]
	v_pk_add_f32 v[26:27], v[18:19], v[26:27]
	v_pk_add_f32 v[24:25], v[16:17], v[24:25]
	v_add_f32_e32 v16, v20, v21
	v_add_f32_e32 v17, v22, v23
	v_add_f32_e32 v16, v16, v17
	v_add_f32_e32 v17, v24, v25
	v_add_f32_e32 v18, v26, v27
	v_add_f32_e32 v17, v17, v18
	v_add_f32_e32 v16, v16, v17
	v_mul_f32_e32 v17, v21, v21
	v_mul_f32_e32 v18, v23, v23
	v_fmac_f32_e32 v17, v20, v20
	v_fmac_f32_e32 v18, v22, v22
	v_add_f32_e32 v17, v17, v18
	v_mul_f32_e32 v18, v25, v25
	v_mul_f32_e32 v19, v27, v27
	v_add_f32_e32 v57, v57, v58
	v_fmac_f32_e32 v18, v24, v24
	v_fmac_f32_e32 v19, v26, v26
	v_add_f32_e32 v56, v56, v57
	v_add_f32_e32 v18, v18, v19
	v_add_f32_e32 v56, 0, v56
	v_add_f32_e32 v17, v17, v18
	v_add_f32_e32 v16, v16, v56
	v_add_f32_e32 v17, v28, v17
	ds_bpermute_b32 v18, v216, v16
	ds_bpermute_b32 v19, v216, v17
	global_store_dwordx4 v[60:61], v[20:23], off offset:512
	global_store_dwordx4 v[60:61], v[24:27], off offset:528
	s_waitcnt lgkmcnt(1)
;     __device__ __forceinline__ void operator()(const f32x4 (&acc)[2][2][4][2], const Unit& u, int wr, int wc, int fr, int fq) const {
;     ...
;         for (int r = 0; r < 8; ++r) { const int ai = r >> 2, m = r & 3; const int row = row0 + ai * HALF + m * 16;
;             f32x4 cx[2][2]; const f32x2v cst = nst;
; #pragma unroll
;             for (int bj = 0; bj < 2; ++bj) { cx[bj][0] = nx[bj][0]; cx[bj][1] = nx[bj][1]; }
;             if (r + 1 < 8) { const int rown = row0 + ((r + 1) >> 2) * HALF + ((r + 1) & 3) * 16; nst = *(const f32x2v*)(st_in + 2 * rown);
; #pragma unroll
;                 for (int bj = 0; bj < 2; ++bj) { const size_t off = (size_t)rown * ldc + col0 + bj * HALF; nx[bj][0] = *(const f32x4*)(Src + off); nx[bj][1] = *(const f32x4*)(Src + off + 4); } }
;             const float mean = cst.x * (1.0f / 2048.0f); const float rstd = 1.0f / sqrtf(cst.y * (1.0f / 2048.0f) - mean * mean + 1e-5f);
;             const float sc = rstd * alpha; float s1 = 0.f, s2 = 0.f;
; #pragma unroll
;             for (int bj = 0; bj < 2; ++bj) { const size_t off = (size_t)row * ldc + col0 + bj * HALF;
;                 const f32x4 a = (cx[bj][0] - mean) * sc * g[bj][0] + b[bj][0] + acc[ai][bj][m][0], d = (cx[bj][1] - mean) * sc * g[bj][1] + b[bj][1] + acc[ai][bj][m][1];
;                 *(f32x4*)(Dst + off) = a; *(f32x4*)(Dst + off + 4) = d;
;                 if (OUTB) { u32x4 pw; pw.x = cvt_pk_bf16(a[0], a[1]); pw.y = cvt_pk_bf16(a[2], a[3]); pw.z = cvt_pk_bf16(d[0], d[1]); pw.w = cvt_pk_bf16(d[2], d[3]);
;                     *(u32x4*)(YB + off) = pw;
;                     s1 += ((a[0] + a[1]) + (a[2] + a[3])) + ((d[0] + d[1]) + (d[2] + d[3]));
;                     s2 += ((a[0] * a[0] + a[1] * a[1]) + (a[2] * a[2] + a[3] * a[3])) + ((d[0] * d[0] + d[1] * d[1]) + (d[2] * d[2] + d[3] * d[3])); } }
;             if (OUTB) { s1 += __shfl_xor(s1, 16); s2 += __shfl_xor(s2, 16); s1 += __shfl_xor(s1, 32); s2 += __shfl_xor(s2, 32);
;                 if (fq == 0) { __hip_atomic_fetch_add(st_out + 2 * row, s1, __ATOMIC_RELAXED, __HIP_MEMORY_SCOPE_AGENT); __hip_atomic_fetch_add(st_out + 2 * row + 1, s2, __ATOMIC_RELAXED, __HIP_MEMORY_SCOPE_AGENT); } } }
	v_add_f32_e32 v16, v16, v18
	s_waitcnt lgkmcnt(0)
	v_add_f32_e32 v17, v17, v19
	ds_bpermute_b32 v18, v195, v16
	ds_bpermute_b32 v19, v195, v17
	v_cvt_pk_bf16_f32 v20, v20, v21
	v_cvt_pk_bf16_f32 v21, v22, v23
	v_cvt_pk_bf16_f32 v22, v24, v25
	v_cvt_pk_bf16_f32 v23, v26, v27
	v_lshl_add_u64 v[24:25], s[24:25], 0, v[62:63]
	global_store_dwordx4 v[24:25], v[20:23], off
	s_waitcnt lgkmcnt(1)
	v_add_f32_e32 v16, v16, v18
	s_waitcnt lgkmcnt(0)
	v_add_f32_e32 v17, v17, v19
	s_mov_b32 s90, 0
	s_mov_b32 s91, 0xffff
	v_cndmask_b32_e64 v254, v254, v16, s[90:91]
	v_cndmask_b32_e64 v255, v255, v17, s[90:91]
	s_waitcnt vmcnt(8)
	v_pk_mul_f32 v[20:21], v[84:85], s[46:47] op_sel_hi:[1,0]
	s_nop 0
	v_fma_f32 v16, -v20, v20, v21
	v_add_f32_e32 v16, 0x3727c5ac, v16
	v_mul_f32_e32 v17, 0x4f800000, v16
	v_cmp_gt_f32_e32 vcc, s77, v16
	s_nop 1
	v_cndmask_b32_e32 v16, v16, v17, vcc
	v_sqrt_f32_e32 v17, v16
	s_waitcnt lgkmcnt(1)
	v_add_u32_e32 v18, -1, v17
	v_fma_f32 v21, -v18, v17, v16
	s_waitcnt lgkmcnt(0)
	v_add_u32_e32 v19, 1, v17
	v_cmp_ge_f32_e64 s[10:11], 0, v21
	s_nop 1
	v_cndmask_b32_e64 v18, v17, v18, s[10:11]
	v_fma_f32 v17, -v19, v17, v16
	v_cmp_lt_f32_e64 s[10:11], 0, v17
	s_nop 1
	v_cndmask_b32_e64 v17, v18, v19, s[10:11]
	v_mul_f32_e32 v18, 0x37800000, v17
	v_cndmask_b32_e32 v17, v17, v18, vcc
	v_cmp_class_f32_e32 vcc, v16, v215
	s_nop 1
	v_cndmask_b32_e32 v16, v17, v16, vcc
	v_div_scale_f32 v17, s[10:11], v16, v16, 1.0
	v_rcp_f32_e32 v18, v17
	s_nop 0
	v_fma_f32 v19, -v17, v18, 1.0
	v_fmac_f32_e32 v18, v19, v18
	v_div_scale_f32 v19, vcc, 1.0, v16, 1.0
	v_mul_f32_e32 v21, v19, v18
	v_fma_f32 v22, -v17, v21, v19
	v_fmac_f32_e32 v21, v22, v18
	v_fma_f32 v17, -v17, v21, v19
	v_div_fmas_f32 v17, v17, v18, v21
	v_div_fixup_f32 v16, v17, v16, 1.0
	v_mul_f32_e32 v22, 0x3fb504f3, v16
	v_lshlrev_b64 v[16:17], 11, v[82:83]
	v_lshl_add_u64 v[24:25], v[16:17], 0, v[176:177]
	s_waitcnt vmcnt(6)
	v_sub_f32_e32 v17, v45, v20
	v_sub_f32_e32 v16, v44, v20
	v_sub_f32_e32 v19, v47, v20
	v_sub_f32_e32 v18, v46, v20
	v_pk_mul_f32 v[18:19], v[18:19], v[22:23] op_sel_hi:[1,0]
	v_pk_mul_f32 v[16:17], v[16:17], v[22:23] op_sel_hi:[1,0]
	v_pk_fma_f32 v[18:19], v[78:79], v[18:19], v[190:191]
	v_pk_fma_f32 v[16:17], v[76:77], v[16:17], v[192:193]
	v_pk_add_f32 v[14:15], v[14:15], v[18:19]
	v_pk_add_f32 v[12:13], v[12:13], v[16:17]
	v_sub_f32_e32 v17, v41, v20
	v_sub_f32_e32 v16, v40, v20
	v_sub_f32_e32 v19, v43, v20
	v_sub_f32_e32 v18, v42, v20
	v_pk_mul_f32 v[18:19], v[18:19], v[22:23] op_sel_hi:[1,0]
	v_pk_mul_f32 v[16:17], v[16:17], v[22:23] op_sel_hi:[1,0]
	v_pk_fma_f32 v[18:19], v[70:71], v[18:19], v[186:187]
	v_pk_fma_f32 v[16:17], v[68:69], v[16:17], v[188:189]
	v_pk_add_f32 v[10:11], v[10:11], v[18:19]
	v_pk_add_f32 v[8:9], v[8:9], v[16:17]
	v_lshl_add_u64 v[26:27], v[24:25], 2, s[18:19]
	v_lshlrev_b64 v[24:25], 1, v[24:25]
	v_cvt_pk_bf16_f32 v16, v12, v13
	v_cvt_pk_bf16_f32 v17, v14, v15
	v_cvt_pk_bf16_f32 v18, v8, v9
	v_cvt_pk_bf16_f32 v19, v10, v11
	v_lshl_add_u64 v[28:29], s[24:25], 0, v[24:25]
	global_store_dwordx4 v[26:27], v[12:15], off
	global_store_dwordx4 v[26:27], v[8:11], off offset:16
	global_store_dwordx4 v[28:29], v[16:19], off
	v_or_b32_e32 v24, 0x100, v24
	s_nop 0
	v_add_f32_e32 v16, v12, v13
	v_add_f32_e32 v17, v14, v15
	v_add_f32_e32 v16, v16, v17
	v_add_f32_e32 v17, v8, v9
	v_mul_f32_e32 v13, v13, v13
	v_mul_f32_e32 v9, v9, v9
	v_fmac_f32_e32 v13, v12, v12
	v_mul_f32_e32 v12, v15, v15
	v_fmac_f32_e32 v9, v8, v8
	v_mul_f32_e32 v8, v11, v11
	v_fmac_f32_e32 v12, v14, v14
	v_fmac_f32_e32 v8, v10, v10
	v_add_f32_e32 v12, v13, v12
	v_add_f32_e32 v8, v9, v8
	v_add_f32_e32 v18, v10, v11
	v_add_f32_e32 v12, v12, v8
	s_waitcnt vmcnt(7)
	v_sub_f32_e32 v9, v37, v20
	v_sub_f32_e32 v8, v36, v20
	v_sub_f32_e32 v11, v39, v20
	v_sub_f32_e32 v10, v38, v20
	v_pk_mul_f32 v[10:11], v[10:11], v[22:23] op_sel_hi:[1,0]
	v_pk_mul_f32 v[8:9], v[8:9], v[22:23] op_sel_hi:[1,0]
	v_pk_fma_f32 v[10:11], v[74:75], v[10:11], v[182:183]
	v_pk_fma_f32 v[8:9], v[72:73], v[8:9], v[184:185]
	v_pk_add_f32 v[6:7], v[6:7], v[10:11]
	v_pk_add_f32 v[4:5], v[4:5], v[8:9]
	v_sub_f32_e32 v9, v33, v20
	v_sub_f32_e32 v8, v32, v20
	v_sub_f32_e32 v11, v35, v20
	v_sub_f32_e32 v10, v34, v20
	v_pk_mul_f32 v[10:11], v[10:11], v[22:23] op_sel_hi:[1,0]
	v_pk_mul_f32 v[8:9], v[8:9], v[22:23] op_sel_hi:[1,0]
	v_pk_fma_f32 v[10:11], v[66:67], v[10:11], v[178:179]
	v_pk_fma_f32 v[8:9], v[64:65], v[8:9], v[180:181]
	v_pk_add_f32 v[10:11], v[2:3], v[10:11]
	v_pk_add_f32 v[8:9], v[0:1], v[8:9]
	v_add_f32_e32 v0, v4, v5
	v_add_f32_e32 v1, v6, v7
	v_add_f32_e32 v0, v0, v1
	v_add_f32_e32 v1, v8, v9
	v_add_f32_e32 v2, v10, v11
	v_add_f32_e32 v1, v1, v2
	v_add_f32_e32 v0, v0, v1
	v_mul_f32_e32 v1, v5, v5
	v_mul_f32_e32 v2, v7, v7
	v_fmac_f32_e32 v1, v4, v4
	v_fmac_f32_e32 v2, v6, v6
	v_add_f32_e32 v1, v1, v2
	v_mul_f32_e32 v2, v9, v9
	v_mul_f32_e32 v3, v11, v11
	v_add_f32_e32 v17, v17, v18
	v_fmac_f32_e32 v2, v8, v8
	v_fmac_f32_e32 v3, v10, v10
	v_add_f32_e32 v16, v16, v17
	v_add_f32_e32 v2, v2, v3
	v_add_f32_e32 v16, 0, v16
	v_add_f32_e32 v1, v1, v2
	v_add_f32_e32 v0, v0, v16
	v_add_f32_e32 v1, v12, v1
	ds_bpermute_b32 v2, v216, v0
	ds_bpermute_b32 v3, v216, v1
	global_store_dwordx4 v[26:27], v[4:7], off offset:512
	global_store_dwordx4 v[26:27], v[8:11], off offset:528
	s_waitcnt lgkmcnt(1)
	v_add_f32_e32 v0, v0, v2
	s_waitcnt lgkmcnt(0)
	v_add_f32_e32 v1, v1, v3
	ds_bpermute_b32 v2, v195, v0
	ds_bpermute_b32 v3, v195, v1
	v_cvt_pk_bf16_f32 v4, v4, v5
	v_cvt_pk_bf16_f32 v5, v6, v7
	v_cvt_pk_bf16_f32 v6, v8, v9
	v_cvt_pk_bf16_f32 v7, v10, v11
	v_lshl_add_u64 v[8:9], s[24:25], 0, v[24:25]
	global_store_dwordx4 v[8:9], v[4:7], off
	s_waitcnt lgkmcnt(1)
	v_add_f32_e32 v0, v0, v2
	s_waitcnt lgkmcnt(0)
	v_add_f32_e32 v1, v1, v3
	s_mov_b32 s90, 0
	s_mov_b32 s91, 0xffff0000
	v_cndmask_b32_e64 v254, v254, v0, s[90:91]
	v_cndmask_b32_e64 v255, v255, v1, s[90:91]
	v_lshrrev_b32_e32 v2, 4, v240
	v_lshlrev_b32_e32 v2, 7, v2
	v_add_co_u32_e32 v250, vcc, v250, v2
	s_nop 1
	v_addc_co_u32_e32 v251, vcc, 0, v251, vcc
	global_atomic_add_f32 v[250:251], v252, off
	global_atomic_add_f32 v[250:251], v253, off offset:4
	global_atomic_add_f32 v[250:251], v254, off offset:1024
	global_atomic_add_f32 v[250:251], v255, off offset:1028
	s_andn2_b64 vcc, exec, s[6:7]
	s_mov_b64 s[6:7], -1
	s_cbranch_vccnz .LBB0_325
	s_andn2_b64 vcc, exec, s[36:37]
	s_cbranch_vccnz .LBB0_324
	s_barrier
	s_branch .LBB0_324

;     __device__ __forceinline__ void operator()(const f32x4 (&acc)[2][2][4][2], const Unit& u, int wr, int wc, int fr, int fq) const {
;     ...
;         const int row0 = u.pm * BM + wr * 64 + fr; const int col0 = u.pn * BM + wc * 32 + 8 * fq;
;         f32x4 g[2][2], b[2][2];
; #pragma unroll
;         for (int bj = 0; bj < 2; ++bj)
; #pragma unroll
;             for (int n = 0; n < 2; ++n) { g[bj][n] = *(const f32x4*)(gam + col0 + bj * HALF + 4 * n); b[bj][n] = *(const f32x4*)(bet + col0 + bj * HALF + 4 * n) * alpha; }
;         f32x4 nx[2][2]; f32x2v nst;
;         { const int row = row0; nst = *(const f32x2v*)(st_in + 2 * row);
; #pragma unroll
;           for (int bj = 0; bj < 2; ++bj) { const size_t off = (size_t)row * ldc + col0 + bj * HALF; nx[bj][0] = *(const f32x4*)(Src + off); nx[bj][1] = *(const f32x4*)(Src + off + 4); } }
; #pragma unroll
;         for (int r = 0; r < 8; ++r) { const int ai = r >> 2, m = r & 3; const int row = row0 + ai * HALF + m * 16;
;             f32x4 cx[2][2]; const f32x2v cst = nst;
; #pragma unroll
;             for (int bj = 0; bj < 2; ++bj) { cx[bj][0] = nx[bj][0]; cx[bj][1] = nx[bj][1]; }
;             if (r + 1 < 8) { const int rown = row0 + ((r + 1) >> 2) * HALF + ((r + 1) & 3) * 16; nst = *(const f32x2v*)(st_in + 2 * rown);
; #pragma unroll
;                 for (int bj = 0; bj < 2; ++bj) { const size_t off = (size_t)rown * ldc + col0 + bj * HALF; nx[bj][0] = *(const f32x4*)(Src + off); nx[bj][1] = *(const f32x4*)(Src + off + 4); } }
;             const float mean = cst.x * (1.0f / 2048.0f); const float rstd = 1.0f / sqrtf(cst.y * (1.0f / 2048.0f) - mean * mean + 1e-5f);
;             const float sc = rstd * alpha; float s1 = 0.f, s2 = 0.f;
; #pragma unroll
;             for (int bj = 0; bj < 2; ++bj) { const size_t off = (size_t)row * ldc + col0 + bj * HALF;
;                 const f32x4 a = (cx[bj][0] - mean) * sc * g[bj][0] + b[bj][0] + acc[ai][bj][m][0], d = (cx[bj][1] - mean) * sc * g[bj][1] + b[bj][1] + acc[ai][bj][m][1];
.LBB0_512:
	v_lshl_or_b32 v176, s56, 8, v212
	v_ashrrev_i32_e32 v177, 31, v176
	v_lshl_add_u32 v194, s10, 8, v210
	v_lshlrev_b64 v[144:145], 2, v[176:177]
	v_lshlrev_b32_e32 v198, 1, v194
	v_lshl_add_u64 v[64:65], s[30:31], 0, v[144:145]
	v_ashrrev_i32_e32 v199, 31, v198
	global_load_dwordx4 v[178:181], v[64:65], off offset:16
	global_load_dwordx4 v[182:185], v[64:65], off
	global_load_dwordx4 v[220:223], v[64:65], off offset:528
	global_load_dwordx4 v[224:227], v[64:65], off offset:512
	v_lshl_add_u64 v[64:65], v[198:199], 2, s[36:37]
	global_load_dwordx2 v[208:209], v[64:65], off
	v_ashrrev_i32_e32 v195, 31, v194
	v_lshlrev_b64 v[64:65], 13, v[194:195]
	v_lshl_add_u64 v[64:65], s[18:19], 0, v[64:65]
	v_lshl_add_u64 v[206:207], v[64:65], 0, v[144:145]
	global_load_dwordx4 v[228:231], v[206:207], off
	global_load_dwordx4 v[232:235], v[206:207], off offset:16
	v_lshl_add_u64 v[72:73], s[28:29], 0, v[144:145]
	global_load_dwordx4 v[68:71], v[72:73], off offset:16
	global_load_dwordx4 v[76:79], v[72:73], off
	v_and_b32_e32 v65, 64, v216
	v_xor_b32_e32 v64, 16, v216
	v_add_u32_e32 v65, 64, v65
	v_xor_b32_e32 v66, 32, v216
	v_or_b32_e32 v204, 16, v194
	v_cmp_lt_i32_e32 vcc, v64, v65
	v_lshlrev_b32_e32 v196, 1, v204
	v_ashrrev_i32_e32 v197, 31, v196
	v_cndmask_b32_e32 v67, v216, v64, vcc
	v_cmp_lt_i32_e32 vcc, v66, v65
	v_lshlrev_b64 v[64:65], 11, v[194:195]
	v_lshlrev_b32_e32 v218, 2, v67
	v_cndmask_b32_e32 v66, v216, v66, vcc
	v_lshlrev_b32_e32 v195, 2, v66
	v_lshl_add_u64 v[248:249], v[64:65], 0, v[176:177]
	global_load_dwordx4 v[64:67], v[72:73], off offset:528
	s_nop 0
	global_load_dwordx4 v[72:75], v[72:73], off offset:512
	v_lshl_add_u64 v[148:149], v[196:197], 2, s[36:37]
	global_load_dwordx4 v[236:239], v[206:207], off offset:528
	global_load_dwordx4 v[244:247], v[206:207], off offset:512
	global_load_dwordx2 v[202:203], v[148:149], off
	v_ashrrev_i32_e32 v205, 31, v204
	v_lshlrev_b64 v[146:147], 13, v[204:205]
	v_lshl_add_u64 v[146:147], s[18:19], 0, v[146:147]
	v_lshl_add_u64 v[200:201], v[146:147], 0, v[144:145]
	global_load_dwordx4 v[152:155], v[200:201], off offset:16
	global_load_dwordx4 v[156:159], v[200:201], off
	global_load_dwordx4 v[144:147], v[200:201], off offset:528
	global_load_dwordx4 v[148:151], v[200:201], off offset:512
	s_waitcnt vmcnt(0)
	v_pk_mul_f32 v[186:187], v[180:181], s[44:45] op_sel_hi:[1,0]
	v_pk_mul_f32 v[192:193], v[182:183], s[44:45] op_sel_hi:[1,0]
	v_pk_mul_f32 v[180:181], v[220:221], s[44:45] op_sel_hi:[1,0]
	v_pk_mul_f32 v[182:183], v[226:227], s[44:45] op_sel_hi:[1,0]
	v_pk_mul_f32 v[188:189], v[178:179], s[44:45] op_sel_hi:[1,0]
	v_pk_mul_f32 v[208:209], v[208:209], s[46:47] op_sel_hi:[1,0]
	v_pk_mul_f32 v[178:179], v[222:223], s[44:45] op_sel_hi:[1,0]
	v_fma_f32 v209, -v208, v208, v209
	v_add_f32_e32 v209, 0x3727c5ac, v209
	v_mul_f32_e32 v219, 0x4f800000, v209
	v_cmp_gt_f32_e32 vcc, s77, v209
	v_sub_f32_e32 v221, v229, v208
	v_sub_f32_e32 v220, v228, v208
	v_cndmask_b32_e32 v209, v209, v219, vcc
	v_sqrt_f32_e32 v219, v209
	v_sub_f32_e32 v222, v230, v208
	v_sub_f32_e32 v223, v231, v208
	v_pk_mul_f32 v[190:191], v[184:185], s[44:45] op_sel_hi:[1,0]
	v_add_u32_e32 v226, -1, v219
	v_add_u32_e32 v228, 1, v219
	v_fma_f32 v229, -v226, v219, v209
	v_fma_f32 v230, -v228, v219, v209
	v_cmp_ge_f32_e64 s[10:11], 0, v229
	v_pk_mul_f32 v[184:185], v[224:225], s[44:45] op_sel_hi:[1,0]
	v_sub_f32_e32 v225, v233, v208
	v_cndmask_b32_e64 v219, v219, v226, s[10:11]
	v_cmp_lt_f32_e64 s[10:11], 0, v230
	v_sub_f32_e32 v224, v232, v208
	v_sub_f32_e32 v227, v235, v208
	v_cndmask_b32_e64 v219, v219, v228, s[10:11]
	v_mul_f32_e32 v226, 0x37800000, v219
	v_cndmask_b32_e32 v219, v219, v226, vcc
	v_cmp_class_f32_e32 vcc, v209, v217
	v_sub_f32_e32 v226, v234, v208
	s_nop 0
	v_cndmask_b32_e32 v209, v219, v209, vcc
	v_div_scale_f32 v219, s[10:11], v209, v209, 1.0
	v_rcp_f32_e32 v228, v219
	v_div_scale_f32 v229, vcc, 1.0, v209, 1.0
	v_fma_f32 v230, -v219, v228, 1.0
	v_fmac_f32_e32 v228, v230, v228
	v_mul_f32_e32 v230, v229, v228
	v_fma_f32 v231, -v219, v230, v229
	v_fmac_f32_e32 v230, v231, v228
	v_fma_f32 v219, -v219, v230, v229
	v_div_fmas_f32 v219, v219, v228, v230
	v_div_fixup_f32 v209, v219, v209, 1.0
	v_mul_f32_e32 v228, 0x3fb504f3, v209
	v_pk_mul_f32 v[222:223], v[222:223], v[228:229] op_sel_hi:[1,0]
	v_pk_mul_f32 v[220:221], v[220:221], v[228:229] op_sel_hi:[1,0]
	v_pk_mul_f32 v[224:225], v[224:225], v[228:229] op_sel_hi:[1,0]
	v_pk_fma_f32 v[220:221], v[76:77], v[220:221], v[192:193]
	v_pk_fma_f32 v[222:223], v[78:79], v[222:223], v[190:191]
	v_pk_mul_f32 v[226:227], v[226:227], v[228:229] op_sel_hi:[1,0]
	v_pk_fma_f32 v[224:225], v[68:69], v[224:225], v[188:189]
	v_pk_add_f32 v[142:143], v[142:143], v[222:223]
	v_pk_add_f32 v[140:141], v[140:141], v[220:221]
	v_pk_fma_f32 v[226:227], v[70:71], v[226:227], v[186:187]
	v_pk_add_f32 v[136:137], v[136:137], v[224:225]
	v_add_f32_e32 v209, v140, v141
	v_add_f32_e32 v219, v142, v143
	v_pk_add_f32 v[138:139], v[138:139], v[226:227]
	global_store_dwordx4 v[206:207], v[140:143], off
	global_store_dwordx4 v[206:207], v[136:139], off offset:16
	v_cvt_pk_bf16_f32 v220, v140, v141
	v_cvt_pk_bf16_f32 v222, v136, v137
	v_add_f32_e32 v209, v209, v219
	v_add_f32_e32 v219, v136, v137
	v_mul_f32_e32 v141, v141, v141
	v_mul_f32_e32 v137, v137, v137
	v_fmac_f32_e32 v141, v140, v140
	v_mul_f32_e32 v140, v143, v143
	v_fmac_f32_e32 v137, v136, v136
	v_mul_f32_e32 v136, v139, v139
	v_lshlrev_b64 v[224:225], 1, v[248:249]
	v_fmac_f32_e32 v140, v142, v142
	v_fmac_f32_e32 v136, v138, v138
	v_cvt_pk_bf16_f32 v221, v142, v143
	v_cvt_pk_bf16_f32 v223, v138, v139
	v_lshl_add_u64 v[226:227], s[24:25], 0, v[224:225]
;     __device__ __forceinline__ void operator()(const f32x4 (&acc)[2][2][4][2], const Unit& u, int wr, int wc, int fr, int fq) const {
;     ...
;             for (int bj = 0; bj < 2; ++bj) { const size_t off = (size_t)row * ldc + col0 + bj * HALF;
;                 const f32x4 a = (cx[bj][0] - mean) * sc * g[bj][0] + b[bj][0] + acc[ai][bj][m][0], d = (cx[bj][1] - mean) * sc * g[bj][1] + b[bj][1] + acc[ai][bj][m][1];
;                 *(f32x4*)(Dst + off) = a; *(f32x4*)(Dst + off + 4) = d;
;                 if (OUTB) { u32x4 pw; pw.x = cvt_pk_bf16(a[0], a[1]); pw.y = cvt_pk_bf16(a[2], a[3]); pw.z = cvt_pk_bf16(d[0], d[1]); pw.w = cvt_pk_bf16(d[2], d[3]);
;                     *(u32x4*)(YB + off) = pw;
;                     s1 += ((a[0] + a[1]) + (a[2] + a[3])) + ((d[0] + d[1]) + (d[2] + d[3]));
;                     s2 += ((a[0] * a[0] + a[1] * a[1]) + (a[2] * a[2] + a[3] * a[3])) + ((d[0] * d[0] + d[1] * d[1]) + (d[2] * d[2] + d[3] * d[3])); } }
;             if (OUTB) { s1 += __shfl_xor(s1, 16); s2 += __shfl_xor(s2, 16); s1 += __shfl_xor(s1, 32); s2 += __shfl_xor(s2, 32);
;                 if (fq == 0) { __hip_atomic_fetch_add(st_out + 2 * row, s1, __ATOMIC_RELAXED, __HIP_MEMORY_SCOPE_AGENT); __hip_atomic_fetch_add(st_out + 2 * row + 1, s2, __ATOMIC_RELAXED, __HIP_MEMORY_SCOPE_AGENT); } } }
	v_add_f32_e32 v140, v141, v140
	v_add_f32_e32 v136, v137, v136
	global_store_dwordx4 v[226:227], v[220:223], off
	v_add_f32_e32 v140, v140, v136
	v_sub_f32_e32 v137, v245, v208
	v_add_f32_e32 v220, v138, v139
	v_sub_f32_e32 v136, v244, v208
	v_sub_f32_e32 v139, v247, v208
	v_sub_f32_e32 v138, v246, v208
	v_pk_mul_f32 v[138:139], v[138:139], v[228:229] op_sel_hi:[1,0]
	v_pk_mul_f32 v[136:137], v[136:137], v[228:229] op_sel_hi:[1,0]
	v_pk_fma_f32 v[138:139], v[74:75], v[138:139], v[182:183]
	v_pk_fma_f32 v[136:137], v[72:73], v[136:137], v[184:185]
	v_pk_add_f32 v[134:135], v[134:135], v[138:139]
	v_pk_add_f32 v[132:133], v[132:133], v[136:137]
	v_sub_f32_e32 v137, v237, v208
	v_sub_f32_e32 v136, v236, v208
	v_sub_f32_e32 v139, v239, v208
	v_sub_f32_e32 v138, v238, v208
	v_pk_mul_f32 v[138:139], v[138:139], v[228:229] op_sel_hi:[1,0]
	v_pk_mul_f32 v[136:137], v[136:137], v[228:229] op_sel_hi:[1,0]
	v_pk_fma_f32 v[138:139], v[66:67], v[138:139], v[178:179]
	v_pk_fma_f32 v[136:137], v[64:65], v[136:137], v[180:181]
	v_pk_add_f32 v[138:139], v[130:131], v[138:139]
	v_pk_add_f32 v[136:137], v[128:129], v[136:137]
	v_add_f32_e32 v128, v132, v133
	v_add_f32_e32 v129, v134, v135
	v_add_f32_e32 v128, v128, v129
	v_add_f32_e32 v129, v136, v137
	v_add_f32_e32 v130, v138, v139
	v_add_f32_e32 v129, v129, v130
	v_add_f32_e32 v128, v128, v129
	v_mul_f32_e32 v129, v133, v133
	v_mul_f32_e32 v130, v135, v135
	v_fmac_f32_e32 v129, v132, v132
	v_fmac_f32_e32 v130, v134, v134
	v_add_f32_e32 v129, v129, v130
	v_mul_f32_e32 v130, v137, v137
	v_mul_f32_e32 v131, v139, v139
	v_add_f32_e32 v219, v219, v220
	v_fmac_f32_e32 v130, v136, v136
	v_fmac_f32_e32 v131, v138, v138
	v_add_f32_e32 v209, v209, v219
	v_add_f32_e32 v130, v130, v131
	v_add_f32_e32 v209, 0, v209
	v_add_f32_e32 v129, v129, v130
	v_add_f32_e32 v128, v128, v209
	v_add_f32_e32 v129, v140, v129
	ds_bpermute_b32 v130, v218, v128
	ds_bpermute_b32 v131, v218, v129
	v_or_b32_e32 v224, 0x100, v224
	global_store_dwordx4 v[206:207], v[132:135], off offset:512
	global_store_dwordx4 v[206:207], v[136:139], off offset:528
	s_waitcnt lgkmcnt(1)
	v_add_f32_e32 v128, v128, v130
	s_waitcnt lgkmcnt(0)
	v_add_f32_e32 v129, v129, v131
	ds_bpermute_b32 v130, v195, v128
	ds_bpermute_b32 v131, v195, v129
	v_cvt_pk_bf16_f32 v132, v132, v133
	v_cvt_pk_bf16_f32 v133, v134, v135
	v_cvt_pk_bf16_f32 v134, v136, v137
	v_cvt_pk_bf16_f32 v135, v138, v139
	v_lshl_add_u64 v[136:137], s[24:25], 0, v[224:225]
	global_store_dwordx4 v[136:137], v[132:135], off
	v_lshl_add_u64 v[250:251], v[198:199], 2, s[38:39]
	s_waitcnt lgkmcnt(1)
	v_add_f32_e32 v128, v128, v130
	s_waitcnt lgkmcnt(0)
	v_add_f32_e32 v129, v129, v131
	v_mov_b32_e32 v252, v128
	v_mov_b32_e32 v253, v129
	v_or_b32_e32 v206, 32, v194
	v_lshlrev_b32_e32 v198, 1, v206
	v_ashrrev_i32_e32 v199, 31, v198
	v_lshl_add_u64 v[128:129], v[198:199], 2, s[36:37]
	v_pk_mul_f32 v[220:221], v[202:203], s[46:47] op_sel_hi:[1,0]
	global_load_dwordx2 v[208:209], v[128:129], off
	v_fma_f32 v128, -v220, v220, v221
	v_add_f32_e32 v128, 0x3727c5ac, v128
	v_mul_f32_e32 v129, 0x4f800000, v128
	v_cmp_gt_f32_e32 vcc, s77, v128
	v_ashrrev_i32_e32 v207, 31, v206
	v_sub_f32_e32 v157, v157, v220
	s_waitcnt lgkmcnt(1)
	v_cndmask_b32_e32 v130, v128, v129, vcc
	s_waitcnt lgkmcnt(0)
	v_sqrt_f32_e32 v131, v130
	v_lshlrev_b64 v[128:129], 13, v[206:207]
	v_lshl_add_u64 v[128:129], s[18:19], 0, v[128:129]
	v_lshl_add_u64 v[202:203], v[176:177], 2, v[128:129]
	v_add_u32_e32 v128, -1, v131
	v_fma_f32 v129, -v128, v131, v130
	v_cmp_ge_f32_e64 s[10:11], 0, v129
	v_add_u32_e32 v129, 1, v131
	v_sub_f32_e32 v156, v156, v220
	v_cndmask_b32_e64 v128, v131, v128, s[10:11]
	v_fma_f32 v131, -v129, v131, v130
	v_cmp_lt_f32_e64 s[10:11], 0, v131
	v_sub_f32_e32 v159, v159, v220
	v_sub_f32_e32 v158, v158, v220
	v_cndmask_b32_e64 v128, v128, v129, s[10:11]
	v_mul_f32_e32 v129, 0x37800000, v128
	v_cndmask_b32_e32 v128, v128, v129, vcc
	v_cmp_class_f32_e32 vcc, v130, v217
	v_sub_f32_e32 v153, v153, v220
	v_sub_f32_e32 v152, v152, v220
	v_cndmask_b32_e32 v219, v128, v130, vcc
	global_load_dwordx4 v[136:139], v[202:203], off offset:16
	global_load_dwordx4 v[140:143], v[202:203], off
	global_load_dwordx4 v[128:131], v[202:203], off offset:528
	global_load_dwordx4 v[132:135], v[202:203], off offset:512
	v_div_scale_f32 v221, s[10:11], v219, v219, 1.0
	v_rcp_f32_e32 v222, v221
	v_sub_f32_e32 v155, v155, v220
	v_sub_f32_e32 v154, v154, v220
	v_lshlrev_b64 v[204:205], 11, v[204:205]
	v_fma_f32 v223, -v221, v222, 1.0
	v_fmac_f32_e32 v222, v223, v222
	v_div_scale_f32 v223, vcc, 1.0, v219, 1.0
	v_mul_f32_e32 v224, v223, v222
	v_fma_f32 v225, -v221, v224, v223
	v_fmac_f32_e32 v224, v225, v222
	v_fma_f32 v221, -v221, v224, v223
	v_div_fmas_f32 v221, v221, v222, v224
	v_div_fixup_f32 v219, v221, v219, 1.0
	v_mul_f32_e32 v222, 0x3fb504f3, v219
	v_pk_mul_f32 v[158:159], v[158:159], v[222:223] op_sel_hi:[1,0]
	v_pk_mul_f32 v[156:157], v[156:157], v[222:223] op_sel_hi:[1,0]
	v_pk_mul_f32 v[154:155], v[154:155], v[222:223] op_sel_hi:[1,0]
	v_pk_mul_f32 v[152:153], v[152:153], v[222:223] op_sel_hi:[1,0]
	v_lshl_add_u64 v[204:205], v[204:205], 0, v[176:177]
	v_pk_fma_f32 v[156:157], v[76:77], v[156:157], v[192:193]
	v_pk_fma_f32 v[158:159], v[78:79], v[158:159], v[190:191]
	v_pk_fma_f32 v[152:153], v[68:69], v[152:153], v[188:189]
	v_pk_fma_f32 v[154:155], v[70:71], v[154:155], v[186:187]
	v_pk_add_f32 v[126:127], v[126:127], v[158:159]
	v_pk_add_f32 v[124:125], v[124:125], v[156:157]
	v_pk_add_f32 v[122:123], v[122:123], v[154:155]
	v_pk_add_f32 v[120:121], v[120:121], v[152:153]
	v_lshlrev_b64 v[156:157], 1, v[204:205]
	v_cvt_pk_bf16_f32 v152, v124, v125
;     __device__ __forceinline__ void operator()(const f32x4 (&acc)[2][2][4][2], const Unit& u, int wr, int wc, int fr, int fq) const {
;     ...
;         for (int r = 0; r < 8; ++r) { const int ai = r >> 2, m = r & 3; const int row = row0 + ai * HALF + m * 16;
;             f32x4 cx[2][2]; const f32x2v cst = nst;
; #pragma unroll
;             for (int bj = 0; bj < 2; ++bj) { cx[bj][0] = nx[bj][0]; cx[bj][1] = nx[bj][1]; }
;             if (r + 1 < 8) { const int rown = row0 + ((r + 1) >> 2) * HALF + ((r + 1) & 3) * 16; nst = *(const f32x2v*)(st_in + 2 * rown);
; #pragma unroll
;                 for (int bj = 0; bj < 2; ++bj) { const size_t off = (size_t)rown * ldc + col0 + bj * HALF; nx[bj][0] = *(const f32x4*)(Src + off); nx[bj][1] = *(const f32x4*)(Src + off + 4); } }
;             const float mean = cst.x * (1.0f / 2048.0f); const float rstd = 1.0f / sqrtf(cst.y * (1.0f / 2048.0f) - mean * mean + 1e-5f);
;             const float sc = rstd * alpha; float s1 = 0.f, s2 = 0.f;
; #pragma unroll
;             for (int bj = 0; bj < 2; ++bj) { const size_t off = (size_t)row * ldc + col0 + bj * HALF;
;                 const f32x4 a = (cx[bj][0] - mean) * sc * g[bj][0] + b[bj][0] + acc[ai][bj][m][0], d = (cx[bj][1] - mean) * sc * g[bj][1] + b[bj][1] + acc[ai][bj][m][1];
;                 *(f32x4*)(Dst + off) = a; *(f32x4*)(Dst + off + 4) = d;
;                 if (OUTB) { u32x4 pw; pw.x = cvt_pk_bf16(a[0], a[1]); pw.y = cvt_pk_bf16(a[2], a[3]); pw.z = cvt_pk_bf16(d[0], d[1]); pw.w = cvt_pk_bf16(d[2], d[3]);
;                     *(u32x4*)(YB + off) = pw;
;                     s1 += ((a[0] + a[1]) + (a[2] + a[3])) + ((d[0] + d[1]) + (d[2] + d[3]));
;                     s2 += ((a[0] * a[0] + a[1] * a[1]) + (a[2] * a[2] + a[3] * a[3])) + ((d[0] * d[0] + d[1] * d[1]) + (d[2] * d[2] + d[3] * d[3])); } }
;             if (OUTB) { s1 += __shfl_xor(s1, 16); s2 += __shfl_xor(s2, 16); s1 += __shfl_xor(s1, 32); s2 += __shfl_xor(s2, 32);
;                 if (fq == 0) { __hip_atomic_fetch_add(st_out + 2 * row, s1, __ATOMIC_RELAXED, __HIP_MEMORY_SCOPE_AGENT); __hip_atomic_fetch_add(st_out + 2 * row + 1, s2, __ATOMIC_RELAXED, __HIP_MEMORY_SCOPE_AGENT); } } }
	v_cvt_pk_bf16_f32 v153, v126, v127
	v_cvt_pk_bf16_f32 v154, v120, v121
	v_cvt_pk_bf16_f32 v155, v122, v123
	v_lshl_add_u64 v[158:159], s[24:25], 0, v[156:157]
	global_store_dwordx4 v[200:201], v[124:127], off
	global_store_dwordx4 v[200:201], v[120:123], off offset:16
	global_store_dwordx4 v[158:159], v[152:155], off
	v_or_b32_e32 v156, 0x100, v156
	s_nop 0
	v_add_f32_e32 v152, v124, v125
	v_add_f32_e32 v153, v126, v127
	v_add_f32_e32 v152, v152, v153
	v_add_f32_e32 v153, v120, v121
	v_mul_f32_e32 v125, v125, v125
	v_mul_f32_e32 v121, v121, v121
	v_fmac_f32_e32 v125, v124, v124
	v_mul_f32_e32 v124, v127, v127
	v_fmac_f32_e32 v121, v120, v120
	v_mul_f32_e32 v120, v123, v123
	v_fmac_f32_e32 v124, v126, v126
	v_fmac_f32_e32 v120, v122, v122
	v_add_f32_e32 v124, v125, v124
	v_add_f32_e32 v120, v121, v120
	v_add_f32_e32 v154, v122, v123
	v_add_f32_e32 v124, v124, v120
	v_sub_f32_e32 v121, v149, v220
	v_sub_f32_e32 v120, v148, v220
	v_sub_f32_e32 v123, v151, v220
	v_sub_f32_e32 v122, v150, v220
	v_pk_mul_f32 v[122:123], v[122:123], v[222:223] op_sel_hi:[1,0]
	v_pk_mul_f32 v[120:121], v[120:121], v[222:223] op_sel_hi:[1,0]
	v_pk_fma_f32 v[122:123], v[74:75], v[122:123], v[182:183]
	v_pk_fma_f32 v[120:121], v[72:73], v[120:121], v[184:185]
	v_pk_add_f32 v[118:119], v[118:119], v[122:123]
	v_pk_add_f32 v[116:117], v[116:117], v[120:121]
	v_sub_f32_e32 v121, v145, v220
	v_sub_f32_e32 v120, v144, v220
	v_sub_f32_e32 v123, v147, v220
	v_sub_f32_e32 v122, v146, v220
	v_pk_mul_f32 v[122:123], v[122:123], v[222:223] op_sel_hi:[1,0]
	v_pk_mul_f32 v[120:121], v[120:121], v[222:223] op_sel_hi:[1,0]
	v_pk_fma_f32 v[122:123], v[66:67], v[122:123], v[178:179]
	v_pk_fma_f32 v[120:121], v[64:65], v[120:121], v[180:181]
	v_pk_add_f32 v[122:123], v[114:115], v[122:123]
	v_pk_add_f32 v[120:121], v[112:113], v[120:121]
	v_add_f32_e32 v112, v116, v117
	v_add_f32_e32 v113, v118, v119
	v_add_f32_e32 v112, v112, v113
	v_add_f32_e32 v113, v120, v121
	v_add_f32_e32 v114, v122, v123
	v_add_f32_e32 v113, v113, v114
	v_add_f32_e32 v112, v112, v113
	v_mul_f32_e32 v113, v117, v117
	v_mul_f32_e32 v114, v119, v119
	v_fmac_f32_e32 v113, v116, v116
	v_fmac_f32_e32 v114, v118, v118
	v_add_f32_e32 v113, v113, v114
	v_mul_f32_e32 v114, v121, v121
	v_mul_f32_e32 v115, v123, v123
	v_add_f32_e32 v153, v153, v154
	v_fmac_f32_e32 v114, v120, v120
	v_fmac_f32_e32 v115, v122, v122
	v_add_f32_e32 v152, v152, v153
	v_add_f32_e32 v114, v114, v115
	v_add_f32_e32 v152, 0, v152
	v_add_f32_e32 v113, v113, v114
	v_add_f32_e32 v112, v112, v152
	v_add_f32_e32 v113, v124, v113
	ds_bpermute_b32 v114, v218, v112
	ds_bpermute_b32 v115, v218, v113
	global_store_dwordx4 v[200:201], v[116:119], off offset:512
	global_store_dwordx4 v[200:201], v[120:123], off offset:528
	s_waitcnt lgkmcnt(1)
	v_add_f32_e32 v112, v112, v114
	s_waitcnt lgkmcnt(0)
	v_add_f32_e32 v113, v113, v115
	ds_bpermute_b32 v114, v195, v112
	ds_bpermute_b32 v115, v195, v113
	v_cvt_pk_bf16_f32 v116, v116, v117
	v_cvt_pk_bf16_f32 v117, v118, v119
	v_cvt_pk_bf16_f32 v118, v120, v121
	v_cvt_pk_bf16_f32 v119, v122, v123
	v_lshl_add_u64 v[120:121], s[24:25], 0, v[156:157]
	global_store_dwordx4 v[120:121], v[116:119], off
	s_waitcnt lgkmcnt(1)
	v_add_f32_e32 v112, v112, v114
	s_waitcnt lgkmcnt(0)
	v_add_f32_e32 v113, v113, v115
	s_mov_b32 s90, 0xffff0000
	s_mov_b32 s91, 0
	v_cndmask_b32_e64 v252, v252, v112, s[90:91]
	v_cndmask_b32_e64 v253, v253, v113, s[90:91]
	v_or_b32_e32 v148, 48, v194
	v_lshlrev_b32_e32 v144, 1, v148
	v_ashrrev_i32_e32 v145, 31, v144
	v_lshl_add_u64 v[112:113], v[144:145], 2, s[36:37]
	s_waitcnt vmcnt(8)
	v_pk_mul_f32 v[152:153], v[208:209], s[46:47] op_sel_hi:[1,0]
	global_load_dwordx2 v[150:151], v[112:113], off
	v_fma_f32 v112, -v152, v152, v153
	v_add_f32_e32 v112, 0x3727c5ac, v112
	v_mul_f32_e32 v113, 0x4f800000, v112
	v_cmp_gt_f32_e32 vcc, s77, v112
	v_ashrrev_i32_e32 v149, 31, v148
	s_waitcnt vmcnt(7)
	v_sub_f32_e32 v141, v141, v152
	s_waitcnt lgkmcnt(1)
	v_cndmask_b32_e32 v114, v112, v113, vcc
	s_waitcnt lgkmcnt(0)
	v_sqrt_f32_e32 v115, v114
	v_lshlrev_b64 v[112:113], 13, v[148:149]
	v_lshl_add_u64 v[112:113], s[18:19], 0, v[112:113]
	v_lshl_add_u64 v[146:147], v[176:177], 2, v[112:113]
	v_add_u32_e32 v112, -1, v115
	v_fma_f32 v113, -v112, v115, v114
	v_cmp_ge_f32_e64 s[10:11], 0, v113
	v_add_u32_e32 v113, 1, v115
	v_sub_f32_e32 v140, v140, v152
	v_cndmask_b32_e64 v112, v115, v112, s[10:11]
	v_fma_f32 v115, -v113, v115, v114
	v_cmp_lt_f32_e64 s[10:11], 0, v115
	v_sub_f32_e32 v143, v143, v152
	v_sub_f32_e32 v142, v142, v152
	v_cndmask_b32_e64 v112, v112, v113, s[10:11]
	v_mul_f32_e32 v113, 0x37800000, v112
	v_cndmask_b32_e32 v112, v112, v113, vcc
	v_cmp_class_f32_e32 vcc, v114, v217
	v_sub_f32_e32 v137, v137, v152
	v_sub_f32_e32 v136, v136, v152
	v_cndmask_b32_e32 v153, v112, v114, vcc
	global_load_dwordx4 v[120:123], v[146:147], off offset:16
	global_load_dwordx4 v[124:127], v[146:147], off
	global_load_dwordx4 v[112:115], v[146:147], off offset:528
	global_load_dwordx4 v[116:119], v[146:147], off offset:512
	v_div_scale_f32 v154, s[10:11], v153, v153, 1.0
	v_rcp_f32_e32 v155, v154
	v_sub_f32_e32 v139, v139, v152
	v_sub_f32_e32 v138, v138, v152
	v_fma_f32 v156, -v154, v155, 1.0
	v_fmac_f32_e32 v155, v156, v155
	v_div_scale_f32 v156, vcc, 1.0, v153, 1.0
	v_mul_f32_e32 v157, v156, v155
	v_fma_f32 v158, -v154, v157, v156
	v_fmac_f32_e32 v157, v158, v155
	v_fma_f32 v154, -v154, v157, v156
	v_div_fmas_f32 v154, v154, v155, v157
	v_div_fixup_f32 v153, v154, v153, 1.0
	v_mul_f32_e32 v154, 0x3fb504f3, v153
	v_lshlrev_b64 v[156:157], 11, v[206:207]
	v_pk_mul_f32 v[142:143], v[142:143], v[154:155] op_sel_hi:[1,0]
;     __device__ __forceinline__ void operator()(const f32x4 (&acc)[2][2][4][2], const Unit& u, int wr, int wc, int fr, int fq) const {
;     ...
;         for (int r = 0; r < 8; ++r) { const int ai = r >> 2, m = r & 3; const int row = row0 + ai * HALF + m * 16;
;             f32x4 cx[2][2]; const f32x2v cst = nst;
; #pragma unroll
;             for (int bj = 0; bj < 2; ++bj) { cx[bj][0] = nx[bj][0]; cx[bj][1] = nx[bj][1]; }
;             if (r + 1 < 8) { const int rown = row0 + ((r + 1) >> 2) * HALF + ((r + 1) & 3) * 16; nst = *(const f32x2v*)(st_in + 2 * rown);
; #pragma unroll
;                 for (int bj = 0; bj < 2; ++bj) { const size_t off = (size_t)rown * ldc + col0 + bj * HALF; nx[bj][0] = *(const f32x4*)(Src + off); nx[bj][1] = *(const f32x4*)(Src + off + 4); } }
;             const float mean = cst.x * (1.0f / 2048.0f); const float rstd = 1.0f / sqrtf(cst.y * (1.0f / 2048.0f) - mean * mean + 1e-5f);
;             const float sc = rstd * alpha; float s1 = 0.f, s2 = 0.f;
; #pragma unroll
;             for (int bj = 0; bj < 2; ++bj) { const size_t off = (size_t)row * ldc + col0 + bj * HALF;
;                 const f32x4 a = (cx[bj][0] - mean) * sc * g[bj][0] + b[bj][0] + acc[ai][bj][m][0], d = (cx[bj][1] - mean) * sc * g[bj][1] + b[bj][1] + acc[ai][bj][m][1];
;                 *(f32x4*)(Dst + off) = a; *(f32x4*)(Dst + off + 4) = d;
;                 if (OUTB) { u32x4 pw; pw.x = cvt_pk_bf16(a[0], a[1]); pw.y = cvt_pk_bf16(a[2], a[3]); pw.z = cvt_pk_bf16(d[0], d[1]); pw.w = cvt_pk_bf16(d[2], d[3]);
;                     *(u32x4*)(YB + off) = pw;
;                     s1 += ((a[0] + a[1]) + (a[2] + a[3])) + ((d[0] + d[1]) + (d[2] + d[3]));
;                     s2 += ((a[0] * a[0] + a[1] * a[1]) + (a[2] * a[2] + a[3] * a[3])) + ((d[0] * d[0] + d[1] * d[1]) + (d[2] * d[2] + d[3] * d[3])); } }
;             if (OUTB) { s1 += __shfl_xor(s1, 16); s2 += __shfl_xor(s2, 16); s1 += __shfl_xor(s1, 32); s2 += __shfl_xor(s2, 32);
;                 if (fq == 0) { __hip_atomic_fetch_add(st_out + 2 * row, s1, __ATOMIC_RELAXED, __HIP_MEMORY_SCOPE_AGENT); __hip_atomic_fetch_add(st_out + 2 * row + 1, s2, __ATOMIC_RELAXED, __HIP_MEMORY_SCOPE_AGENT); } } }
	v_pk_mul_f32 v[140:141], v[140:141], v[154:155] op_sel_hi:[1,0]
	v_pk_mul_f32 v[138:139], v[138:139], v[154:155] op_sel_hi:[1,0]
	v_pk_mul_f32 v[136:137], v[136:137], v[154:155] op_sel_hi:[1,0]
	v_lshl_add_u64 v[156:157], v[156:157], 0, v[176:177]
	v_pk_fma_f32 v[140:141], v[76:77], v[140:141], v[192:193]
	v_pk_fma_f32 v[142:143], v[78:79], v[142:143], v[190:191]
	v_pk_fma_f32 v[136:137], v[68:69], v[136:137], v[188:189]
	v_pk_fma_f32 v[138:139], v[70:71], v[138:139], v[186:187]
	v_pk_add_f32 v[110:111], v[110:111], v[142:143]
	v_pk_add_f32 v[108:109], v[108:109], v[140:141]
	v_pk_add_f32 v[106:107], v[106:107], v[138:139]
	v_pk_add_f32 v[104:105], v[104:105], v[136:137]
	v_lshlrev_b64 v[140:141], 1, v[156:157]
	v_cvt_pk_bf16_f32 v136, v108, v109
	v_cvt_pk_bf16_f32 v137, v110, v111
	v_cvt_pk_bf16_f32 v138, v104, v105
	v_cvt_pk_bf16_f32 v139, v106, v107
	v_lshl_add_u64 v[142:143], s[24:25], 0, v[140:141]
	global_store_dwordx4 v[202:203], v[108:111], off
	global_store_dwordx4 v[202:203], v[104:107], off offset:16
	global_store_dwordx4 v[142:143], v[136:139], off
	v_or_b32_e32 v140, 0x100, v140
	s_nop 0
	v_add_f32_e32 v136, v108, v109
	v_add_f32_e32 v137, v110, v111
	v_add_f32_e32 v136, v136, v137
	v_add_f32_e32 v137, v104, v105
	v_mul_f32_e32 v109, v109, v109
	v_mul_f32_e32 v105, v105, v105
	v_fmac_f32_e32 v109, v108, v108
	v_mul_f32_e32 v108, v111, v111
	v_fmac_f32_e32 v105, v104, v104
	v_mul_f32_e32 v104, v107, v107
	v_fmac_f32_e32 v108, v110, v110
	v_fmac_f32_e32 v104, v106, v106
	v_add_f32_e32 v108, v109, v108
	v_add_f32_e32 v104, v105, v104
	v_add_f32_e32 v138, v106, v107
	v_add_f32_e32 v108, v108, v104
	s_waitcnt vmcnt(12)
	v_sub_f32_e32 v105, v133, v152
	v_sub_f32_e32 v104, v132, v152
	v_sub_f32_e32 v107, v135, v152
	v_sub_f32_e32 v106, v134, v152
	v_pk_mul_f32 v[106:107], v[106:107], v[154:155] op_sel_hi:[1,0]
	v_pk_mul_f32 v[104:105], v[104:105], v[154:155] op_sel_hi:[1,0]
	v_pk_fma_f32 v[106:107], v[74:75], v[106:107], v[182:183]
	v_pk_fma_f32 v[104:105], v[72:73], v[104:105], v[184:185]
	v_pk_add_f32 v[102:103], v[102:103], v[106:107]
	v_pk_add_f32 v[100:101], v[100:101], v[104:105]
	v_sub_f32_e32 v105, v129, v152
	v_sub_f32_e32 v104, v128, v152
	v_sub_f32_e32 v107, v131, v152
	v_sub_f32_e32 v106, v130, v152
	v_pk_mul_f32 v[106:107], v[106:107], v[154:155] op_sel_hi:[1,0]
	v_pk_mul_f32 v[104:105], v[104:105], v[154:155] op_sel_hi:[1,0]
	v_pk_fma_f32 v[106:107], v[66:67], v[106:107], v[178:179]
	v_pk_fma_f32 v[104:105], v[64:65], v[104:105], v[180:181]
	v_pk_add_f32 v[106:107], v[98:99], v[106:107]
	v_pk_add_f32 v[104:105], v[96:97], v[104:105]
	v_add_f32_e32 v96, v100, v101
	v_add_f32_e32 v97, v102, v103
	v_add_f32_e32 v96, v96, v97
	v_add_f32_e32 v97, v104, v105
	v_add_f32_e32 v98, v106, v107
	v_add_f32_e32 v97, v97, v98
	v_add_f32_e32 v96, v96, v97
	v_mul_f32_e32 v97, v101, v101
	v_mul_f32_e32 v98, v103, v103
	v_fmac_f32_e32 v97, v100, v100
	v_fmac_f32_e32 v98, v102, v102
	v_add_f32_e32 v97, v97, v98
	v_mul_f32_e32 v98, v105, v105
	v_mul_f32_e32 v99, v107, v107
	v_add_f32_e32 v137, v137, v138
	v_fmac_f32_e32 v98, v104, v104
	v_fmac_f32_e32 v99, v106, v106
	v_add_f32_e32 v136, v136, v137
	v_add_f32_e32 v98, v98, v99
	v_add_f32_e32 v136, 0, v136
	v_add_f32_e32 v97, v97, v98
	v_add_f32_e32 v96, v96, v136
	v_add_f32_e32 v97, v108, v97
	ds_bpermute_b32 v98, v218, v96
	ds_bpermute_b32 v99, v218, v97
	global_store_dwordx4 v[202:203], v[100:103], off offset:512
	global_store_dwordx4 v[202:203], v[104:107], off offset:528
	s_waitcnt lgkmcnt(1)
	v_add_f32_e32 v96, v96, v98
	s_waitcnt lgkmcnt(0)
	v_add_f32_e32 v97, v97, v99
	ds_bpermute_b32 v98, v195, v96
	ds_bpermute_b32 v99, v195, v97
	v_cvt_pk_bf16_f32 v100, v100, v101
	v_cvt_pk_bf16_f32 v101, v102, v103
	v_cvt_pk_bf16_f32 v102, v104, v105
	v_cvt_pk_bf16_f32 v103, v106, v107
	v_lshl_add_u64 v[104:105], s[24:25], 0, v[140:141]
	global_store_dwordx4 v[104:105], v[100:103], off
	s_waitcnt lgkmcnt(1)
	v_add_f32_e32 v96, v96, v98
	s_waitcnt lgkmcnt(0)
	v_add_f32_e32 v97, v97, v99
	s_mov_b32 s90, 0
	s_mov_b32 s91, 0xffff
	v_cndmask_b32_e64 v252, v252, v96, s[90:91]
	v_cndmask_b32_e64 v253, v253, v97, s[90:91]
	v_add_u32_e32 v128, 0x80, v194
	v_lshlrev_b32_e32 v130, 1, v128
	v_ashrrev_i32_e32 v131, 31, v130
	v_lshl_add_u64 v[96:97], v[130:131], 2, s[36:37]
	s_waitcnt vmcnt(8)
	v_pk_mul_f32 v[136:137], v[150:151], s[46:47] op_sel_hi:[1,0]
	global_load_dwordx2 v[134:135], v[96:97], off
	v_fma_f32 v96, -v136, v136, v137
	v_add_f32_e32 v96, 0x3727c5ac, v96
	v_mul_f32_e32 v97, 0x4f800000, v96
	v_cmp_gt_f32_e32 vcc, s77, v96
	v_ashrrev_i32_e32 v129, 31, v128
	s_waitcnt vmcnt(7)
	v_sub_f32_e32 v125, v125, v136
	s_waitcnt lgkmcnt(1)
	v_cndmask_b32_e32 v98, v96, v97, vcc
	s_waitcnt lgkmcnt(0)
;     __device__ __forceinline__ void operator()(const f32x4 (&acc)[2][2][4][2], const Unit& u, int wr, int wc, int fr, int fq) const {
;     ...
;         for (int r = 0; r < 8; ++r) { const int ai = r >> 2, m = r & 3; const int row = row0 + ai * HALF + m * 16;
;             f32x4 cx[2][2]; const f32x2v cst = nst;
; #pragma unroll
;             for (int bj = 0; bj < 2; ++bj) { cx[bj][0] = nx[bj][0]; cx[bj][1] = nx[bj][1]; }
;             if (r + 1 < 8) { const int rown = row0 + ((r + 1) >> 2) * HALF + ((r + 1) & 3) * 16; nst = *(const f32x2v*)(st_in + 2 * rown);
; #pragma unroll
;                 for (int bj = 0; bj < 2; ++bj) { const size_t off = (size_t)rown * ldc + col0 + bj * HALF; nx[bj][0] = *(const f32x4*)(Src + off); nx[bj][1] = *(const f32x4*)(Src + off + 4); } }
;             const float mean = cst.x * (1.0f / 2048.0f); const float rstd = 1.0f / sqrtf(cst.y * (1.0f / 2048.0f) - mean * mean + 1e-5f);
;             const float sc = rstd * alpha; float s1 = 0.f, s2 = 0.f;
; #pragma unroll
;             for (int bj = 0; bj < 2; ++bj) { const size_t off = (size_t)row * ldc + col0 + bj * HALF;
;                 const f32x4 a = (cx[bj][0] - mean) * sc * g[bj][0] + b[bj][0] + acc[ai][bj][m][0], d = (cx[bj][1] - mean) * sc * g[bj][1] + b[bj][1] + acc[ai][bj][m][1];
;                 *(f32x4*)(Dst + off) = a; *(f32x4*)(Dst + off + 4) = d;
;                 if (OUTB) { u32x4 pw; pw.x = cvt_pk_bf16(a[0], a[1]); pw.y = cvt_pk_bf16(a[2], a[3]); pw.z = cvt_pk_bf16(d[0], d[1]); pw.w = cvt_pk_bf16(d[2], d[3]);
;                     *(u32x4*)(YB + off) = pw;
;                     s1 += ((a[0] + a[1]) + (a[2] + a[3])) + ((d[0] + d[1]) + (d[2] + d[3]));
;                     s2 += ((a[0] * a[0] + a[1] * a[1]) + (a[2] * a[2] + a[3] * a[3])) + ((d[0] * d[0] + d[1] * d[1]) + (d[2] * d[2] + d[3] * d[3])); } }
;             if (OUTB) { s1 += __shfl_xor(s1, 16); s2 += __shfl_xor(s2, 16); s1 += __shfl_xor(s1, 32); s2 += __shfl_xor(s2, 32);
;                 if (fq == 0) { __hip_atomic_fetch_add(st_out + 2 * row, s1, __ATOMIC_RELAXED, __HIP_MEMORY_SCOPE_AGENT); __hip_atomic_fetch_add(st_out + 2 * row + 1, s2, __ATOMIC_RELAXED, __HIP_MEMORY_SCOPE_AGENT); } } }
	v_sqrt_f32_e32 v99, v98
	v_lshlrev_b64 v[96:97], 13, v[128:129]
	v_lshl_add_u64 v[96:97], s[18:19], 0, v[96:97]
	v_lshl_add_u64 v[132:133], v[176:177], 2, v[96:97]
	v_add_u32_e32 v96, -1, v99
	v_fma_f32 v97, -v96, v99, v98
	v_cmp_ge_f32_e64 s[10:11], 0, v97
	v_add_u32_e32 v97, 1, v99
	v_sub_f32_e32 v124, v124, v136
	v_cndmask_b32_e64 v96, v99, v96, s[10:11]
	v_fma_f32 v99, -v97, v99, v98
	v_cmp_lt_f32_e64 s[10:11], 0, v99
	v_sub_f32_e32 v127, v127, v136
	v_sub_f32_e32 v126, v126, v136
	v_cndmask_b32_e64 v96, v96, v97, s[10:11]
	v_mul_f32_e32 v97, 0x37800000, v96
	v_cndmask_b32_e32 v96, v96, v97, vcc
	v_cmp_class_f32_e32 vcc, v98, v217
	v_sub_f32_e32 v121, v121, v136
	v_sub_f32_e32 v120, v120, v136
	v_cndmask_b32_e32 v137, v96, v98, vcc
	global_load_dwordx4 v[104:107], v[132:133], off offset:16
	global_load_dwordx4 v[108:111], v[132:133], off
	global_load_dwordx4 v[96:99], v[132:133], off offset:528
	global_load_dwordx4 v[100:103], v[132:133], off offset:512
	v_div_scale_f32 v138, s[10:11], v137, v137, 1.0
	v_rcp_f32_e32 v139, v138
	v_sub_f32_e32 v123, v123, v136
	v_sub_f32_e32 v122, v122, v136
	v_fma_f32 v140, -v138, v139, 1.0
	v_fmac_f32_e32 v139, v140, v139
	v_div_scale_f32 v140, vcc, 1.0, v137, 1.0
	v_mul_f32_e32 v141, v140, v139
	v_fma_f32 v142, -v138, v141, v140
	v_fmac_f32_e32 v141, v142, v139
	v_fma_f32 v138, -v138, v141, v140
	v_div_fmas_f32 v138, v138, v139, v141
	v_div_fixup_f32 v137, v138, v137, 1.0
	v_mul_f32_e32 v138, 0x3fb504f3, v137
	v_lshlrev_b64 v[140:141], 11, v[148:149]
	v_pk_mul_f32 v[126:127], v[126:127], v[138:139] op_sel_hi:[1,0]
	v_pk_mul_f32 v[124:125], v[124:125], v[138:139] op_sel_hi:[1,0]
	v_pk_mul_f32 v[122:123], v[122:123], v[138:139] op_sel_hi:[1,0]
	v_pk_mul_f32 v[120:121], v[120:121], v[138:139] op_sel_hi:[1,0]
	v_lshl_add_u64 v[140:141], v[140:141], 0, v[176:177]
	v_pk_fma_f32 v[124:125], v[76:77], v[124:125], v[192:193]
	v_pk_fma_f32 v[126:127], v[78:79], v[126:127], v[190:191]
	v_pk_fma_f32 v[120:121], v[68:69], v[120:121], v[188:189]
	v_pk_fma_f32 v[122:123], v[70:71], v[122:123], v[186:187]
	v_pk_add_f32 v[94:95], v[94:95], v[126:127]
	v_pk_add_f32 v[92:93], v[92:93], v[124:125]
	v_pk_add_f32 v[90:91], v[90:91], v[122:123]
	v_pk_add_f32 v[88:89], v[88:89], v[120:121]
	v_lshlrev_b64 v[124:125], 1, v[140:141]
	v_cvt_pk_bf16_f32 v120, v92, v93
	v_cvt_pk_bf16_f32 v121, v94, v95
	v_cvt_pk_bf16_f32 v122, v88, v89
	v_cvt_pk_bf16_f32 v123, v90, v91
	v_lshl_add_u64 v[126:127], s[24:25], 0, v[124:125]
	global_store_dwordx4 v[146:147], v[92:95], off
	global_store_dwordx4 v[146:147], v[88:91], off offset:16
	global_store_dwordx4 v[126:127], v[120:123], off
	v_or_b32_e32 v124, 0x100, v124
	s_nop 0
	v_add_f32_e32 v120, v92, v93
	v_add_f32_e32 v121, v94, v95
	v_add_f32_e32 v120, v120, v121
	v_add_f32_e32 v121, v88, v89
	v_mul_f32_e32 v93, v93, v93
	v_mul_f32_e32 v89, v89, v89
	v_fmac_f32_e32 v93, v92, v92
	v_mul_f32_e32 v92, v95, v95
	v_fmac_f32_e32 v89, v88, v88
	v_mul_f32_e32 v88, v91, v91
	v_fmac_f32_e32 v92, v94, v94
	v_fmac_f32_e32 v88, v90, v90
	v_add_f32_e32 v92, v93, v92
	v_add_f32_e32 v88, v89, v88
	v_add_f32_e32 v122, v90, v91
	v_add_f32_e32 v92, v92, v88
	s_waitcnt vmcnt(12)
	v_sub_f32_e32 v89, v117, v136
	v_sub_f32_e32 v88, v116, v136
	v_sub_f32_e32 v91, v119, v136
	v_sub_f32_e32 v90, v118, v136
	v_pk_mul_f32 v[90:91], v[90:91], v[138:139] op_sel_hi:[1,0]
	v_pk_mul_f32 v[88:89], v[88:89], v[138:139] op_sel_hi:[1,0]
	v_pk_fma_f32 v[90:91], v[74:75], v[90:91], v[182:183]
	v_pk_fma_f32 v[88:89], v[72:73], v[88:89], v[184:185]
	v_pk_add_f32 v[86:87], v[86:87], v[90:91]
	v_pk_add_f32 v[84:85], v[84:85], v[88:89]
	v_sub_f32_e32 v89, v113, v136
	v_sub_f32_e32 v88, v112, v136
	v_sub_f32_e32 v91, v115, v136
	v_sub_f32_e32 v90, v114, v136
	v_pk_mul_f32 v[90:91], v[90:91], v[138:139] op_sel_hi:[1,0]
	v_pk_mul_f32 v[88:89], v[88:89], v[138:139] op_sel_hi:[1,0]
	v_pk_fma_f32 v[90:91], v[66:67], v[90:91], v[178:179]
	v_pk_fma_f32 v[88:89], v[64:65], v[88:89], v[180:181]
	v_pk_add_f32 v[90:91], v[82:83], v[90:91]
	v_pk_add_f32 v[88:89], v[80:81], v[88:89]
	v_add_f32_e32 v80, v84, v85
	v_add_f32_e32 v81, v86, v87
	v_add_f32_e32 v80, v80, v81
	v_add_f32_e32 v81, v88, v89
	v_add_f32_e32 v82, v90, v91
	v_add_f32_e32 v81, v81, v82
	v_add_f32_e32 v80, v80, v81
	v_mul_f32_e32 v81, v85, v85
	v_mul_f32_e32 v82, v87, v87
	v_fmac_f32_e32 v81, v84, v84
	v_fmac_f32_e32 v82, v86, v86
	v_add_f32_e32 v81, v81, v82
	v_mul_f32_e32 v82, v89, v89
	v_mul_f32_e32 v83, v91, v91
	v_add_f32_e32 v121, v121, v122
	v_fmac_f32_e32 v82, v88, v88
	v_fmac_f32_e32 v83, v90, v90
	v_add_f32_e32 v120, v120, v121
	v_add_f32_e32 v82, v82, v83
	v_add_f32_e32 v120, 0, v120
	v_add_f32_e32 v81, v81, v82
	v_add_f32_e32 v80, v80, v120
	v_add_f32_e32 v81, v92, v81
	ds_bpermute_b32 v82, v218, v80
	ds_bpermute_b32 v83, v218, v81
	global_store_dwordx4 v[146:147], v[84:87], off offset:512
	global_store_dwordx4 v[146:147], v[88:91], off offset:528
	s_waitcnt lgkmcnt(1)
	v_add_f32_e32 v80, v80, v82
	s_waitcnt lgkmcnt(0)
	v_add_f32_e32 v81, v81, v83
	ds_bpermute_b32 v82, v195, v80
	ds_bpermute_b32 v83, v195, v81
	v_cvt_pk_bf16_f32 v84, v84, v85
	v_cvt_pk_bf16_f32 v85, v86, v87
	v_cvt_pk_bf16_f32 v86, v88, v89
	v_cvt_pk_bf16_f32 v87, v90, v91
	v_lshl_add_u64 v[88:89], s[24:25], 0, v[124:125]
	global_store_dwordx4 v[88:89], v[84:87], off
	s_waitcnt lgkmcnt(1)
	v_add_f32_e32 v80, v80, v82
	s_waitcnt lgkmcnt(0)
	v_add_f32_e32 v81, v81, v83
	s_mov_b32 s90, 0
	s_mov_b32 s91, 0xffff0000
	v_cndmask_b32_e64 v252, v252, v80, s[90:91]
	v_cndmask_b32_e64 v253, v253, v81, s[90:91]
	v_or_b32_e32 v116, 16, v128
	v_lshlrev_b32_e32 v112, 1, v116
	v_ashrrev_i32_e32 v113, 31, v112
	v_lshl_add_u64 v[80:81], v[112:113], 2, s[36:37]
	s_waitcnt vmcnt(8)
;     __device__ __forceinline__ void operator()(const f32x4 (&acc)[2][2][4][2], const Unit& u, int wr, int wc, int fr, int fq) const {
;     ...
;         for (int r = 0; r < 8; ++r) { const int ai = r >> 2, m = r & 3; const int row = row0 + ai * HALF + m * 16;
;             f32x4 cx[2][2]; const f32x2v cst = nst;
; #pragma unroll
;             for (int bj = 0; bj < 2; ++bj) { cx[bj][0] = nx[bj][0]; cx[bj][1] = nx[bj][1]; }
;             if (r + 1 < 8) { const int rown = row0 + ((r + 1) >> 2) * HALF + ((r + 1) & 3) * 16; nst = *(const f32x2v*)(st_in + 2 * rown);
; #pragma unroll
;                 for (int bj = 0; bj < 2; ++bj) { const size_t off = (size_t)rown * ldc + col0 + bj * HALF; nx[bj][0] = *(const f32x4*)(Src + off); nx[bj][1] = *(const f32x4*)(Src + off + 4); } }
;             const float mean = cst.x * (1.0f / 2048.0f); const float rstd = 1.0f / sqrtf(cst.y * (1.0f / 2048.0f) - mean * mean + 1e-5f);
;             const float sc = rstd * alpha; float s1 = 0.f, s2 = 0.f;
; #pragma unroll
;             for (int bj = 0; bj < 2; ++bj) { const size_t off = (size_t)row * ldc + col0 + bj * HALF;
;                 const f32x4 a = (cx[bj][0] - mean) * sc * g[bj][0] + b[bj][0] + acc[ai][bj][m][0], d = (cx[bj][1] - mean) * sc * g[bj][1] + b[bj][1] + acc[ai][bj][m][1];
;                 *(f32x4*)(Dst + off) = a; *(f32x4*)(Dst + off + 4) = d;
;                 if (OUTB) { u32x4 pw; pw.x = cvt_pk_bf16(a[0], a[1]); pw.y = cvt_pk_bf16(a[2], a[3]); pw.z = cvt_pk_bf16(d[0], d[1]); pw.w = cvt_pk_bf16(d[2], d[3]);
;                     *(u32x4*)(YB + off) = pw;
;                     s1 += ((a[0] + a[1]) + (a[2] + a[3])) + ((d[0] + d[1]) + (d[2] + d[3]));
;                     s2 += ((a[0] * a[0] + a[1] * a[1]) + (a[2] * a[2] + a[3] * a[3])) + ((d[0] * d[0] + d[1] * d[1]) + (d[2] * d[2] + d[3] * d[3])); } }
;             if (OUTB) { s1 += __shfl_xor(s1, 16); s2 += __shfl_xor(s2, 16); s1 += __shfl_xor(s1, 32); s2 += __shfl_xor(s2, 32);
;                 if (fq == 0) { __hip_atomic_fetch_add(st_out + 2 * row, s1, __ATOMIC_RELAXED, __HIP_MEMORY_SCOPE_AGENT); __hip_atomic_fetch_add(st_out + 2 * row + 1, s2, __ATOMIC_RELAXED, __HIP_MEMORY_SCOPE_AGENT); } } }
	v_pk_mul_f32 v[120:121], v[134:135], s[46:47] op_sel_hi:[1,0]
	global_load_dwordx2 v[118:119], v[80:81], off
	v_fma_f32 v80, -v120, v120, v121
	v_add_f32_e32 v80, 0x3727c5ac, v80
	v_mul_f32_e32 v81, 0x4f800000, v80
	v_cmp_gt_f32_e32 vcc, s77, v80
	v_ashrrev_i32_e32 v117, 31, v116
	s_waitcnt vmcnt(7)
	v_sub_f32_e32 v109, v109, v120
	s_waitcnt lgkmcnt(1)
	v_cndmask_b32_e32 v82, v80, v81, vcc
	s_waitcnt lgkmcnt(0)
	v_sqrt_f32_e32 v83, v82
	v_lshlrev_b64 v[80:81], 13, v[116:117]
	v_lshl_add_u64 v[80:81], s[18:19], 0, v[80:81]
	v_lshl_add_u64 v[114:115], v[176:177], 2, v[80:81]
	v_add_u32_e32 v80, -1, v83
	v_fma_f32 v81, -v80, v83, v82
	v_cmp_ge_f32_e64 s[10:11], 0, v81
	v_add_u32_e32 v81, 1, v83
	v_sub_f32_e32 v108, v108, v120
	v_cndmask_b32_e64 v80, v83, v80, s[10:11]
	v_fma_f32 v83, -v81, v83, v82
	v_cmp_lt_f32_e64 s[10:11], 0, v83
	v_sub_f32_e32 v111, v111, v120
	v_sub_f32_e32 v110, v110, v120
	v_cndmask_b32_e64 v80, v80, v81, s[10:11]
	v_mul_f32_e32 v81, 0x37800000, v80
	v_cndmask_b32_e32 v80, v80, v81, vcc
	v_cmp_class_f32_e32 vcc, v82, v217
	v_sub_f32_e32 v105, v105, v120
	v_sub_f32_e32 v104, v104, v120
	v_cndmask_b32_e32 v121, v80, v82, vcc
	global_load_dwordx4 v[88:91], v[114:115], off offset:16
	global_load_dwordx4 v[92:95], v[114:115], off
	global_load_dwordx4 v[80:83], v[114:115], off offset:528
	global_load_dwordx4 v[84:87], v[114:115], off offset:512
	v_div_scale_f32 v122, s[10:11], v121, v121, 1.0
	v_rcp_f32_e32 v123, v122
	v_sub_f32_e32 v107, v107, v120
	v_sub_f32_e32 v106, v106, v120
	v_fma_f32 v124, -v122, v123, 1.0
	v_fmac_f32_e32 v123, v124, v123
	v_div_scale_f32 v124, vcc, 1.0, v121, 1.0
	v_mul_f32_e32 v125, v124, v123
	v_fma_f32 v126, -v122, v125, v124
	v_fmac_f32_e32 v125, v126, v123
	v_fma_f32 v122, -v122, v125, v124
	v_div_fmas_f32 v122, v122, v123, v125
	v_div_fixup_f32 v121, v122, v121, 1.0
	v_mul_f32_e32 v122, 0x3fb504f3, v121
	v_lshlrev_b64 v[124:125], 11, v[128:129]
	v_pk_mul_f32 v[110:111], v[110:111], v[122:123] op_sel_hi:[1,0]
	v_pk_mul_f32 v[108:109], v[108:109], v[122:123] op_sel_hi:[1,0]
	v_pk_mul_f32 v[106:107], v[106:107], v[122:123] op_sel_hi:[1,0]
	v_pk_mul_f32 v[104:105], v[104:105], v[122:123] op_sel_hi:[1,0]
	v_lshl_add_u64 v[124:125], v[124:125], 0, v[176:177]
	v_pk_fma_f32 v[108:109], v[76:77], v[108:109], v[192:193]
	v_pk_fma_f32 v[110:111], v[78:79], v[110:111], v[190:191]
	v_pk_fma_f32 v[104:105], v[68:69], v[104:105], v[188:189]
	v_pk_fma_f32 v[106:107], v[70:71], v[106:107], v[186:187]
	v_pk_add_f32 v[62:63], v[62:63], v[110:111]
	v_pk_add_f32 v[60:61], v[60:61], v[108:109]
	v_pk_add_f32 v[58:59], v[58:59], v[106:107]
	v_pk_add_f32 v[56:57], v[56:57], v[104:105]
	v_lshlrev_b64 v[108:109], 1, v[124:125]
	v_cvt_pk_bf16_f32 v104, v60, v61
	v_cvt_pk_bf16_f32 v105, v62, v63
	v_cvt_pk_bf16_f32 v106, v56, v57
	v_cvt_pk_bf16_f32 v107, v58, v59
	v_lshl_add_u64 v[110:111], s[24:25], 0, v[108:109]
	global_store_dwordx4 v[132:133], v[60:63], off
	global_store_dwordx4 v[132:133], v[56:59], off offset:16
	global_store_dwordx4 v[110:111], v[104:107], off
	v_or_b32_e32 v108, 0x100, v108
	s_nop 0
	v_add_f32_e32 v104, v60, v61
	v_add_f32_e32 v105, v62, v63
	v_add_f32_e32 v104, v104, v105
	v_add_f32_e32 v105, v56, v57
	v_mul_f32_e32 v61, v61, v61
	v_mul_f32_e32 v57, v57, v57
	v_fmac_f32_e32 v61, v60, v60
	v_mul_f32_e32 v60, v63, v63
	v_fmac_f32_e32 v57, v56, v56
	v_mul_f32_e32 v56, v59, v59
	v_fmac_f32_e32 v60, v62, v62
	v_fmac_f32_e32 v56, v58, v58
	v_add_f32_e32 v60, v61, v60
	v_add_f32_e32 v56, v57, v56
	v_add_f32_e32 v106, v58, v59
	v_add_f32_e32 v60, v60, v56
	s_waitcnt vmcnt(12)
	v_sub_f32_e32 v57, v101, v120
	v_sub_f32_e32 v56, v100, v120
	v_sub_f32_e32 v59, v103, v120
	v_sub_f32_e32 v58, v102, v120
	v_pk_mul_f32 v[58:59], v[58:59], v[122:123] op_sel_hi:[1,0]
	v_pk_mul_f32 v[56:57], v[56:57], v[122:123] op_sel_hi:[1,0]
	v_pk_fma_f32 v[58:59], v[74:75], v[58:59], v[182:183]
	v_pk_fma_f32 v[56:57], v[72:73], v[56:57], v[184:185]
	v_pk_add_f32 v[54:55], v[54:55], v[58:59]
	v_pk_add_f32 v[52:53], v[52:53], v[56:57]
	v_sub_f32_e32 v57, v97, v120
	v_sub_f32_e32 v56, v96, v120
	v_sub_f32_e32 v59, v99, v120
	v_sub_f32_e32 v58, v98, v120
	v_pk_mul_f32 v[58:59], v[58:59], v[122:123] op_sel_hi:[1,0]
	v_pk_mul_f32 v[56:57], v[56:57], v[122:123] op_sel_hi:[1,0]
	v_pk_fma_f32 v[58:59], v[66:67], v[58:59], v[178:179]
	v_pk_fma_f32 v[56:57], v[64:65], v[56:57], v[180:181]
	v_pk_add_f32 v[58:59], v[50:51], v[58:59]
	v_pk_add_f32 v[56:57], v[48:49], v[56:57]
	v_add_f32_e32 v48, v52, v53
	v_add_f32_e32 v49, v54, v55
	v_add_f32_e32 v48, v48, v49
	v_add_f32_e32 v49, v56, v57
	v_add_f32_e32 v50, v58, v59
	v_add_f32_e32 v49, v49, v50
	v_add_f32_e32 v48, v48, v49
	v_mul_f32_e32 v49, v53, v53
	v_mul_f32_e32 v50, v55, v55
	v_fmac_f32_e32 v49, v52, v52
	v_fmac_f32_e32 v50, v54, v54
	v_add_f32_e32 v49, v49, v50
	v_mul_f32_e32 v50, v57, v57
	v_mul_f32_e32 v51, v59, v59
	v_add_f32_e32 v105, v105, v106
	v_fmac_f32_e32 v50, v56, v56
	v_fmac_f32_e32 v51, v58, v58
	v_add_f32_e32 v104, v104, v105
	v_add_f32_e32 v50, v50, v51
	v_add_f32_e32 v104, 0, v104
	v_add_f32_e32 v49, v49, v50
	v_add_f32_e32 v48, v48, v104
	v_add_f32_e32 v49, v60, v49
	ds_bpermute_b32 v50, v218, v48
	ds_bpermute_b32 v51, v218, v49
	global_store_dwordx4 v[132:133], v[52:55], off offset:512
	global_store_dwordx4 v[132:133], v[56:59], off offset:528
	s_waitcnt lgkmcnt(1)
	v_add_f32_e32 v48, v48, v50
	s_waitcnt lgkmcnt(0)
	v_add_f32_e32 v49, v49, v51
	ds_bpermute_b32 v50, v195, v48
	ds_bpermute_b32 v51, v195, v49
	v_cvt_pk_bf16_f32 v52, v52, v53
	v_cvt_pk_bf16_f32 v53, v54, v55
	v_cvt_pk_bf16_f32 v54, v56, v57
	v_cvt_pk_bf16_f32 v55, v58, v59
	v_lshl_add_u64 v[56:57], s[24:25], 0, v[108:109]
	global_store_dwordx4 v[56:57], v[52:55], off
	s_waitcnt lgkmcnt(1)
;     __device__ __forceinline__ void operator()(const f32x4 (&acc)[2][2][4][2], const Unit& u, int wr, int wc, int fr, int fq) const {
;     ...
;         for (int r = 0; r < 8; ++r) { const int ai = r >> 2, m = r & 3; const int row = row0 + ai * HALF + m * 16;
;             f32x4 cx[2][2]; const f32x2v cst = nst;
; #pragma unroll
;             for (int bj = 0; bj < 2; ++bj) { cx[bj][0] = nx[bj][0]; cx[bj][1] = nx[bj][1]; }
;             if (r + 1 < 8) { const int rown = row0 + ((r + 1) >> 2) * HALF + ((r + 1) & 3) * 16; nst = *(const f32x2v*)(st_in + 2 * rown);
; #pragma unroll
;                 for (int bj = 0; bj < 2; ++bj) { const size_t off = (size_t)rown * ldc + col0 + bj * HALF; nx[bj][0] = *(const f32x4*)(Src + off); nx[bj][1] = *(const f32x4*)(Src + off + 4); } }
;             const float mean = cst.x * (1.0f / 2048.0f); const float rstd = 1.0f / sqrtf(cst.y * (1.0f / 2048.0f) - mean * mean + 1e-5f);
;             const float sc = rstd * alpha; float s1 = 0.f, s2 = 0.f;
; #pragma unroll
;             for (int bj = 0; bj < 2; ++bj) { const size_t off = (size_t)row * ldc + col0 + bj * HALF;
;                 const f32x4 a = (cx[bj][0] - mean) * sc * g[bj][0] + b[bj][0] + acc[ai][bj][m][0], d = (cx[bj][1] - mean) * sc * g[bj][1] + b[bj][1] + acc[ai][bj][m][1];
;                 *(f32x4*)(Dst + off) = a; *(f32x4*)(Dst + off + 4) = d;
;                 if (OUTB) { u32x4 pw; pw.x = cvt_pk_bf16(a[0], a[1]); pw.y = cvt_pk_bf16(a[2], a[3]); pw.z = cvt_pk_bf16(d[0], d[1]); pw.w = cvt_pk_bf16(d[2], d[3]);
;                     *(u32x4*)(YB + off) = pw;
;                     s1 += ((a[0] + a[1]) + (a[2] + a[3])) + ((d[0] + d[1]) + (d[2] + d[3]));
;                     s2 += ((a[0] * a[0] + a[1] * a[1]) + (a[2] * a[2] + a[3] * a[3])) + ((d[0] * d[0] + d[1] * d[1]) + (d[2] * d[2] + d[3] * d[3])); } }
;             if (OUTB) { s1 += __shfl_xor(s1, 16); s2 += __shfl_xor(s2, 16); s1 += __shfl_xor(s1, 32); s2 += __shfl_xor(s2, 32);
;                 if (fq == 0) { __hip_atomic_fetch_add(st_out + 2 * row, s1, __ATOMIC_RELAXED, __HIP_MEMORY_SCOPE_AGENT); __hip_atomic_fetch_add(st_out + 2 * row + 1, s2, __ATOMIC_RELAXED, __HIP_MEMORY_SCOPE_AGENT); } } }
	v_add_f32_e32 v48, v48, v50
	s_waitcnt lgkmcnt(0)
	v_add_f32_e32 v49, v49, v51
	v_mov_b32_e32 v254, v48
	v_mov_b32_e32 v255, v49
	v_or_b32_e32 v100, 32, v128
	v_lshlrev_b32_e32 v96, 1, v100
	v_ashrrev_i32_e32 v97, 31, v96
	v_lshl_add_u64 v[48:49], v[96:97], 2, s[36:37]
	s_waitcnt vmcnt(8)
	v_pk_mul_f32 v[104:105], v[118:119], s[46:47] op_sel_hi:[1,0]
	global_load_dwordx2 v[102:103], v[48:49], off
	v_fma_f32 v48, -v104, v104, v105
	v_add_f32_e32 v48, 0x3727c5ac, v48
	v_mul_f32_e32 v49, 0x4f800000, v48
	v_cmp_gt_f32_e32 vcc, s77, v48
	v_ashrrev_i32_e32 v101, 31, v100
	s_waitcnt vmcnt(7)
	v_sub_f32_e32 v93, v93, v104
	s_waitcnt lgkmcnt(1)
	v_cndmask_b32_e32 v50, v48, v49, vcc
	s_waitcnt lgkmcnt(0)
	v_sqrt_f32_e32 v51, v50
	v_lshlrev_b64 v[48:49], 13, v[100:101]
	v_lshl_add_u64 v[48:49], s[18:19], 0, v[48:49]
	v_lshl_add_u64 v[98:99], v[176:177], 2, v[48:49]
	v_add_u32_e32 v48, -1, v51
	v_fma_f32 v49, -v48, v51, v50
	v_cmp_ge_f32_e64 s[10:11], 0, v49
	v_add_u32_e32 v49, 1, v51
	v_sub_f32_e32 v92, v92, v104
	v_cndmask_b32_e64 v48, v51, v48, s[10:11]
	v_fma_f32 v51, -v49, v51, v50
	v_cmp_lt_f32_e64 s[10:11], 0, v51
	v_sub_f32_e32 v95, v95, v104
	v_sub_f32_e32 v94, v94, v104
	v_cndmask_b32_e64 v48, v48, v49, s[10:11]
	v_mul_f32_e32 v49, 0x37800000, v48
	v_cndmask_b32_e32 v48, v48, v49, vcc
	v_cmp_class_f32_e32 vcc, v50, v217
	v_sub_f32_e32 v89, v89, v104
	v_sub_f32_e32 v88, v88, v104
	v_cndmask_b32_e32 v105, v48, v50, vcc
	global_load_dwordx4 v[56:59], v[98:99], off offset:16
	global_load_dwordx4 v[60:63], v[98:99], off
	global_load_dwordx4 v[48:51], v[98:99], off offset:528
	global_load_dwordx4 v[52:55], v[98:99], off offset:512
	v_div_scale_f32 v106, s[10:11], v105, v105, 1.0
	v_rcp_f32_e32 v107, v106
	v_sub_f32_e32 v91, v91, v104
	v_sub_f32_e32 v90, v90, v104
	v_fma_f32 v108, -v106, v107, 1.0
	v_fmac_f32_e32 v107, v108, v107
	v_div_scale_f32 v108, vcc, 1.0, v105, 1.0
	v_mul_f32_e32 v109, v108, v107
	v_fma_f32 v110, -v106, v109, v108
	v_fmac_f32_e32 v109, v110, v107
	v_fma_f32 v106, -v106, v109, v108
	v_div_fmas_f32 v106, v106, v107, v109
	v_div_fixup_f32 v105, v106, v105, 1.0
	v_mul_f32_e32 v106, 0x3fb504f3, v105
	v_lshlrev_b64 v[108:109], 11, v[116:117]
	v_pk_mul_f32 v[94:95], v[94:95], v[106:107] op_sel_hi:[1,0]
	v_pk_mul_f32 v[92:93], v[92:93], v[106:107] op_sel_hi:[1,0]
	v_pk_mul_f32 v[90:91], v[90:91], v[106:107] op_sel_hi:[1,0]
	v_pk_mul_f32 v[88:89], v[88:89], v[106:107] op_sel_hi:[1,0]
	v_lshl_add_u64 v[108:109], v[108:109], 0, v[176:177]
	v_pk_fma_f32 v[92:93], v[76:77], v[92:93], v[192:193]
	v_pk_fma_f32 v[94:95], v[78:79], v[94:95], v[190:191]
	v_pk_fma_f32 v[88:89], v[68:69], v[88:89], v[188:189]
	v_pk_fma_f32 v[90:91], v[70:71], v[90:91], v[186:187]
	v_pk_add_f32 v[46:47], v[46:47], v[94:95]
	v_pk_add_f32 v[44:45], v[44:45], v[92:93]
	v_pk_add_f32 v[42:43], v[42:43], v[90:91]
	v_pk_add_f32 v[40:41], v[40:41], v[88:89]
	v_lshlrev_b64 v[92:93], 1, v[108:109]
	v_cvt_pk_bf16_f32 v88, v44, v45
	v_cvt_pk_bf16_f32 v89, v46, v47
	v_cvt_pk_bf16_f32 v90, v40, v41
	v_cvt_pk_bf16_f32 v91, v42, v43
	v_lshl_add_u64 v[94:95], s[24:25], 0, v[92:93]
	global_store_dwordx4 v[114:115], v[44:47], off
	global_store_dwordx4 v[114:115], v[40:43], off offset:16
	global_store_dwordx4 v[94:95], v[88:91], off
	v_or_b32_e32 v92, 0x100, v92
	s_nop 0
	v_add_f32_e32 v88, v44, v45
	v_add_f32_e32 v89, v46, v47
	v_add_f32_e32 v88, v88, v89
	v_add_f32_e32 v89, v40, v41
	v_mul_f32_e32 v45, v45, v45
	v_mul_f32_e32 v41, v41, v41
	v_fmac_f32_e32 v45, v44, v44
	v_mul_f32_e32 v44, v47, v47
	v_fmac_f32_e32 v41, v40, v40
	v_mul_f32_e32 v40, v43, v43
	v_fmac_f32_e32 v44, v46, v46
	v_fmac_f32_e32 v40, v42, v42
	v_add_f32_e32 v44, v45, v44
	v_add_f32_e32 v40, v41, v40
	v_add_f32_e32 v90, v42, v43
	v_add_f32_e32 v44, v44, v40
	s_waitcnt vmcnt(12)
	v_sub_f32_e32 v41, v85, v104
	v_sub_f32_e32 v40, v84, v104
	v_sub_f32_e32 v43, v87, v104
	v_sub_f32_e32 v42, v86, v104
	v_pk_mul_f32 v[42:43], v[42:43], v[106:107] op_sel_hi:[1,0]
	v_pk_mul_f32 v[40:41], v[40:41], v[106:107] op_sel_hi:[1,0]
	v_pk_fma_f32 v[42:43], v[74:75], v[42:43], v[182:183]
	v_pk_fma_f32 v[40:41], v[72:73], v[40:41], v[184:185]
	v_pk_add_f32 v[38:39], v[38:39], v[42:43]
	v_pk_add_f32 v[36:37], v[36:37], v[40:41]
	v_sub_f32_e32 v41, v81, v104
	v_sub_f32_e32 v40, v80, v104
	v_sub_f32_e32 v43, v83, v104
	v_sub_f32_e32 v42, v82, v104
	v_pk_mul_f32 v[42:43], v[42:43], v[106:107] op_sel_hi:[1,0]
	v_pk_mul_f32 v[40:41], v[40:41], v[106:107] op_sel_hi:[1,0]
	v_pk_fma_f32 v[42:43], v[66:67], v[42:43], v[178:179]
	v_pk_fma_f32 v[40:41], v[64:65], v[40:41], v[180:181]
	v_pk_add_f32 v[42:43], v[34:35], v[42:43]
	v_pk_add_f32 v[40:41], v[32:33], v[40:41]
	v_add_f32_e32 v32, v36, v37
	v_add_f32_e32 v33, v38, v39
	v_add_f32_e32 v32, v32, v33
	v_add_f32_e32 v33, v40, v41
	v_add_f32_e32 v34, v42, v43
	v_add_f32_e32 v33, v33, v34
	v_add_f32_e32 v32, v32, v33
	v_mul_f32_e32 v33, v37, v37
	v_mul_f32_e32 v34, v39, v39
	v_fmac_f32_e32 v33, v36, v36
	v_fmac_f32_e32 v34, v38, v38
	v_add_f32_e32 v33, v33, v34
	v_mul_f32_e32 v34, v41, v41
	v_mul_f32_e32 v35, v43, v43
	v_add_f32_e32 v89, v89, v90
	v_fmac_f32_e32 v34, v40, v40
	v_fmac_f32_e32 v35, v42, v42
	v_add_f32_e32 v88, v88, v89
	v_add_f32_e32 v34, v34, v35
	v_add_f32_e32 v88, 0, v88
	v_add_f32_e32 v33, v33, v34
	v_add_f32_e32 v32, v32, v88
	v_add_f32_e32 v33, v44, v33
	ds_bpermute_b32 v34, v218, v32
	ds_bpermute_b32 v35, v218, v33
	global_store_dwordx4 v[114:115], v[36:39], off offset:512
	global_store_dwordx4 v[114:115], v[40:43], off offset:528
	s_waitcnt lgkmcnt(1)
	v_add_f32_e32 v32, v32, v34
	s_waitcnt lgkmcnt(0)
;     __device__ __forceinline__ void operator()(const f32x4 (&acc)[2][2][4][2], const Unit& u, int wr, int wc, int fr, int fq) const {
;     ...
;         for (int r = 0; r < 8; ++r) { const int ai = r >> 2, m = r & 3; const int row = row0 + ai * HALF + m * 16;
;             f32x4 cx[2][2]; const f32x2v cst = nst;
; #pragma unroll
;             for (int bj = 0; bj < 2; ++bj) { cx[bj][0] = nx[bj][0]; cx[bj][1] = nx[bj][1]; }
;             if (r + 1 < 8) { const int rown = row0 + ((r + 1) >> 2) * HALF + ((r + 1) & 3) * 16; nst = *(const f32x2v*)(st_in + 2 * rown);
; #pragma unroll
;                 for (int bj = 0; bj < 2; ++bj) { const size_t off = (size_t)rown * ldc + col0 + bj * HALF; nx[bj][0] = *(const f32x4*)(Src + off); nx[bj][1] = *(const f32x4*)(Src + off + 4); } }
;             const float mean = cst.x * (1.0f / 2048.0f); const float rstd = 1.0f / sqrtf(cst.y * (1.0f / 2048.0f) - mean * mean + 1e-5f);
;             const float sc = rstd * alpha; float s1 = 0.f, s2 = 0.f;
; #pragma unroll
;             for (int bj = 0; bj < 2; ++bj) { const size_t off = (size_t)row * ldc + col0 + bj * HALF;
;                 const f32x4 a = (cx[bj][0] - mean) * sc * g[bj][0] + b[bj][0] + acc[ai][bj][m][0], d = (cx[bj][1] - mean) * sc * g[bj][1] + b[bj][1] + acc[ai][bj][m][1];
;                 *(f32x4*)(Dst + off) = a; *(f32x4*)(Dst + off + 4) = d;
;                 if (OUTB) { u32x4 pw; pw.x = cvt_pk_bf16(a[0], a[1]); pw.y = cvt_pk_bf16(a[2], a[3]); pw.z = cvt_pk_bf16(d[0], d[1]); pw.w = cvt_pk_bf16(d[2], d[3]);
;                     *(u32x4*)(YB + off) = pw;
;                     s1 += ((a[0] + a[1]) + (a[2] + a[3])) + ((d[0] + d[1]) + (d[2] + d[3]));
;                     s2 += ((a[0] * a[0] + a[1] * a[1]) + (a[2] * a[2] + a[3] * a[3])) + ((d[0] * d[0] + d[1] * d[1]) + (d[2] * d[2] + d[3] * d[3])); } }
;             if (OUTB) { s1 += __shfl_xor(s1, 16); s2 += __shfl_xor(s2, 16); s1 += __shfl_xor(s1, 32); s2 += __shfl_xor(s2, 32);
;                 if (fq == 0) { __hip_atomic_fetch_add(st_out + 2 * row, s1, __ATOMIC_RELAXED, __HIP_MEMORY_SCOPE_AGENT); __hip_atomic_fetch_add(st_out + 2 * row + 1, s2, __ATOMIC_RELAXED, __HIP_MEMORY_SCOPE_AGENT); } } }
	v_add_f32_e32 v33, v33, v35
	ds_bpermute_b32 v34, v195, v32
	ds_bpermute_b32 v35, v195, v33
	v_cvt_pk_bf16_f32 v36, v36, v37
	v_cvt_pk_bf16_f32 v37, v38, v39
	v_cvt_pk_bf16_f32 v38, v40, v41
	v_cvt_pk_bf16_f32 v39, v42, v43
	v_lshl_add_u64 v[40:41], s[24:25], 0, v[92:93]
	global_store_dwordx4 v[40:41], v[36:39], off
	s_waitcnt lgkmcnt(1)
	v_add_f32_e32 v32, v32, v34
	s_waitcnt lgkmcnt(0)
	v_add_f32_e32 v33, v33, v35
	s_mov_b32 s90, 0xffff0000
	s_mov_b32 s91, 0
	v_cndmask_b32_e64 v254, v254, v32, s[90:91]
	v_cndmask_b32_e64 v255, v255, v33, s[90:91]
	v_or_b32_e32 v84, 48, v128
	v_lshlrev_b32_e32 v80, 1, v84
	v_ashrrev_i32_e32 v81, 31, v80
	v_lshl_add_u64 v[32:33], v[80:81], 2, s[36:37]
	s_waitcnt vmcnt(8)
	v_pk_mul_f32 v[88:89], v[102:103], s[46:47] op_sel_hi:[1,0]
	global_load_dwordx2 v[86:87], v[32:33], off
	v_fma_f32 v32, -v88, v88, v89
	v_add_f32_e32 v32, 0x3727c5ac, v32
	v_mul_f32_e32 v33, 0x4f800000, v32
	v_cmp_gt_f32_e32 vcc, s77, v32
	v_ashrrev_i32_e32 v85, 31, v84
	s_waitcnt vmcnt(7)
	v_sub_f32_e32 v61, v61, v88
	s_waitcnt lgkmcnt(1)
	v_cndmask_b32_e32 v34, v32, v33, vcc
	s_waitcnt lgkmcnt(0)
	v_sqrt_f32_e32 v35, v34
	v_lshlrev_b64 v[32:33], 13, v[84:85]
	v_lshl_add_u64 v[32:33], s[18:19], 0, v[32:33]
	v_lshl_add_u64 v[82:83], v[176:177], 2, v[32:33]
	v_add_u32_e32 v32, -1, v35
	v_fma_f32 v33, -v32, v35, v34
	v_cmp_ge_f32_e64 s[10:11], 0, v33
	v_add_u32_e32 v33, 1, v35
	v_sub_f32_e32 v60, v60, v88
	v_cndmask_b32_e64 v32, v35, v32, s[10:11]
	v_fma_f32 v35, -v33, v35, v34
	v_cmp_lt_f32_e64 s[10:11], 0, v35
	v_sub_f32_e32 v63, v63, v88
	v_sub_f32_e32 v62, v62, v88
	v_cndmask_b32_e64 v32, v32, v33, s[10:11]
	v_mul_f32_e32 v33, 0x37800000, v32
	v_cndmask_b32_e32 v32, v32, v33, vcc
	v_cmp_class_f32_e32 vcc, v34, v217
	v_sub_f32_e32 v57, v57, v88
	v_sub_f32_e32 v56, v56, v88
	v_cndmask_b32_e32 v89, v32, v34, vcc
	global_load_dwordx4 v[40:43], v[82:83], off offset:16
	global_load_dwordx4 v[44:47], v[82:83], off
	global_load_dwordx4 v[32:35], v[82:83], off offset:528
	global_load_dwordx4 v[36:39], v[82:83], off offset:512
	v_div_scale_f32 v90, s[10:11], v89, v89, 1.0
	v_rcp_f32_e32 v91, v90
	v_sub_f32_e32 v59, v59, v88
	v_sub_f32_e32 v58, v58, v88
	v_fma_f32 v92, -v90, v91, 1.0
	v_fmac_f32_e32 v91, v92, v91
	v_div_scale_f32 v92, vcc, 1.0, v89, 1.0
	v_mul_f32_e32 v93, v92, v91
	v_fma_f32 v94, -v90, v93, v92
	v_fmac_f32_e32 v93, v94, v91
	v_fma_f32 v90, -v90, v93, v92
	v_div_fmas_f32 v90, v90, v91, v93
	v_div_fixup_f32 v89, v90, v89, 1.0
	v_mul_f32_e32 v90, 0x3fb504f3, v89
	v_lshlrev_b64 v[92:93], 11, v[100:101]
	v_pk_mul_f32 v[62:63], v[62:63], v[90:91] op_sel_hi:[1,0]
	v_pk_mul_f32 v[60:61], v[60:61], v[90:91] op_sel_hi:[1,0]
	v_pk_mul_f32 v[58:59], v[58:59], v[90:91] op_sel_hi:[1,0]
	v_pk_mul_f32 v[56:57], v[56:57], v[90:91] op_sel_hi:[1,0]
	v_lshl_add_u64 v[92:93], v[92:93], 0, v[176:177]
	v_pk_fma_f32 v[60:61], v[76:77], v[60:61], v[192:193]
	v_pk_fma_f32 v[62:63], v[78:79], v[62:63], v[190:191]
	v_pk_fma_f32 v[56:57], v[68:69], v[56:57], v[188:189]
	v_pk_fma_f32 v[58:59], v[70:71], v[58:59], v[186:187]
	v_pk_add_f32 v[30:31], v[30:31], v[62:63]
	v_pk_add_f32 v[28:29], v[28:29], v[60:61]
	v_pk_add_f32 v[26:27], v[26:27], v[58:59]
	v_pk_add_f32 v[24:25], v[24:25], v[56:57]
	v_lshlrev_b64 v[60:61], 1, v[92:93]
	v_cvt_pk_bf16_f32 v56, v28, v29
	v_cvt_pk_bf16_f32 v57, v30, v31
	v_cvt_pk_bf16_f32 v58, v24, v25
	v_cvt_pk_bf16_f32 v59, v26, v27
	v_lshl_add_u64 v[62:63], s[24:25], 0, v[60:61]
	global_store_dwordx4 v[98:99], v[28:31], off
	global_store_dwordx4 v[98:99], v[24:27], off offset:16
	global_store_dwordx4 v[62:63], v[56:59], off
	v_or_b32_e32 v60, 0x100, v60
	s_nop 0
	v_add_f32_e32 v56, v28, v29
	v_add_f32_e32 v57, v30, v31
	v_add_f32_e32 v56, v56, v57
	v_add_f32_e32 v57, v24, v25
	v_mul_f32_e32 v29, v29, v29
	v_mul_f32_e32 v25, v25, v25
	v_fmac_f32_e32 v29, v28, v28
	v_mul_f32_e32 v28, v31, v31
	v_fmac_f32_e32 v25, v24, v24
	v_mul_f32_e32 v24, v27, v27
	v_fmac_f32_e32 v28, v30, v30
	v_fmac_f32_e32 v24, v26, v26
	v_add_f32_e32 v28, v29, v28
	v_add_f32_e32 v24, v25, v24
	v_add_f32_e32 v58, v26, v27
	v_add_f32_e32 v28, v28, v24
	s_waitcnt vmcnt(12)
	v_sub_f32_e32 v25, v53, v88
	v_sub_f32_e32 v24, v52, v88
	v_sub_f32_e32 v27, v55, v88
	v_sub_f32_e32 v26, v54, v88
	v_pk_mul_f32 v[26:27], v[26:27], v[90:91] op_sel_hi:[1,0]
	v_pk_mul_f32 v[24:25], v[24:25], v[90:91] op_sel_hi:[1,0]
	v_pk_fma_f32 v[26:27], v[74:75], v[26:27], v[182:183]
	v_pk_fma_f32 v[24:25], v[72:73], v[24:25], v[184:185]
	v_pk_add_f32 v[22:23], v[22:23], v[26:27]
	v_pk_add_f32 v[20:21], v[20:21], v[24:25]
	v_sub_f32_e32 v25, v49, v88
	v_sub_f32_e32 v24, v48, v88
	v_sub_f32_e32 v27, v51, v88
	v_sub_f32_e32 v26, v50, v88
	v_pk_mul_f32 v[26:27], v[26:27], v[90:91] op_sel_hi:[1,0]
	v_pk_mul_f32 v[24:25], v[24:25], v[90:91] op_sel_hi:[1,0]
	v_pk_fma_f32 v[26:27], v[66:67], v[26:27], v[178:179]
	v_pk_fma_f32 v[24:25], v[64:65], v[24:25], v[180:181]
	v_pk_add_f32 v[26:27], v[18:19], v[26:27]
	v_pk_add_f32 v[24:25], v[16:17], v[24:25]
	v_add_f32_e32 v16, v20, v21
	v_add_f32_e32 v17, v22, v23
	v_add_f32_e32 v16, v16, v17
	v_add_f32_e32 v17, v24, v25
	v_add_f32_e32 v18, v26, v27
	v_add_f32_e32 v17, v17, v18
	v_add_f32_e32 v16, v16, v17
	v_mul_f32_e32 v17, v21, v21
	v_mul_f32_e32 v18, v23, v23
	v_fmac_f32_e32 v17, v20, v20
	v_fmac_f32_e32 v18, v22, v22
	v_add_f32_e32 v17, v17, v18
	v_mul_f32_e32 v18, v25, v25
	v_mul_f32_e32 v19, v27, v27
	v_add_f32_e32 v57, v57, v58
	v_fmac_f32_e32 v18, v24, v24
	v_fmac_f32_e32 v19, v26, v26
	v_add_f32_e32 v56, v56, v57
	v_add_f32_e32 v18, v18, v19
	v_add_f32_e32 v56, 0, v56
	v_add_f32_e32 v17, v17, v18
	v_add_f32_e32 v16, v16, v56
	v_add_f32_e32 v17, v28, v17
	ds_bpermute_b32 v18, v218, v16
	ds_bpermute_b32 v19, v218, v17
	global_store_dwordx4 v[98:99], v[20:23], off offset:512
	global_store_dwordx4 v[98:99], v[24:27], off offset:528
	s_waitcnt lgkmcnt(1)
;     __device__ __forceinline__ void operator()(const f32x4 (&acc)[2][2][4][2], const Unit& u, int wr, int wc, int fr, int fq) const {
;     ...
;         for (int r = 0; r < 8; ++r) { const int ai = r >> 2, m = r & 3; const int row = row0 + ai * HALF + m * 16;
;             f32x4 cx[2][2]; const f32x2v cst = nst;
; #pragma unroll
;             for (int bj = 0; bj < 2; ++bj) { cx[bj][0] = nx[bj][0]; cx[bj][1] = nx[bj][1]; }
;             if (r + 1 < 8) { const int rown = row0 + ((r + 1) >> 2) * HALF + ((r + 1) & 3) * 16; nst = *(const f32x2v*)(st_in + 2 * rown);
; #pragma unroll
;                 for (int bj = 0; bj < 2; ++bj) { const size_t off = (size_t)rown * ldc + col0 + bj * HALF; nx[bj][0] = *(const f32x4*)(Src + off); nx[bj][1] = *(const f32x4*)(Src + off + 4); } }
;             const float mean = cst.x * (1.0f / 2048.0f); const float rstd = 1.0f / sqrtf(cst.y * (1.0f / 2048.0f) - mean * mean + 1e-5f);
;             const float sc = rstd * alpha; float s1 = 0.f, s2 = 0.f;
; #pragma unroll
;             for (int bj = 0; bj < 2; ++bj) { const size_t off = (size_t)row * ldc + col0 + bj * HALF;
;                 const f32x4 a = (cx[bj][0] - mean) * sc * g[bj][0] + b[bj][0] + acc[ai][bj][m][0], d = (cx[bj][1] - mean) * sc * g[bj][1] + b[bj][1] + acc[ai][bj][m][1];
;                 *(f32x4*)(Dst + off) = a; *(f32x4*)(Dst + off + 4) = d;
;                 if (OUTB) { u32x4 pw; pw.x = cvt_pk_bf16(a[0], a[1]); pw.y = cvt_pk_bf16(a[2], a[3]); pw.z = cvt_pk_bf16(d[0], d[1]); pw.w = cvt_pk_bf16(d[2], d[3]);
;                     *(u32x4*)(YB + off) = pw;
;                     s1 += ((a[0] + a[1]) + (a[2] + a[3])) + ((d[0] + d[1]) + (d[2] + d[3]));
;                     s2 += ((a[0] * a[0] + a[1] * a[1]) + (a[2] * a[2] + a[3] * a[3])) + ((d[0] * d[0] + d[1] * d[1]) + (d[2] * d[2] + d[3] * d[3])); } }
;             if (OUTB) { s1 += __shfl_xor(s1, 16); s2 += __shfl_xor(s2, 16); s1 += __shfl_xor(s1, 32); s2 += __shfl_xor(s2, 32);
;                 if (fq == 0) { __hip_atomic_fetch_add(st_out + 2 * row, s1, __ATOMIC_RELAXED, __HIP_MEMORY_SCOPE_AGENT); __hip_atomic_fetch_add(st_out + 2 * row + 1, s2, __ATOMIC_RELAXED, __HIP_MEMORY_SCOPE_AGENT); } } }
	v_add_f32_e32 v16, v16, v18
	s_waitcnt lgkmcnt(0)
	v_add_f32_e32 v17, v17, v19
	ds_bpermute_b32 v18, v195, v16
	ds_bpermute_b32 v19, v195, v17
	v_cvt_pk_bf16_f32 v20, v20, v21
	v_cvt_pk_bf16_f32 v21, v22, v23
	v_cvt_pk_bf16_f32 v22, v24, v25
	v_cvt_pk_bf16_f32 v23, v26, v27
	v_lshl_add_u64 v[24:25], s[24:25], 0, v[60:61]
	global_store_dwordx4 v[24:25], v[20:23], off
	s_waitcnt lgkmcnt(1)
	v_add_f32_e32 v16, v16, v18
	s_waitcnt lgkmcnt(0)
	v_add_f32_e32 v17, v17, v19
	s_mov_b32 s90, 0
	s_mov_b32 s91, 0xffff
	v_cndmask_b32_e64 v254, v254, v16, s[90:91]
	v_cndmask_b32_e64 v255, v255, v17, s[90:91]
	s_waitcnt vmcnt(8)
	v_pk_mul_f32 v[20:21], v[86:87], s[46:47] op_sel_hi:[1,0]
	s_nop 0
	v_fma_f32 v16, -v20, v20, v21
	v_add_f32_e32 v16, 0x3727c5ac, v16
	v_mul_f32_e32 v17, 0x4f800000, v16
	v_cmp_gt_f32_e32 vcc, s77, v16
	s_nop 1
	v_cndmask_b32_e32 v16, v16, v17, vcc
	v_sqrt_f32_e32 v17, v16
	s_waitcnt lgkmcnt(1)
	v_add_u32_e32 v18, -1, v17
	v_fma_f32 v21, -v18, v17, v16
	s_waitcnt lgkmcnt(0)
	v_add_u32_e32 v19, 1, v17
	v_cmp_ge_f32_e64 s[10:11], 0, v21
	s_nop 1
	v_cndmask_b32_e64 v18, v17, v18, s[10:11]
	v_fma_f32 v17, -v19, v17, v16
	v_cmp_lt_f32_e64 s[10:11], 0, v17
	s_nop 1
	v_cndmask_b32_e64 v17, v18, v19, s[10:11]
	v_mul_f32_e32 v18, 0x37800000, v17
	v_cndmask_b32_e32 v17, v17, v18, vcc
	v_cmp_class_f32_e32 vcc, v16, v217
	s_nop 1
	v_cndmask_b32_e32 v16, v17, v16, vcc
	v_div_scale_f32 v17, s[10:11], v16, v16, 1.0
	v_rcp_f32_e32 v18, v17
	s_nop 0
	v_fma_f32 v19, -v17, v18, 1.0
	v_fmac_f32_e32 v18, v19, v18
	v_div_scale_f32 v19, vcc, 1.0, v16, 1.0
	v_mul_f32_e32 v21, v19, v18
	v_fma_f32 v22, -v17, v21, v19
	v_fmac_f32_e32 v21, v22, v18
	v_fma_f32 v17, -v17, v21, v19
	v_div_fmas_f32 v17, v17, v18, v21
	v_div_fixup_f32 v16, v17, v16, 1.0
	v_mul_f32_e32 v22, 0x3fb504f3, v16
	v_lshlrev_b64 v[16:17], 11, v[84:85]
	v_lshl_add_u64 v[24:25], v[16:17], 0, v[176:177]
	s_waitcnt vmcnt(6)
	v_sub_f32_e32 v17, v45, v20
	v_sub_f32_e32 v16, v44, v20
	v_sub_f32_e32 v19, v47, v20
	v_sub_f32_e32 v18, v46, v20
	v_pk_mul_f32 v[18:19], v[18:19], v[22:23] op_sel_hi:[1,0]
	v_pk_mul_f32 v[16:17], v[16:17], v[22:23] op_sel_hi:[1,0]
	v_pk_fma_f32 v[18:19], v[78:79], v[18:19], v[190:191]
	v_pk_fma_f32 v[16:17], v[76:77], v[16:17], v[192:193]
	v_pk_add_f32 v[14:15], v[14:15], v[18:19]
	v_pk_add_f32 v[12:13], v[12:13], v[16:17]
	v_sub_f32_e32 v17, v41, v20
	v_sub_f32_e32 v16, v40, v20
	v_sub_f32_e32 v19, v43, v20
	v_sub_f32_e32 v18, v42, v20
	v_pk_mul_f32 v[18:19], v[18:19], v[22:23] op_sel_hi:[1,0]
	v_pk_mul_f32 v[16:17], v[16:17], v[22:23] op_sel_hi:[1,0]
	v_pk_fma_f32 v[18:19], v[70:71], v[18:19], v[186:187]
	v_pk_fma_f32 v[16:17], v[68:69], v[16:17], v[188:189]
	v_pk_add_f32 v[10:11], v[10:11], v[18:19]
	v_pk_add_f32 v[8:9], v[8:9], v[16:17]
	v_lshlrev_b64 v[24:25], 1, v[24:25]
	v_cvt_pk_bf16_f32 v16, v12, v13
	v_cvt_pk_bf16_f32 v17, v14, v15
	v_cvt_pk_bf16_f32 v18, v8, v9
	v_cvt_pk_bf16_f32 v19, v10, v11
	v_lshl_add_u64 v[26:27], s[24:25], 0, v[24:25]
	global_store_dwordx4 v[82:83], v[12:15], off
	global_store_dwordx4 v[82:83], v[8:11], off offset:16
	global_store_dwordx4 v[26:27], v[16:19], off
	v_or_b32_e32 v24, 0x100, v24
	s_nop 0
	v_add_f32_e32 v16, v12, v13
	v_add_f32_e32 v17, v14, v15
	v_add_f32_e32 v16, v16, v17
	v_add_f32_e32 v17, v8, v9
	v_mul_f32_e32 v13, v13, v13
	v_mul_f32_e32 v9, v9, v9
	v_fmac_f32_e32 v13, v12, v12
	v_mul_f32_e32 v12, v15, v15
	v_fmac_f32_e32 v9, v8, v8
	v_mul_f32_e32 v8, v11, v11
	v_fmac_f32_e32 v12, v14, v14
	v_fmac_f32_e32 v8, v10, v10
	v_add_f32_e32 v12, v13, v12
	v_add_f32_e32 v8, v9, v8
	v_add_f32_e32 v18, v10, v11
	v_add_f32_e32 v12, v12, v8
	s_waitcnt vmcnt(7)
	v_sub_f32_e32 v9, v37, v20
	v_sub_f32_e32 v8, v36, v20
	v_sub_f32_e32 v11, v39, v20
	v_sub_f32_e32 v10, v38, v20
	v_pk_mul_f32 v[10:11], v[10:11], v[22:23] op_sel_hi:[1,0]
	v_pk_mul_f32 v[8:9], v[8:9], v[22:23] op_sel_hi:[1,0]
	v_pk_fma_f32 v[10:11], v[74:75], v[10:11], v[182:183]
	v_pk_fma_f32 v[8:9], v[72:73], v[8:9], v[184:185]
	v_pk_add_f32 v[6:7], v[6:7], v[10:11]
	v_pk_add_f32 v[4:5], v[4:5], v[8:9]
	v_sub_f32_e32 v9, v33, v20
	v_sub_f32_e32 v8, v32, v20
	v_sub_f32_e32 v11, v35, v20
	v_sub_f32_e32 v10, v34, v20
	v_pk_mul_f32 v[10:11], v[10:11], v[22:23] op_sel_hi:[1,0]
	v_pk_mul_f32 v[8:9], v[8:9], v[22:23] op_sel_hi:[1,0]
	v_pk_fma_f32 v[10:11], v[66:67], v[10:11], v[178:179]
	v_pk_fma_f32 v[8:9], v[64:65], v[8:9], v[180:181]
	v_pk_add_f32 v[10:11], v[2:3], v[10:11]
	v_pk_add_f32 v[8:9], v[0:1], v[8:9]
	v_add_f32_e32 v0, v4, v5
	v_add_f32_e32 v1, v6, v7
	v_add_f32_e32 v0, v0, v1
	v_add_f32_e32 v1, v8, v9
	v_add_f32_e32 v2, v10, v11
	v_add_f32_e32 v1, v1, v2
	v_add_f32_e32 v0, v0, v1
	v_mul_f32_e32 v1, v5, v5
	v_mul_f32_e32 v2, v7, v7
	v_fmac_f32_e32 v1, v4, v4
	v_fmac_f32_e32 v2, v6, v6
	v_add_f32_e32 v1, v1, v2
	v_mul_f32_e32 v2, v9, v9
	v_mul_f32_e32 v3, v11, v11
	v_add_f32_e32 v17, v17, v18
	v_fmac_f32_e32 v2, v8, v8
	v_fmac_f32_e32 v3, v10, v10
	v_add_f32_e32 v16, v16, v17
	v_add_f32_e32 v2, v2, v3
	v_add_f32_e32 v16, 0, v16
	v_add_f32_e32 v1, v1, v2
	v_add_f32_e32 v0, v0, v16
	v_add_f32_e32 v1, v12, v1
	ds_bpermute_b32 v2, v218, v0
	ds_bpermute_b32 v3, v218, v1
	global_store_dwordx4 v[82:83], v[4:7], off offset:512
	global_store_dwordx4 v[82:83], v[8:11], off offset:528
	s_waitcnt lgkmcnt(1)
	v_add_f32_e32 v0, v0, v2
	s_waitcnt lgkmcnt(0)
	v_add_f32_e32 v1, v1, v3
	ds_bpermute_b32 v2, v195, v0
	ds_bpermute_b32 v3, v195, v1
	v_cvt_pk_bf16_f32 v4, v4, v5
	v_cvt_pk_bf16_f32 v5, v6, v7
	v_cvt_pk_bf16_f32 v6, v8, v9
	v_cvt_pk_bf16_f32 v7, v10, v11
	v_lshl_add_u64 v[8:9], s[24:25], 0, v[24:25]
	global_store_dwordx4 v[8:9], v[4:7], off
	s_waitcnt lgkmcnt(1)
	v_add_f32_e32 v0, v0, v2
	s_waitcnt lgkmcnt(0)
	v_add_f32_e32 v1, v1, v3
	s_mov_b32 s90, 0
	s_mov_b32 s91, 0xffff0000
	v_cndmask_b32_e64 v254, v254, v0, s[90:91]
	v_cndmask_b32_e64 v255, v255, v1, s[90:91]
	v_lshrrev_b32_e32 v2, 4, v240
	v_lshlrev_b32_e32 v2, 7, v2
	v_add_co_u32_e32 v250, vcc, v250, v2
	s_nop 1
	v_addc_co_u32_e32 v251, vcc, 0, v251, vcc
	global_atomic_add_f32 v[250:251], v252, off
	global_atomic_add_f32 v[250:251], v253, off offset:4
	global_atomic_add_f32 v[250:251], v254, off offset:1024
	global_atomic_add_f32 v[250:251], v255, off offset:1028
	s_andn2_b64 vcc, exec, s[6:7]
	s_mov_b64 s[6:7], -1
	s_cbranch_vccnz .LBB0_501
	s_andn2_b64 vcc, exec, s[34:35]
	s_cbranch_vccnz .LBB0_500
	s_barrier
	s_branch .LBB0_500

; __global__ void __launch_bounds__(512, 2) fwd_mega(Args a) {
	.amdhsa_kernel _Z8fwd_mega4Args
		.amdhsa_group_segment_fixed_size 0
		.amdhsa_private_segment_fixed_size 0
		.amdhsa_kernarg_size 424
		.amdhsa_user_sgpr_count 2
		.amdhsa_user_sgpr_dispatch_ptr 0
		.amdhsa_user_sgpr_queue_ptr 0
		.amdhsa_user_sgpr_kernarg_segment_ptr 1
		.amdhsa_user_sgpr_dispatch_id 0
		.amdhsa_user_sgpr_kernarg_preload_length 0
		.amdhsa_user_sgpr_kernarg_preload_offset 0
		.amdhsa_user_sgpr_private_segment_size 0
		.amdhsa_uses_dynamic_stack 0
		.amdhsa_enable_private_segment 0
		.amdhsa_system_sgpr_workgroup_id_x 1
		.amdhsa_system_sgpr_workgroup_id_y 0
		.amdhsa_system_sgpr_workgroup_id_z 0
		.amdhsa_system_sgpr_workgroup_info 0
		.amdhsa_system_vgpr_workitem_id 2
		.amdhsa_next_free_vgpr 256
		.amdhsa_next_free_sgpr 96
		.amdhsa_accum_offset 256
		.amdhsa_reserve_vcc 1
		.amdhsa_float_round_mode_32 0
		.amdhsa_float_round_mode_16_64 0
		.amdhsa_float_denorm_mode_32 3
		.amdhsa_float_denorm_mode_16_64 3
		.amdhsa_dx10_clamp 1
		.amdhsa_ieee_mode 1
		.amdhsa_fp16_overflow 0
		.amdhsa_tg_split 0
		.amdhsa_exception_fp_ieee_invalid_op 0
		.amdhsa_exception_fp_denorm_src 0
		.amdhsa_exception_fp_ieee_div_zero 0
		.amdhsa_exception_fp_ieee_overflow 0
		.amdhsa_exception_fp_ieee_underflow 0
		.amdhsa_exception_fp_ieee_inexact 0
		.amdhsa_exception_int_div_zero 0
	.end_amdhsa_kernel

; __global__ void __launch_bounds__(512, 2) fwd_mega(Args a) {
amdhsa.kernels:
  - .agpr_count:     0
    .args:
      - .offset:         0
        .size:           168
        .value_kind:     by_value
      - .offset:         168
        .size:           4
        .value_kind:     hidden_block_count_x
      - .offset:         172
        .size:           4
        .value_kind:     hidden_block_count_y
      - .offset:         176
        .size:           4
        .value_kind:     hidden_block_count_z
      - .offset:         180
        .size:           2
        .value_kind:     hidden_group_size_x
      - .offset:         182
        .size:           2
        .value_kind:     hidden_group_size_y
      - .offset:         184
        .size:           2
        .value_kind:     hidden_group_size_z
      - .offset:         186
        .size:           2
        .value_kind:     hidden_remainder_x
      - .offset:         188
        .size:           2
        .value_kind:     hidden_remainder_y
      - .offset:         190
        .size:           2
        .value_kind:     hidden_remainder_z
      - .offset:         208
        .size:           8
        .value_kind:     hidden_global_offset_x
      - .offset:         216
        .size:           8
        .value_kind:     hidden_global_offset_y
      - .offset:         224
        .size:           8
        .value_kind:     hidden_global_offset_z
      - .offset:         232
        .size:           2
        .value_kind:     hidden_grid_dims
      - .offset:         256
        .size:           8
        .value_kind:     hidden_multigrid_sync_arg
      - .offset:         288
        .size:           4
        .value_kind:     hidden_dynamic_lds_size
    .group_segment_fixed_size: 0
    .kernarg_segment_align: 8
    .kernarg_segment_size: 424
    .language:       OpenCL C
    .language_version:
      - 2
      - 0
    .max_flat_workgroup_size: 512
    .name:           _Z8fwd_mega4Args
    .private_segment_fixed_size: 0
    .sgpr_count:     102
    .sgpr_spill_count: 0
    .symbol:         _Z8fwd_mega4Args.kd
    .uniform_work_group_size: 1
    .uses_dynamic_stack: false
    .vgpr_count:     256
    .vgpr_spill_count: 0
    .wavefront_size: 64
